# QKV epilogue (all six q/k/v variants): each pair of 8-byte bf16 stores merged into one 16-byte store after a v_permlane16_swap exchange between neighbouring lane rows (same bytes, same addresses)
# speedup vs baseline: 1.0170x; 1.0088x over previous
.LBB0_356:
	s_lshl_b64 s[78:79], s[78:79], 9
	s_add_u32 s76, s76, s78
	s_addc_u32 s77, s77, s79
	s_and_b64 s[74:75], s[74:75], exec
	s_cselect_b32 s30, 0x1000000, 0
	s_add_u32 s30, s4, s30
	s_addc_u32 s31, s5, 0
	s_lshl_b32 s4, s70, 1
	s_or_b32 s4, s4, s83
	s_ashr_i32 s5, s4, 31
	s_lshl_b64 s[4:5], s[4:5], 18
	s_add_u32 s4, s30, s4
	s_addc_u32 s5, s31, s5
	v_lshl_add_u64 v[158:159], v[154:155], 2, s[4:5]
	s_mov_b64 s[4:5], 0x4000000
	v_lshl_add_u64 v[156:157], v[154:155], 1, s[76:77]
	v_lshl_add_u64 v[158:159], v[158:159], 0, s[4:5]
	s_andn2_b64 vcc, exec, s[72:73]
	s_mov_b64 s[4:5], -1
	s_cbranch_vccnz .LBB0_362
	s_and_b64 vcc, exec, s[66:67]
	s_cbranch_vccz .LBB0_359
	s_add_i32 s4, 0, 0x20000
	v_lshlrev_b32_e32 v160, 8, v182
	v_lshl_add_u32 v176, v182, 5, s4
	v_ashrrev_i32_e32 v161, 31, v160
	v_lshl_add_u64 v[168:169], v[160:161], 1, v[156:157]
	v_lshl_add_u64 v[170:171], v[160:161], 2, v[158:159]
	ds_read_b128 v[160:163], v176
	s_waitcnt lgkmcnt(0)
	v_mov_b32_e32 v164, v161
	v_mov_b32_e32 v165, v162
	v_mov_b32_e32 v161, v163
	v_pk_add_f32 v[160:161], v[164:165], v[160:161]
	s_nop 0
	v_add_f32_e32 v96, v160, v161
	v_fmamk_f32 v96, v96, 0x3c000000, v251
	v_rsq_f32_e32 v96, v96
	s_nop 0
	v_pk_mul_f32 v[160:161], v[126:127], v[96:97] op_sel_hi:[1,0]
	v_pk_mul_f32 v[162:163], v[128:129], v[96:97] op_sel_hi:[1,0]
	s_waitcnt vmcnt(0)
	v_pk_mul_f32 v[160:161], v[134:135], v[160:161]
	v_pk_mul_f32 v[162:163], v[136:137], v[162:163]
	v_pk_mul_f32 v[164:165], v[122:123], v[96:97] op_sel_hi:[1,0]
	v_pk_mul_f32 v[166:167], v[124:125], v[96:97] op_sel_hi:[1,0]
	v_cvt_pk_bf16_f32 v172, v160, v161
	v_cvt_pk_bf16_f32 v173, v162, v163
	v_pk_mul_f32 v[164:165], v[130:131], v[164:165]
	v_pk_mul_f32 v[166:167], v[132:133], v[166:167]
	v_cvt_pk_bf16_f32 v174, v164, v165
	s_nop 0
	v_cvt_pk_bf16_f32 v175, v166, v167
	v_mbcnt_lo_u32_b32 v196, -1, 0
	v_mbcnt_hi_u32_b32 v196, -1, v196
	v_bfe_u32 v196, v196, 4, 1
	v_mul_u32_u24_e32 v196, 56, v196
	v_mov_b32_e32 v197, 0
	s_nop 1
	v_mov_b32_e32 v192, v172
	v_mov_b32_e32 v193, v173
	v_mov_b32_e32 v194, v174
	v_mov_b32_e32 v195, v175
	v_lshl_add_u64 v[198:199], v[168:169], 0, v[196:197]
	s_nop 0
	v_permlane16_swap_b32_e32 v192, v194
	v_permlane16_swap_b32_e32 v193, v195
	global_store_dwordx4 v[198:199], v[192:195], off
	global_store_dwordx4 v[170:171], v[160:163], off nt
	global_store_dwordx4 v[170:171], v[164:167], off offset:128 nt
	ds_read_b128 v[160:163], v176 offset:16
	s_waitcnt lgkmcnt(0)
	v_mov_b32_e32 v164, v161
	v_mov_b32_e32 v165, v162
	v_mov_b32_e32 v161, v163
	v_pk_add_f32 v[160:161], v[164:165], v[160:161]
	s_nop 0
	v_add_f32_e32 v96, v160, v161
	v_fmamk_f32 v96, v96, 0x3c000000, v251
	v_rsq_f32_e32 v96, v96
	s_nop 0
	v_pk_mul_f32 v[160:161], v[118:119], v[96:97] op_sel_hi:[1,0]
	v_pk_mul_f32 v[162:163], v[120:121], v[96:97] op_sel_hi:[1,0]
	v_pk_mul_f32 v[160:161], v[134:135], v[160:161]
	v_pk_mul_f32 v[162:163], v[136:137], v[162:163]
	v_pk_mul_f32 v[164:165], v[114:115], v[96:97] op_sel_hi:[1,0]
	v_pk_mul_f32 v[166:167], v[116:117], v[96:97] op_sel_hi:[1,0]
	v_cvt_pk_bf16_f32 v172, v160, v161
	v_cvt_pk_bf16_f32 v173, v162, v163
	v_pk_mul_f32 v[164:165], v[130:131], v[164:165]
	v_pk_mul_f32 v[166:167], v[132:133], v[166:167]
	v_cvt_pk_bf16_f32 v174, v164, v165
	s_nop 0
	v_cvt_pk_bf16_f32 v175, v166, v167
	s_nop 1
	v_mov_b32_e32 v200, v172
	v_mov_b32_e32 v201, v173
	v_mov_b32_e32 v202, v174
	v_mov_b32_e32 v203, v175
	v_lshl_add_u64 v[204:205], v[168:169], 0, v[196:197]
	s_nop 0
	v_permlane16_swap_b32_e32 v200, v202
	v_permlane16_swap_b32_e32 v201, v203
	global_store_dwordx4 v[204:205], v[200:203], off offset:256
	global_store_dwordx4 v[170:171], v[160:163], off offset:512 nt
	global_store_dwordx4 v[170:171], v[164:167], off offset:640 nt
	v_add_u32_e32 v96, 16, v182
	v_lshlrev_b32_e32 v160, 8, v96
	v_lshl_add_u32 v176, v96, 5, s4
	v_ashrrev_i32_e32 v161, 31, v160
	v_lshl_add_u64 v[168:169], v[160:161], 1, v[156:157]
	v_lshl_add_u64 v[170:171], v[160:161], 2, v[158:159]
	ds_read_b128 v[160:163], v176
	s_waitcnt lgkmcnt(0)
	v_mov_b32_e32 v164, v161
	v_mov_b32_e32 v165, v162
	v_mov_b32_e32 v161, v163
	v_pk_add_f32 v[160:161], v[164:165], v[160:161]
	s_nop 0
	v_add_f32_e32 v96, v160, v161
	v_fmamk_f32 v96, v96, 0x3c000000, v251
	v_rsq_f32_e32 v96, v96
	s_nop 0
	v_pk_mul_f32 v[160:161], v[110:111], v[96:97] op_sel_hi:[1,0]
	v_pk_mul_f32 v[162:163], v[112:113], v[96:97] op_sel_hi:[1,0]
	v_pk_mul_f32 v[160:161], v[134:135], v[160:161]
	v_pk_mul_f32 v[162:163], v[136:137], v[162:163]
	v_pk_mul_f32 v[164:165], v[106:107], v[96:97] op_sel_hi:[1,0]
	v_pk_mul_f32 v[166:167], v[108:109], v[96:97] op_sel_hi:[1,0]
	v_cvt_pk_bf16_f32 v172, v160, v161
	v_cvt_pk_bf16_f32 v173, v162, v163
	v_pk_mul_f32 v[164:165], v[130:131], v[164:165]
	v_pk_mul_f32 v[166:167], v[132:133], v[166:167]
	v_cvt_pk_bf16_f32 v174, v164, v165
	s_nop 0
	v_cvt_pk_bf16_f32 v175, v166, v167
	s_nop 1
	v_mov_b32_e32 v192, v172
	v_mov_b32_e32 v193, v173
	v_mov_b32_e32 v194, v174
	v_mov_b32_e32 v195, v175
	v_lshl_add_u64 v[198:199], v[168:169], 0, v[196:197]
	s_nop 0
	v_permlane16_swap_b32_e32 v192, v194
	v_permlane16_swap_b32_e32 v193, v195
	global_store_dwordx4 v[198:199], v[192:195], off
	global_store_dwordx4 v[170:171], v[160:163], off nt
	global_store_dwordx4 v[170:171], v[164:167], off offset:128 nt
	ds_read_b128 v[160:163], v176 offset:16
	s_waitcnt lgkmcnt(0)
	v_mov_b32_e32 v164, v161
	v_mov_b32_e32 v165, v162
	v_mov_b32_e32 v161, v163
	v_pk_add_f32 v[160:161], v[164:165], v[160:161]
	s_nop 0
	v_add_f32_e32 v96, v160, v161
	v_fmamk_f32 v96, v96, 0x3c000000, v251
	v_rsq_f32_e32 v96, v96
	s_nop 0
	v_pk_mul_f32 v[160:161], v[102:103], v[96:97] op_sel_hi:[1,0]
	v_pk_mul_f32 v[162:163], v[104:105], v[96:97] op_sel_hi:[1,0]
	v_pk_mul_f32 v[160:161], v[134:135], v[160:161]
	v_pk_mul_f32 v[162:163], v[136:137], v[162:163]
	v_pk_mul_f32 v[164:165], v[98:99], v[96:97] op_sel_hi:[1,0]
	v_pk_mul_f32 v[166:167], v[100:101], v[96:97] op_sel_hi:[1,0]
	v_cvt_pk_bf16_f32 v172, v160, v161
	v_cvt_pk_bf16_f32 v173, v162, v163
	v_pk_mul_f32 v[164:165], v[130:131], v[164:165]
	v_pk_mul_f32 v[166:167], v[132:133], v[166:167]
	v_cvt_pk_bf16_f32 v174, v164, v165
	s_nop 0
	v_cvt_pk_bf16_f32 v175, v166, v167
	s_nop 1
	v_mov_b32_e32 v200, v172
	v_mov_b32_e32 v201, v173
	v_mov_b32_e32 v202, v174
	v_mov_b32_e32 v203, v175
	v_lshl_add_u64 v[204:205], v[168:169], 0, v[196:197]
	s_nop 0
	v_permlane16_swap_b32_e32 v200, v202
	v_permlane16_swap_b32_e32 v201, v203
	global_store_dwordx4 v[204:205], v[200:203], off offset:256
	global_store_dwordx4 v[170:171], v[160:163], off offset:512 nt
	global_store_dwordx4 v[170:171], v[164:167], off offset:640 nt
	v_add_u32_e32 v96, 32, v182
	v_lshlrev_b32_e32 v160, 8, v96
	v_lshl_add_u32 v176, v96, 5, s4
	v_ashrrev_i32_e32 v161, 31, v160
	v_lshl_add_u64 v[168:169], v[160:161], 1, v[156:157]
	v_lshl_add_u64 v[170:171], v[160:161], 2, v[158:159]
	ds_read_b128 v[160:163], v176
	s_waitcnt lgkmcnt(0)
	v_mov_b32_e32 v164, v161
	v_mov_b32_e32 v165, v162
	v_mov_b32_e32 v161, v163
	v_pk_add_f32 v[160:161], v[164:165], v[160:161]
	s_nop 0
	v_add_f32_e32 v96, v160, v161
	v_fmamk_f32 v96, v96, 0x3c000000, v251
	v_rsq_f32_e32 v96, v96
	s_nop 0
	v_pk_mul_f32 v[160:161], v[92:93], v[96:97] op_sel_hi:[1,0]
	v_pk_mul_f32 v[162:163], v[94:95], v[96:97] op_sel_hi:[1,0]
	v_pk_mul_f32 v[160:161], v[134:135], v[160:161]
	v_pk_mul_f32 v[162:163], v[136:137], v[162:163]
	v_pk_mul_f32 v[164:165], v[88:89], v[96:97] op_sel_hi:[1,0]
	v_pk_mul_f32 v[166:167], v[90:91], v[96:97] op_sel_hi:[1,0]
	v_cvt_pk_bf16_f32 v172, v160, v161
	v_cvt_pk_bf16_f32 v173, v162, v163
	v_pk_mul_f32 v[164:165], v[130:131], v[164:165]
	v_pk_mul_f32 v[166:167], v[132:133], v[166:167]
	v_cvt_pk_bf16_f32 v174, v164, v165
	s_nop 0
	v_cvt_pk_bf16_f32 v175, v166, v167
	s_nop 1
	v_mov_b32_e32 v192, v172
	v_mov_b32_e32 v193, v173
	v_mov_b32_e32 v194, v174
	v_mov_b32_e32 v195, v175
	v_lshl_add_u64 v[198:199], v[168:169], 0, v[196:197]
	s_nop 0
	v_permlane16_swap_b32_e32 v192, v194
	v_permlane16_swap_b32_e32 v193, v195
	global_store_dwordx4 v[198:199], v[192:195], off
	global_store_dwordx4 v[170:171], v[160:163], off nt
	global_store_dwordx4 v[170:171], v[164:167], off offset:128 nt
	ds_read_b128 v[160:163], v176 offset:16
	s_waitcnt lgkmcnt(0)
	v_mov_b32_e32 v164, v161
	v_mov_b32_e32 v165, v162
	v_mov_b32_e32 v161, v163
	v_pk_add_f32 v[160:161], v[164:165], v[160:161]
	s_nop 0
	v_add_f32_e32 v96, v160, v161
	v_fmamk_f32 v96, v96, 0x3c000000, v251
	v_rsq_f32_e32 v96, v96
	s_nop 0
	v_pk_mul_f32 v[160:161], v[84:85], v[96:97] op_sel_hi:[1,0]
	v_pk_mul_f32 v[162:163], v[86:87], v[96:97] op_sel_hi:[1,0]
	v_pk_mul_f32 v[160:161], v[134:135], v[160:161]
	v_pk_mul_f32 v[162:163], v[136:137], v[162:163]
	v_pk_mul_f32 v[164:165], v[80:81], v[96:97] op_sel_hi:[1,0]
	v_pk_mul_f32 v[166:167], v[82:83], v[96:97] op_sel_hi:[1,0]
	v_cvt_pk_bf16_f32 v172, v160, v161
	v_cvt_pk_bf16_f32 v173, v162, v163
	v_pk_mul_f32 v[164:165], v[130:131], v[164:165]
	v_pk_mul_f32 v[166:167], v[132:133], v[166:167]
	v_cvt_pk_bf16_f32 v174, v164, v165
	s_nop 0
	v_cvt_pk_bf16_f32 v175, v166, v167
	s_nop 1
	v_mov_b32_e32 v200, v172
	v_mov_b32_e32 v201, v173
	v_mov_b32_e32 v202, v174
	v_mov_b32_e32 v203, v175
	v_lshl_add_u64 v[204:205], v[168:169], 0, v[196:197]
	s_nop 0
	v_permlane16_swap_b32_e32 v200, v202
	v_permlane16_swap_b32_e32 v201, v203
	global_store_dwordx4 v[204:205], v[200:203], off offset:256
	global_store_dwordx4 v[170:171], v[160:163], off offset:512 nt
	global_store_dwordx4 v[170:171], v[164:167], off offset:640 nt
	v_add_u32_e32 v96, 48, v182
	v_lshlrev_b32_e32 v160, 8, v96
	v_lshl_add_u32 v176, v96, 5, s4
	v_ashrrev_i32_e32 v161, 31, v160
	v_lshl_add_u64 v[168:169], v[160:161], 1, v[156:157]
	v_lshl_add_u64 v[170:171], v[160:161], 2, v[158:159]
	ds_read_b128 v[160:163], v176
	s_waitcnt lgkmcnt(0)
	v_mov_b32_e32 v164, v161
	v_mov_b32_e32 v165, v162
	v_mov_b32_e32 v161, v163
	v_pk_add_f32 v[160:161], v[164:165], v[160:161]
	s_nop 0
	v_add_f32_e32 v96, v160, v161
	v_fmamk_f32 v96, v96, 0x3c000000, v251
	v_rsq_f32_e32 v96, v96
	s_nop 0
	v_pk_mul_f32 v[160:161], v[76:77], v[96:97] op_sel_hi:[1,0]
	v_pk_mul_f32 v[162:163], v[78:79], v[96:97] op_sel_hi:[1,0]
	v_pk_mul_f32 v[160:161], v[134:135], v[160:161]
	v_pk_mul_f32 v[162:163], v[136:137], v[162:163]
	v_pk_mul_f32 v[164:165], v[72:73], v[96:97] op_sel_hi:[1,0]
	v_pk_mul_f32 v[166:167], v[74:75], v[96:97] op_sel_hi:[1,0]
	v_cvt_pk_bf16_f32 v172, v160, v161
	v_cvt_pk_bf16_f32 v173, v162, v163
	v_pk_mul_f32 v[164:165], v[130:131], v[164:165]
	v_pk_mul_f32 v[166:167], v[132:133], v[166:167]
	v_cvt_pk_bf16_f32 v174, v164, v165
	s_nop 0
	v_cvt_pk_bf16_f32 v175, v166, v167
	s_nop 1
	v_mov_b32_e32 v192, v172
	v_mov_b32_e32 v193, v173
	v_mov_b32_e32 v194, v174
	v_mov_b32_e32 v195, v175
	v_lshl_add_u64 v[198:199], v[168:169], 0, v[196:197]
	s_nop 0
	v_permlane16_swap_b32_e32 v192, v194
	v_permlane16_swap_b32_e32 v193, v195
	global_store_dwordx4 v[198:199], v[192:195], off
	global_store_dwordx4 v[170:171], v[160:163], off nt
	global_store_dwordx4 v[170:171], v[164:167], off offset:128 nt
	ds_read_b128 v[160:163], v176 offset:16
	s_waitcnt lgkmcnt(0)
	v_mov_b32_e32 v164, v161
	v_mov_b32_e32 v165, v162
	v_mov_b32_e32 v161, v163
	v_pk_add_f32 v[160:161], v[164:165], v[160:161]
	s_nop 0
	v_add_f32_e32 v96, v160, v161
	v_fmamk_f32 v96, v96, 0x3c000000, v251
	v_rsq_f32_e32 v96, v96
	s_nop 0
	v_pk_mul_f32 v[160:161], v[68:69], v[96:97] op_sel_hi:[1,0]
	v_pk_mul_f32 v[162:163], v[70:71], v[96:97] op_sel_hi:[1,0]
	v_pk_mul_f32 v[160:161], v[134:135], v[160:161]
	v_pk_mul_f32 v[162:163], v[136:137], v[162:163]
	v_pk_mul_f32 v[164:165], v[64:65], v[96:97] op_sel_hi:[1,0]
	v_pk_mul_f32 v[166:167], v[66:67], v[96:97] op_sel_hi:[1,0]
	v_cvt_pk_bf16_f32 v172, v160, v161
	v_cvt_pk_bf16_f32 v173, v162, v163
	v_pk_mul_f32 v[164:165], v[130:131], v[164:165]
	v_pk_mul_f32 v[166:167], v[132:133], v[166:167]
	v_cvt_pk_bf16_f32 v174, v164, v165
	s_nop 0
	v_cvt_pk_bf16_f32 v175, v166, v167
	s_nop 1
	v_mov_b32_e32 v200, v172
	v_mov_b32_e32 v201, v173
	v_mov_b32_e32 v202, v174
	v_mov_b32_e32 v203, v175
	v_lshl_add_u64 v[204:205], v[168:169], 0, v[196:197]
	s_nop 0
	v_permlane16_swap_b32_e32 v200, v202
	v_permlane16_swap_b32_e32 v201, v203
	global_store_dwordx4 v[204:205], v[200:203], off offset:256
	global_store_dwordx4 v[170:171], v[160:163], off offset:512 nt
	global_store_dwordx4 v[170:171], v[164:167], off offset:640 nt
	v_add_u32_e32 v96, 0x80, v182
	v_lshlrev_b32_e32 v160, 8, v96
	v_lshl_add_u32 v176, v96, 5, s4
	v_ashrrev_i32_e32 v161, 31, v160
	v_lshl_add_u64 v[168:169], v[160:161], 1, v[156:157]
	v_lshl_add_u64 v[170:171], v[160:161], 2, v[158:159]
	ds_read_b128 v[160:163], v176
	s_waitcnt lgkmcnt(0)
	v_mov_b32_e32 v164, v161
	v_mov_b32_e32 v165, v162
	v_mov_b32_e32 v161, v163
	v_pk_add_f32 v[160:161], v[164:165], v[160:161]
	s_nop 0
	v_add_f32_e32 v96, v160, v161
	v_fmamk_f32 v96, v96, 0x3c000000, v251
	v_rsq_f32_e32 v96, v96
	s_nop 0
	v_pk_mul_f32 v[160:161], v[60:61], v[96:97] op_sel_hi:[1,0]
	v_pk_mul_f32 v[162:163], v[62:63], v[96:97] op_sel_hi:[1,0]
	v_pk_mul_f32 v[160:161], v[134:135], v[160:161]
	v_pk_mul_f32 v[162:163], v[136:137], v[162:163]
	v_pk_mul_f32 v[164:165], v[56:57], v[96:97] op_sel_hi:[1,0]
	v_pk_mul_f32 v[166:167], v[58:59], v[96:97] op_sel_hi:[1,0]
	v_cvt_pk_bf16_f32 v172, v160, v161
	v_cvt_pk_bf16_f32 v173, v162, v163
	v_pk_mul_f32 v[164:165], v[130:131], v[164:165]
	v_pk_mul_f32 v[166:167], v[132:133], v[166:167]
	v_cvt_pk_bf16_f32 v174, v164, v165
	s_nop 0
	v_cvt_pk_bf16_f32 v175, v166, v167
	s_nop 1
	v_mov_b32_e32 v192, v172
	v_mov_b32_e32 v193, v173
	v_mov_b32_e32 v194, v174
	v_mov_b32_e32 v195, v175
	v_lshl_add_u64 v[198:199], v[168:169], 0, v[196:197]
	s_nop 0
	v_permlane16_swap_b32_e32 v192, v194
	v_permlane16_swap_b32_e32 v193, v195
	global_store_dwordx4 v[198:199], v[192:195], off
	global_store_dwordx4 v[170:171], v[160:163], off nt
	global_store_dwordx4 v[170:171], v[164:167], off offset:128 nt
	ds_read_b128 v[160:163], v176 offset:16
	s_waitcnt lgkmcnt(0)
	v_mov_b32_e32 v164, v161
	v_mov_b32_e32 v165, v162
	v_mov_b32_e32 v161, v163
	v_pk_add_f32 v[160:161], v[164:165], v[160:161]
	s_nop 0
	v_add_f32_e32 v96, v160, v161
	v_fmamk_f32 v96, v96, 0x3c000000, v251
	v_rsq_f32_e32 v96, v96
	s_nop 0
	v_pk_mul_f32 v[160:161], v[52:53], v[96:97] op_sel_hi:[1,0]
	v_pk_mul_f32 v[162:163], v[54:55], v[96:97] op_sel_hi:[1,0]
	v_pk_mul_f32 v[160:161], v[134:135], v[160:161]
	v_pk_mul_f32 v[162:163], v[136:137], v[162:163]
	v_pk_mul_f32 v[164:165], v[48:49], v[96:97] op_sel_hi:[1,0]
	v_pk_mul_f32 v[166:167], v[50:51], v[96:97] op_sel_hi:[1,0]
	v_cvt_pk_bf16_f32 v172, v160, v161
	v_cvt_pk_bf16_f32 v173, v162, v163
	v_pk_mul_f32 v[164:165], v[130:131], v[164:165]
	v_pk_mul_f32 v[166:167], v[132:133], v[166:167]
	v_cvt_pk_bf16_f32 v174, v164, v165
	s_nop 0
	v_cvt_pk_bf16_f32 v175, v166, v167
	s_nop 1
	v_mov_b32_e32 v200, v172
	v_mov_b32_e32 v201, v173
	v_mov_b32_e32 v202, v174
	v_mov_b32_e32 v203, v175
	v_lshl_add_u64 v[204:205], v[168:169], 0, v[196:197]
	s_nop 0
	v_permlane16_swap_b32_e32 v200, v202
	v_permlane16_swap_b32_e32 v201, v203
	global_store_dwordx4 v[204:205], v[200:203], off offset:256
	global_store_dwordx4 v[170:171], v[160:163], off offset:512 nt
	global_store_dwordx4 v[170:171], v[164:167], off offset:640 nt
	v_add_u32_e32 v96, 0x90, v182
	v_lshlrev_b32_e32 v160, 8, v96
	v_lshl_add_u32 v176, v96, 5, s4
	v_ashrrev_i32_e32 v161, 31, v160
	v_lshl_add_u64 v[168:169], v[160:161], 1, v[156:157]
	v_lshl_add_u64 v[170:171], v[160:161], 2, v[158:159]
	ds_read_b128 v[160:163], v176
	s_waitcnt lgkmcnt(0)
	v_mov_b32_e32 v164, v161
	v_mov_b32_e32 v165, v162
	v_mov_b32_e32 v161, v163
	v_pk_add_f32 v[160:161], v[164:165], v[160:161]
	s_nop 0
	v_add_f32_e32 v96, v160, v161
	v_fmamk_f32 v96, v96, 0x3c000000, v251
	v_rsq_f32_e32 v96, v96
	s_nop 0
	v_pk_mul_f32 v[160:161], v[44:45], v[96:97] op_sel_hi:[1,0]
	v_pk_mul_f32 v[162:163], v[46:47], v[96:97] op_sel_hi:[1,0]
	v_pk_mul_f32 v[160:161], v[134:135], v[160:161]
	v_pk_mul_f32 v[162:163], v[136:137], v[162:163]
	v_pk_mul_f32 v[164:165], v[40:41], v[96:97] op_sel_hi:[1,0]
	v_pk_mul_f32 v[166:167], v[42:43], v[96:97] op_sel_hi:[1,0]
	v_cvt_pk_bf16_f32 v172, v160, v161
	v_cvt_pk_bf16_f32 v173, v162, v163
	v_pk_mul_f32 v[164:165], v[130:131], v[164:165]
	v_pk_mul_f32 v[166:167], v[132:133], v[166:167]
	v_cvt_pk_bf16_f32 v174, v164, v165
	s_nop 0
	v_cvt_pk_bf16_f32 v175, v166, v167
	s_nop 1
	v_mov_b32_e32 v192, v172
	v_mov_b32_e32 v193, v173
	v_mov_b32_e32 v194, v174
	v_mov_b32_e32 v195, v175
	v_lshl_add_u64 v[198:199], v[168:169], 0, v[196:197]
	s_nop 0
	v_permlane16_swap_b32_e32 v192, v194
	v_permlane16_swap_b32_e32 v193, v195
	global_store_dwordx4 v[198:199], v[192:195], off
	global_store_dwordx4 v[170:171], v[160:163], off nt
	global_store_dwordx4 v[170:171], v[164:167], off offset:128 nt
	ds_read_b128 v[160:163], v176 offset:16
	s_waitcnt lgkmcnt(0)
	v_mov_b32_e32 v164, v161
	v_mov_b32_e32 v165, v162
	v_mov_b32_e32 v161, v163
	v_pk_add_f32 v[160:161], v[164:165], v[160:161]
	s_nop 0
	v_add_f32_e32 v96, v160, v161
	v_fmamk_f32 v96, v96, 0x3c000000, v251
	v_rsq_f32_e32 v96, v96
	s_nop 0
	v_pk_mul_f32 v[160:161], v[36:37], v[96:97] op_sel_hi:[1,0]
	v_pk_mul_f32 v[162:163], v[38:39], v[96:97] op_sel_hi:[1,0]
	v_pk_mul_f32 v[160:161], v[134:135], v[160:161]
	v_pk_mul_f32 v[162:163], v[136:137], v[162:163]
	v_pk_mul_f32 v[164:165], v[32:33], v[96:97] op_sel_hi:[1,0]
	v_pk_mul_f32 v[166:167], v[34:35], v[96:97] op_sel_hi:[1,0]
	v_cvt_pk_bf16_f32 v172, v160, v161
	v_cvt_pk_bf16_f32 v173, v162, v163
	v_pk_mul_f32 v[164:165], v[130:131], v[164:165]
	v_pk_mul_f32 v[166:167], v[132:133], v[166:167]
	v_cvt_pk_bf16_f32 v174, v164, v165
	s_nop 0
	v_cvt_pk_bf16_f32 v175, v166, v167
	s_nop 1
	v_mov_b32_e32 v200, v172
	v_mov_b32_e32 v201, v173
	v_mov_b32_e32 v202, v174
	v_mov_b32_e32 v203, v175
	v_lshl_add_u64 v[204:205], v[168:169], 0, v[196:197]
	s_nop 0
	v_permlane16_swap_b32_e32 v200, v202
	v_permlane16_swap_b32_e32 v201, v203
	global_store_dwordx4 v[204:205], v[200:203], off offset:256
	global_store_dwordx4 v[170:171], v[160:163], off offset:512 nt
	global_store_dwordx4 v[170:171], v[164:167], off offset:640 nt
	v_add_u32_e32 v96, 0xa0, v182
	v_lshlrev_b32_e32 v160, 8, v96
	v_lshl_add_u32 v176, v96, 5, s4
	v_ashrrev_i32_e32 v161, 31, v160
	v_lshl_add_u64 v[168:169], v[160:161], 1, v[156:157]
	v_lshl_add_u64 v[170:171], v[160:161], 2, v[158:159]
	ds_read_b128 v[160:163], v176
	s_waitcnt lgkmcnt(0)
	v_mov_b32_e32 v164, v161
	v_mov_b32_e32 v165, v162
	v_mov_b32_e32 v161, v163
	v_pk_add_f32 v[160:161], v[164:165], v[160:161]
	s_nop 0
	v_add_f32_e32 v96, v160, v161
	v_fmamk_f32 v96, v96, 0x3c000000, v251
	v_rsq_f32_e32 v96, v96
	s_nop 0
	v_pk_mul_f32 v[160:161], v[28:29], v[96:97] op_sel_hi:[1,0]
	v_pk_mul_f32 v[162:163], v[30:31], v[96:97] op_sel_hi:[1,0]
	v_pk_mul_f32 v[160:161], v[134:135], v[160:161]
	v_pk_mul_f32 v[162:163], v[136:137], v[162:163]
	v_pk_mul_f32 v[164:165], v[24:25], v[96:97] op_sel_hi:[1,0]
	v_pk_mul_f32 v[166:167], v[26:27], v[96:97] op_sel_hi:[1,0]
	v_cvt_pk_bf16_f32 v172, v160, v161
	v_cvt_pk_bf16_f32 v173, v162, v163
	v_pk_mul_f32 v[164:165], v[130:131], v[164:165]
	v_pk_mul_f32 v[166:167], v[132:133], v[166:167]
	v_cvt_pk_bf16_f32 v174, v164, v165
	s_nop 0
	v_cvt_pk_bf16_f32 v175, v166, v167
	s_nop 1
	v_mov_b32_e32 v192, v172
	v_mov_b32_e32 v193, v173
	v_mov_b32_e32 v194, v174
	v_mov_b32_e32 v195, v175
	v_lshl_add_u64 v[198:199], v[168:169], 0, v[196:197]
	s_nop 0
	v_permlane16_swap_b32_e32 v192, v194
	v_permlane16_swap_b32_e32 v193, v195
	global_store_dwordx4 v[198:199], v[192:195], off
	global_store_dwordx4 v[170:171], v[160:163], off nt
	global_store_dwordx4 v[170:171], v[164:167], off offset:128 nt
	ds_read_b128 v[160:163], v176 offset:16
	s_waitcnt lgkmcnt(0)
	v_mov_b32_e32 v164, v161
	v_mov_b32_e32 v165, v162
	v_mov_b32_e32 v161, v163
	v_pk_add_f32 v[160:161], v[164:165], v[160:161]
	s_nop 0
	v_add_f32_e32 v96, v160, v161
	v_fmamk_f32 v96, v96, 0x3c000000, v251
	v_rsq_f32_e32 v96, v96
	s_nop 0
	v_pk_mul_f32 v[160:161], v[20:21], v[96:97] op_sel_hi:[1,0]
	v_pk_mul_f32 v[162:163], v[22:23], v[96:97] op_sel_hi:[1,0]
	v_pk_mul_f32 v[160:161], v[134:135], v[160:161]
	v_pk_mul_f32 v[162:163], v[136:137], v[162:163]
	v_pk_mul_f32 v[164:165], v[16:17], v[96:97] op_sel_hi:[1,0]
	v_pk_mul_f32 v[166:167], v[18:19], v[96:97] op_sel_hi:[1,0]
	v_cvt_pk_bf16_f32 v172, v160, v161
	v_cvt_pk_bf16_f32 v173, v162, v163
	v_pk_mul_f32 v[164:165], v[130:131], v[164:165]
	v_pk_mul_f32 v[166:167], v[132:133], v[166:167]
	v_cvt_pk_bf16_f32 v174, v164, v165
	s_nop 0
	v_cvt_pk_bf16_f32 v175, v166, v167
	s_nop 1
	v_mov_b32_e32 v200, v172
	v_mov_b32_e32 v201, v173
	v_mov_b32_e32 v202, v174
	v_mov_b32_e32 v203, v175
	v_lshl_add_u64 v[204:205], v[168:169], 0, v[196:197]
	s_nop 0
	v_permlane16_swap_b32_e32 v200, v202
	v_permlane16_swap_b32_e32 v201, v203
	global_store_dwordx4 v[204:205], v[200:203], off offset:256
	global_store_dwordx4 v[170:171], v[160:163], off offset:512 nt
	global_store_dwordx4 v[170:171], v[164:167], off offset:640 nt
	v_add_u32_e32 v96, 0xb0, v182
	v_lshlrev_b32_e32 v160, 8, v96
	v_lshl_add_u32 v176, v96, 5, s4
	v_ashrrev_i32_e32 v161, 31, v160
	v_lshl_add_u64 v[168:169], v[160:161], 1, v[156:157]
	v_lshl_add_u64 v[170:171], v[160:161], 2, v[158:159]
	ds_read_b128 v[160:163], v176
	s_waitcnt lgkmcnt(0)
	v_mov_b32_e32 v164, v161
	v_mov_b32_e32 v165, v162
	v_mov_b32_e32 v161, v163
	v_pk_add_f32 v[160:161], v[164:165], v[160:161]
	s_nop 0
	v_add_f32_e32 v96, v160, v161
	v_fmamk_f32 v96, v96, 0x3c000000, v251
	v_rsq_f32_e32 v96, v96
	s_nop 0
	v_pk_mul_f32 v[160:161], v[12:13], v[96:97] op_sel_hi:[1,0]
	v_pk_mul_f32 v[162:163], v[14:15], v[96:97] op_sel_hi:[1,0]
	v_pk_mul_f32 v[160:161], v[134:135], v[160:161]
	v_pk_mul_f32 v[162:163], v[136:137], v[162:163]
	v_pk_mul_f32 v[164:165], v[8:9], v[96:97] op_sel_hi:[1,0]
	v_pk_mul_f32 v[166:167], v[10:11], v[96:97] op_sel_hi:[1,0]
	v_cvt_pk_bf16_f32 v172, v160, v161
	v_cvt_pk_bf16_f32 v173, v162, v163
	v_pk_mul_f32 v[164:165], v[130:131], v[164:165]
	v_pk_mul_f32 v[166:167], v[132:133], v[166:167]
	v_cvt_pk_bf16_f32 v174, v164, v165
	s_nop 0
	v_cvt_pk_bf16_f32 v175, v166, v167
	s_nop 1
	v_mov_b32_e32 v192, v172
	v_mov_b32_e32 v193, v173
	v_mov_b32_e32 v194, v174
	v_mov_b32_e32 v195, v175
	v_lshl_add_u64 v[198:199], v[168:169], 0, v[196:197]
	s_nop 0
	v_permlane16_swap_b32_e32 v192, v194
	v_permlane16_swap_b32_e32 v193, v195
	global_store_dwordx4 v[198:199], v[192:195], off
	global_store_dwordx4 v[170:171], v[160:163], off nt
	global_store_dwordx4 v[170:171], v[164:167], off offset:128 nt
	ds_read_b128 v[160:163], v176 offset:16
	s_waitcnt lgkmcnt(0)
	v_mov_b32_e32 v164, v161
	v_mov_b32_e32 v165, v162
	v_mov_b32_e32 v161, v163
	v_pk_add_f32 v[160:161], v[164:165], v[160:161]
	s_nop 0
	v_add_f32_e32 v96, v160, v161
	v_fmamk_f32 v96, v96, 0x3c000000, v251
	v_rsq_f32_e32 v96, v96
	s_nop 0
	v_pk_mul_f32 v[160:161], v[4:5], v[96:97] op_sel_hi:[1,0]
	v_pk_mul_f32 v[162:163], v[6:7], v[96:97] op_sel_hi:[1,0]
	v_pk_mul_f32 v[160:161], v[134:135], v[160:161]
	v_pk_mul_f32 v[162:163], v[136:137], v[162:163]
	v_pk_mul_f32 v[164:165], v[0:1], v[96:97] op_sel_hi:[1,0]
	v_pk_mul_f32 v[166:167], v[2:3], v[96:97] op_sel_hi:[1,0]
	v_cvt_pk_bf16_f32 v172, v160, v161
	v_cvt_pk_bf16_f32 v173, v162, v163
	v_pk_mul_f32 v[164:165], v[130:131], v[164:165]
	v_pk_mul_f32 v[166:167], v[132:133], v[166:167]
	v_cvt_pk_bf16_f32 v174, v164, v165
	s_nop 0
	v_cvt_pk_bf16_f32 v175, v166, v167
	s_nop 1
	v_mov_b32_e32 v200, v172
	v_mov_b32_e32 v201, v173
	v_mov_b32_e32 v202, v174
	v_mov_b32_e32 v203, v175
	v_lshl_add_u64 v[204:205], v[168:169], 0, v[196:197]
	s_nop 0
	v_permlane16_swap_b32_e32 v200, v202
	v_permlane16_swap_b32_e32 v201, v203
	global_store_dwordx4 v[204:205], v[200:203], off offset:256
	global_store_dwordx4 v[170:171], v[160:163], off offset:512 nt
	global_store_dwordx4 v[170:171], v[164:167], off offset:640 nt
	s_mov_b64 s[4:5], 0
.LBB0_359:
	s_andn2_b64 vcc, exec, s[4:5]
	s_cbranch_vccnz .LBB0_361
	s_cmp_lt_u32 s21, 2
	v_add_u32_e32 v96, s19, v182
	v_and_b32_e32 v162, 63, v183
	v_ashrrev_i32_e32 v96, 6, v96
	s_cselect_b64 vcc, -1, 0
	v_cndmask_b32_e32 v96, v162, v96, vcc
	v_cvt_f32_i32_e32 v96, v96
	s_add_i32 s4, 0, 0x20000
	v_lshl_add_u32 v190, v182, 5, s4
	ds_read_b128 v[164:167], v190
	v_mul_f32_e32 v163, v152, v96
	v_fract_f32_e32 v163, v163
	v_sin_f32_e32 v168, v163
	v_cos_f32_e32 v170, v163
	v_mul_f32_e32 v163, v153, v96
	v_fract_f32_e32 v163, v163
	v_sin_f32_e32 v169, v163
	v_cos_f32_e32 v171, v163
	v_mul_f32_e32 v163, v150, v96
	s_waitcnt lgkmcnt(0)
	v_mov_b32_e32 v176, v165
	v_mov_b32_e32 v177, v166
	v_mov_b32_e32 v165, v167
	v_fract_f32_e32 v163, v163
	v_pk_add_f32 v[164:165], v[176:177], v[164:165]
	v_sin_f32_e32 v172, v163
	v_cos_f32_e32 v174, v163
	v_mul_f32_e32 v163, v151, v96
	v_add_f32_e32 v96, v164, v165
	v_fmamk_f32 v96, v96, 0x3c000000, v251
	v_rsq_f32_e32 v96, v96
	v_fract_f32_e32 v163, v163
	v_sin_f32_e32 v173, v163
	v_cos_f32_e32 v175, v163
	v_pk_mul_f32 v[176:177], v[122:123], v[96:97] op_sel_hi:[1,0]
	v_pk_mul_f32 v[184:185], v[124:125], v[96:97] op_sel_hi:[1,0]
	v_pk_mul_f32 v[164:165], v[128:129], v[96:97] op_sel_hi:[1,0]
	v_pk_mul_f32 v[166:167], v[126:127], v[96:97] op_sel_hi:[1,0]
	s_waitcnt vmcnt(0)
	v_pk_mul_f32 v[184:185], v[132:133], v[184:185]
	v_pk_mul_f32 v[176:177], v[130:131], v[176:177]
	v_pk_mul_f32 v[166:167], v[134:135], v[166:167]
	v_pk_mul_f32 v[164:165], v[136:137], v[164:165]
	v_pk_mul_f32 v[186:187], v[168:169], v[176:177]
	v_pk_mul_f32 v[188:189], v[172:173], v[184:185]
	v_pk_fma_f32 v[186:187], v[170:171], v[166:167], v[186:187] neg_lo:[0,0,1] neg_hi:[0,0,1]
	v_pk_fma_f32 v[188:189], v[174:175], v[164:165], v[188:189] neg_lo:[0,0,1] neg_hi:[0,0,1]
	v_pk_mul_f32 v[166:167], v[168:169], v[166:167]
	v_pk_mul_f32 v[164:165], v[172:173], v[164:165]
	v_pk_fma_f32 v[166:167], v[170:171], v[176:177], v[166:167]
	v_pk_fma_f32 v[164:165], v[174:175], v[184:185], v[164:165]
	v_cvt_pk_bf16_f32 v176, v186, v187
	v_cvt_pk_bf16_f32 v177, v188, v189
	v_cvt_pk_bf16_f32 v184, v166, v167
	v_lshlrev_b32_e32 v186, 8, v182
	v_cvt_pk_bf16_f32 v185, v164, v165
	ds_read_b128 v[164:167], v190 offset:16
	v_ashrrev_i32_e32 v187, 31, v186
	v_add_u32_e32 v160, 16, v183
	v_add_u32_e32 v96, 48, v183
	v_and_b32_e32 v161, 63, v160
	s_waitcnt lgkmcnt(0)
	v_mov_b32_e32 v188, v165
	v_mov_b32_e32 v189, v166
	v_mov_b32_e32 v165, v167
	v_pk_add_f32 v[164:165], v[188:189], v[164:165]
	v_lshl_add_u64 v[166:167], v[186:187], 1, v[156:157]
	v_add_f32_e32 v163, v164, v165
	v_fmamk_f32 v163, v163, 0x3c000000, v251
	v_rsq_f32_e32 v164, v163
	v_mbcnt_lo_u32_b32 v196, -1, 0
	v_mbcnt_hi_u32_b32 v196, -1, v196
	v_bfe_u32 v196, v196, 4, 1
	v_mul_u32_u24_e32 v196, 56, v196
	v_mov_b32_e32 v197, 0
	s_nop 1
	v_mov_b32_e32 v192, v176
	v_mov_b32_e32 v193, v177
	v_mov_b32_e32 v194, v184
	v_mov_b32_e32 v195, v185
	v_lshl_add_u64 v[198:199], v[166:167], 0, v[196:197]
	s_nop 0
	v_permlane16_swap_b32_e32 v192, v194
	v_permlane16_swap_b32_e32 v193, v195
	global_store_dwordx4 v[198:199], v[192:195], off
	v_bitop3_b32 v160, v183, 32, 63 bitop3:0x6c
	v_and_b32_e32 v96, 63, v96
	v_pk_mul_f32 v[176:177], v[120:121], v[164:165] op_sel_hi:[1,0]
	v_pk_mul_f32 v[184:185], v[118:119], v[164:165] op_sel_hi:[1,0]
	v_pk_mul_f32 v[186:187], v[114:115], v[164:165] op_sel_hi:[1,0]
	v_pk_mul_f32 v[164:165], v[116:117], v[164:165] op_sel_hi:[1,0]
	v_pk_mul_f32 v[184:185], v[134:135], v[184:185]
	v_pk_mul_f32 v[164:165], v[132:133], v[164:165]
	v_pk_mul_f32 v[186:187], v[130:131], v[186:187]
	v_pk_mul_f32 v[176:177], v[136:137], v[176:177]
	v_pk_mul_f32 v[188:189], v[168:169], v[186:187]
	v_pk_mul_f32 v[190:191], v[172:173], v[164:165]
	v_pk_mul_f32 v[168:169], v[168:169], v[184:185]
	v_pk_fma_f32 v[190:191], v[174:175], v[176:177], v[190:191] neg_lo:[0,0,1] neg_hi:[0,0,1]
	v_pk_fma_f32 v[188:189], v[170:171], v[184:185], v[188:189] neg_lo:[0,0,1] neg_hi:[0,0,1]
	v_pk_mul_f32 v[172:173], v[172:173], v[176:177]
	v_pk_fma_f32 v[168:169], v[170:171], v[186:187], v[168:169]
	v_cvt_pk_bf16_f32 v170, v188, v189
	v_cvt_pk_bf16_f32 v171, v190, v191
	v_pk_fma_f32 v[164:165], v[174:175], v[164:165], v[172:173]
	v_cvt_pk_bf16_f32 v168, v168, v169
	s_nop 0
	v_cvt_pk_bf16_f32 v169, v164, v165
	s_nop 1
	v_mov_b32_e32 v200, v170
	v_mov_b32_e32 v201, v171
	v_mov_b32_e32 v202, v168
	v_mov_b32_e32 v203, v169
	v_lshl_add_u64 v[204:205], v[166:167], 0, v[196:197]
	s_nop 0
	v_permlane16_swap_b32_e32 v200, v202
	v_permlane16_swap_b32_e32 v201, v203
	global_store_dwordx4 v[204:205], v[200:203], off offset:256
	v_add_u32_e32 v163, 16, v182
	v_add_u32_e32 v164, s19, v163
	v_ashrrev_i32_e32 v164, 6, v164
	v_cndmask_b32_e32 v164, v161, v164, vcc
	v_cvt_f32_i32_e32 v173, v164
	v_lshl_add_u32 v190, v163, 5, s4
	v_mul_f32_e32 v164, v152, v173
	v_mul_f32_e32 v165, v153, v173
	v_fract_f32_e32 v164, v164
	v_fract_f32_e32 v165, v165
	v_sin_f32_e32 v168, v164
	v_cos_f32_e32 v170, v164
	v_sin_f32_e32 v169, v165
	v_cos_f32_e32 v171, v165
	ds_read_b128 v[164:167], v190
	v_mul_f32_e32 v172, v150, v173
	v_mul_f32_e32 v173, v151, v173
	v_fract_f32_e32 v174, v172
	v_sin_f32_e32 v172, v174
	s_waitcnt lgkmcnt(0)
	v_mov_b32_e32 v176, v165
	v_mov_b32_e32 v177, v166
	v_mov_b32_e32 v165, v167
	v_pk_add_f32 v[164:165], v[176:177], v[164:165]
	v_cos_f32_e32 v174, v174
	v_add_f32_e32 v164, v164, v165
	v_fmamk_f32 v164, v164, 0x3c000000, v251
	v_rsq_f32_e32 v164, v164
	v_fract_f32_e32 v165, v173
	v_sin_f32_e32 v173, v165
	v_cos_f32_e32 v175, v165
	v_pk_mul_f32 v[166:167], v[112:113], v[164:165] op_sel_hi:[1,0]
	v_pk_mul_f32 v[176:177], v[110:111], v[164:165] op_sel_hi:[1,0]
	v_pk_mul_f32 v[184:185], v[106:107], v[164:165] op_sel_hi:[1,0]
	v_pk_mul_f32 v[164:165], v[108:109], v[164:165] op_sel_hi:[1,0]
	v_pk_mul_f32 v[184:185], v[130:131], v[184:185]
	v_pk_mul_f32 v[164:165], v[132:133], v[164:165]
	v_pk_mul_f32 v[176:177], v[134:135], v[176:177]
	v_pk_mul_f32 v[166:167], v[136:137], v[166:167]
	v_pk_mul_f32 v[186:187], v[168:169], v[184:185]
	v_pk_mul_f32 v[188:189], v[172:173], v[164:165]
	v_pk_fma_f32 v[186:187], v[170:171], v[176:177], v[186:187] neg_lo:[0,0,1] neg_hi:[0,0,1]
	v_pk_fma_f32 v[188:189], v[174:175], v[166:167], v[188:189] neg_lo:[0,0,1] neg_hi:[0,0,1]
	v_pk_mul_f32 v[176:177], v[168:169], v[176:177]
	v_pk_mul_f32 v[166:167], v[172:173], v[166:167]
	s_nop 0
	v_pk_fma_f32 v[164:165], v[174:175], v[164:165], v[166:167]
	v_pk_fma_f32 v[166:167], v[170:171], v[184:185], v[176:177]
	v_cvt_pk_bf16_f32 v176, v186, v187
	v_cvt_pk_bf16_f32 v177, v188, v189
	v_lshlrev_b32_e32 v186, 8, v163
	v_cvt_pk_bf16_f32 v184, v166, v167
	v_cvt_pk_bf16_f32 v185, v164, v165
	ds_read_b128 v[164:167], v190 offset:16
	v_ashrrev_i32_e32 v187, 31, v186
	s_waitcnt lgkmcnt(0)
	v_mov_b32_e32 v188, v165
	v_mov_b32_e32 v189, v166
	v_mov_b32_e32 v165, v167
	v_pk_add_f32 v[164:165], v[188:189], v[164:165]
	v_lshl_add_u64 v[166:167], v[186:187], 1, v[156:157]
	v_add_f32_e32 v163, v164, v165
	v_fmamk_f32 v163, v163, 0x3c000000, v251
	v_rsq_f32_e32 v164, v163
	s_nop 1
	v_mov_b32_e32 v192, v176
	v_mov_b32_e32 v193, v177
	v_mov_b32_e32 v194, v184
	v_mov_b32_e32 v195, v185
	v_lshl_add_u64 v[198:199], v[166:167], 0, v[196:197]
	s_nop 0
	v_permlane16_swap_b32_e32 v192, v194
	v_permlane16_swap_b32_e32 v193, v195
	global_store_dwordx4 v[198:199], v[192:195], off
	v_pk_mul_f32 v[176:177], v[104:105], v[164:165] op_sel_hi:[1,0]
	v_pk_mul_f32 v[184:185], v[102:103], v[164:165] op_sel_hi:[1,0]
	v_pk_mul_f32 v[186:187], v[98:99], v[164:165] op_sel_hi:[1,0]
	v_pk_mul_f32 v[164:165], v[100:101], v[164:165] op_sel_hi:[1,0]
	v_pk_mul_f32 v[184:185], v[134:135], v[184:185]
	v_pk_mul_f32 v[164:165], v[132:133], v[164:165]
	v_pk_mul_f32 v[186:187], v[130:131], v[186:187]
	v_pk_mul_f32 v[176:177], v[136:137], v[176:177]
	v_pk_mul_f32 v[188:189], v[168:169], v[186:187]
	v_pk_mul_f32 v[190:191], v[172:173], v[164:165]
	v_pk_mul_f32 v[168:169], v[168:169], v[184:185]
	v_pk_fma_f32 v[190:191], v[174:175], v[176:177], v[190:191] neg_lo:[0,0,1] neg_hi:[0,0,1]
	v_pk_fma_f32 v[188:189], v[170:171], v[184:185], v[188:189] neg_lo:[0,0,1] neg_hi:[0,0,1]
	v_pk_mul_f32 v[172:173], v[172:173], v[176:177]
	v_pk_fma_f32 v[168:169], v[170:171], v[186:187], v[168:169]
	v_cvt_pk_bf16_f32 v170, v188, v189
	v_cvt_pk_bf16_f32 v171, v190, v191
	v_pk_fma_f32 v[164:165], v[174:175], v[164:165], v[172:173]
	v_cvt_pk_bf16_f32 v168, v168, v169
	s_nop 0
	v_cvt_pk_bf16_f32 v169, v164, v165
	s_nop 1
	v_mov_b32_e32 v200, v170
	v_mov_b32_e32 v201, v171
	v_mov_b32_e32 v202, v168
	v_mov_b32_e32 v203, v169
	v_lshl_add_u64 v[204:205], v[166:167], 0, v[196:197]
	s_nop 0
	v_permlane16_swap_b32_e32 v200, v202
	v_permlane16_swap_b32_e32 v201, v203
	global_store_dwordx4 v[204:205], v[200:203], off offset:256
	v_add_u32_e32 v163, 32, v182
	v_add_u32_e32 v164, s19, v163
	v_ashrrev_i32_e32 v164, 6, v164
	v_cndmask_b32_e32 v164, v160, v164, vcc
	v_cvt_f32_i32_e32 v173, v164
	v_lshl_add_u32 v190, v163, 5, s4
	v_mul_f32_e32 v164, v152, v173
	v_mul_f32_e32 v165, v153, v173
	v_fract_f32_e32 v164, v164
	v_fract_f32_e32 v165, v165
	v_sin_f32_e32 v168, v164
	v_cos_f32_e32 v170, v164
	v_sin_f32_e32 v169, v165
	v_cos_f32_e32 v171, v165
	ds_read_b128 v[164:167], v190
	v_mul_f32_e32 v172, v150, v173
	v_mul_f32_e32 v173, v151, v173
	v_fract_f32_e32 v174, v172
	v_sin_f32_e32 v172, v174
	s_waitcnt lgkmcnt(0)
	v_mov_b32_e32 v176, v165
	v_mov_b32_e32 v177, v166
	v_mov_b32_e32 v165, v167
	v_pk_add_f32 v[164:165], v[176:177], v[164:165]
	v_cos_f32_e32 v174, v174
	v_add_f32_e32 v164, v164, v165
	v_fmamk_f32 v164, v164, 0x3c000000, v251
	v_rsq_f32_e32 v164, v164
	v_fract_f32_e32 v165, v173
	v_sin_f32_e32 v173, v165
	v_cos_f32_e32 v175, v165
	v_pk_mul_f32 v[166:167], v[94:95], v[164:165] op_sel_hi:[1,0]
	v_pk_mul_f32 v[176:177], v[92:93], v[164:165] op_sel_hi:[1,0]
	v_pk_mul_f32 v[184:185], v[88:89], v[164:165] op_sel_hi:[1,0]
	v_pk_mul_f32 v[164:165], v[90:91], v[164:165] op_sel_hi:[1,0]
	v_pk_mul_f32 v[184:185], v[130:131], v[184:185]
	v_pk_mul_f32 v[164:165], v[132:133], v[164:165]
	v_pk_mul_f32 v[176:177], v[134:135], v[176:177]
	v_pk_mul_f32 v[166:167], v[136:137], v[166:167]
	v_pk_mul_f32 v[186:187], v[168:169], v[184:185]
	v_pk_mul_f32 v[188:189], v[172:173], v[164:165]
	v_pk_fma_f32 v[186:187], v[170:171], v[176:177], v[186:187] neg_lo:[0,0,1] neg_hi:[0,0,1]
	v_pk_fma_f32 v[188:189], v[174:175], v[166:167], v[188:189] neg_lo:[0,0,1] neg_hi:[0,0,1]
	v_pk_mul_f32 v[176:177], v[168:169], v[176:177]
	v_pk_mul_f32 v[166:167], v[172:173], v[166:167]
	s_nop 0
	v_pk_fma_f32 v[164:165], v[174:175], v[164:165], v[166:167]
	v_pk_fma_f32 v[166:167], v[170:171], v[184:185], v[176:177]
	v_cvt_pk_bf16_f32 v176, v186, v187
	v_cvt_pk_bf16_f32 v177, v188, v189
	v_lshlrev_b32_e32 v186, 8, v163
	v_cvt_pk_bf16_f32 v184, v166, v167
	v_cvt_pk_bf16_f32 v185, v164, v165
	ds_read_b128 v[164:167], v190 offset:16
	v_ashrrev_i32_e32 v187, 31, v186
	s_waitcnt lgkmcnt(0)
	v_mov_b32_e32 v188, v165
	v_mov_b32_e32 v189, v166
	v_mov_b32_e32 v165, v167
	v_pk_add_f32 v[164:165], v[188:189], v[164:165]
	v_lshl_add_u64 v[166:167], v[186:187], 1, v[156:157]
	v_add_f32_e32 v163, v164, v165
	v_fmamk_f32 v163, v163, 0x3c000000, v251
	v_rsq_f32_e32 v164, v163
	s_nop 1
	v_mov_b32_e32 v192, v176
	v_mov_b32_e32 v193, v177
	v_mov_b32_e32 v194, v184
	v_mov_b32_e32 v195, v185
	v_lshl_add_u64 v[198:199], v[166:167], 0, v[196:197]
	s_nop 0
	v_permlane16_swap_b32_e32 v192, v194
	v_permlane16_swap_b32_e32 v193, v195
	global_store_dwordx4 v[198:199], v[192:195], off
	v_pk_mul_f32 v[176:177], v[86:87], v[164:165] op_sel_hi:[1,0]
	v_pk_mul_f32 v[184:185], v[84:85], v[164:165] op_sel_hi:[1,0]
	v_pk_mul_f32 v[186:187], v[80:81], v[164:165] op_sel_hi:[1,0]
	v_pk_mul_f32 v[164:165], v[82:83], v[164:165] op_sel_hi:[1,0]
	v_pk_mul_f32 v[184:185], v[134:135], v[184:185]
	v_pk_mul_f32 v[164:165], v[132:133], v[164:165]
	v_pk_mul_f32 v[186:187], v[130:131], v[186:187]
	v_pk_mul_f32 v[176:177], v[136:137], v[176:177]
	v_pk_mul_f32 v[188:189], v[168:169], v[186:187]
	v_pk_mul_f32 v[190:191], v[172:173], v[164:165]
	v_pk_mul_f32 v[168:169], v[168:169], v[184:185]
	v_pk_fma_f32 v[190:191], v[174:175], v[176:177], v[190:191] neg_lo:[0,0,1] neg_hi:[0,0,1]
	v_pk_fma_f32 v[188:189], v[170:171], v[184:185], v[188:189] neg_lo:[0,0,1] neg_hi:[0,0,1]
	v_pk_mul_f32 v[172:173], v[172:173], v[176:177]
	v_pk_fma_f32 v[168:169], v[170:171], v[186:187], v[168:169]
	v_cvt_pk_bf16_f32 v170, v188, v189
	v_cvt_pk_bf16_f32 v171, v190, v191
	v_pk_fma_f32 v[164:165], v[174:175], v[164:165], v[172:173]
	v_cvt_pk_bf16_f32 v168, v168, v169
	s_nop 0
	v_cvt_pk_bf16_f32 v169, v164, v165
	s_nop 1
	v_mov_b32_e32 v200, v170
	v_mov_b32_e32 v201, v171
	v_mov_b32_e32 v202, v168
	v_mov_b32_e32 v203, v169
	v_lshl_add_u64 v[204:205], v[166:167], 0, v[196:197]
	s_nop 0
	v_permlane16_swap_b32_e32 v200, v202
	v_permlane16_swap_b32_e32 v201, v203
	global_store_dwordx4 v[204:205], v[200:203], off offset:256
	v_add_u32_e32 v163, 48, v182
	v_add_u32_e32 v164, s19, v163
	v_ashrrev_i32_e32 v164, 6, v164
	v_cndmask_b32_e32 v164, v96, v164, vcc
	v_cvt_f32_i32_e32 v173, v164
	v_lshl_add_u32 v190, v163, 5, s4
	v_mul_f32_e32 v164, v152, v173
	v_mul_f32_e32 v165, v153, v173
	v_fract_f32_e32 v164, v164
	v_fract_f32_e32 v165, v165
	v_sin_f32_e32 v168, v164
	v_cos_f32_e32 v170, v164
	v_sin_f32_e32 v169, v165
	v_cos_f32_e32 v171, v165
	ds_read_b128 v[164:167], v190
	v_mul_f32_e32 v172, v150, v173
	v_mul_f32_e32 v173, v151, v173
	v_fract_f32_e32 v174, v172
	v_sin_f32_e32 v172, v174
	s_waitcnt lgkmcnt(0)
	v_mov_b32_e32 v176, v165
	v_mov_b32_e32 v177, v166
	v_mov_b32_e32 v165, v167
	v_pk_add_f32 v[164:165], v[176:177], v[164:165]
	v_cos_f32_e32 v174, v174
	v_add_f32_e32 v164, v164, v165
	v_fmamk_f32 v164, v164, 0x3c000000, v251
	v_rsq_f32_e32 v164, v164
	v_fract_f32_e32 v165, v173
	v_sin_f32_e32 v173, v165
	v_cos_f32_e32 v175, v165
	v_pk_mul_f32 v[166:167], v[78:79], v[164:165] op_sel_hi:[1,0]
	v_pk_mul_f32 v[176:177], v[76:77], v[164:165] op_sel_hi:[1,0]
	v_pk_mul_f32 v[184:185], v[72:73], v[164:165] op_sel_hi:[1,0]
	v_pk_mul_f32 v[164:165], v[74:75], v[164:165] op_sel_hi:[1,0]
	v_pk_mul_f32 v[184:185], v[130:131], v[184:185]
	v_pk_mul_f32 v[164:165], v[132:133], v[164:165]
	v_pk_mul_f32 v[176:177], v[134:135], v[176:177]
	v_pk_mul_f32 v[166:167], v[136:137], v[166:167]
	v_pk_mul_f32 v[186:187], v[168:169], v[184:185]
	v_pk_mul_f32 v[188:189], v[172:173], v[164:165]
	v_pk_fma_f32 v[186:187], v[170:171], v[176:177], v[186:187] neg_lo:[0,0,1] neg_hi:[0,0,1]
	v_pk_fma_f32 v[188:189], v[174:175], v[166:167], v[188:189] neg_lo:[0,0,1] neg_hi:[0,0,1]
	v_pk_mul_f32 v[176:177], v[168:169], v[176:177]
	v_pk_mul_f32 v[166:167], v[172:173], v[166:167]
	s_nop 0
	v_pk_fma_f32 v[164:165], v[174:175], v[164:165], v[166:167]
	v_pk_fma_f32 v[166:167], v[170:171], v[184:185], v[176:177]
	v_cvt_pk_bf16_f32 v176, v186, v187
	v_cvt_pk_bf16_f32 v177, v188, v189
	v_lshlrev_b32_e32 v186, 8, v163
	v_cvt_pk_bf16_f32 v184, v166, v167
	v_cvt_pk_bf16_f32 v185, v164, v165
	ds_read_b128 v[164:167], v190 offset:16
	v_ashrrev_i32_e32 v187, 31, v186
	s_waitcnt lgkmcnt(0)
	v_mov_b32_e32 v188, v165
	v_mov_b32_e32 v189, v166
	v_mov_b32_e32 v165, v167
	v_pk_add_f32 v[164:165], v[188:189], v[164:165]
	v_lshl_add_u64 v[166:167], v[186:187], 1, v[156:157]
	v_add_f32_e32 v163, v164, v165
	v_fmamk_f32 v163, v163, 0x3c000000, v251
	v_rsq_f32_e32 v164, v163
	s_nop 1
	v_mov_b32_e32 v192, v176
	v_mov_b32_e32 v193, v177
	v_mov_b32_e32 v194, v184
	v_mov_b32_e32 v195, v185
	v_lshl_add_u64 v[198:199], v[166:167], 0, v[196:197]
	s_nop 0
	v_permlane16_swap_b32_e32 v192, v194
	v_permlane16_swap_b32_e32 v193, v195
	global_store_dwordx4 v[198:199], v[192:195], off
	v_pk_mul_f32 v[176:177], v[70:71], v[164:165] op_sel_hi:[1,0]
	v_pk_mul_f32 v[184:185], v[68:69], v[164:165] op_sel_hi:[1,0]
	v_pk_mul_f32 v[186:187], v[64:65], v[164:165] op_sel_hi:[1,0]
	v_pk_mul_f32 v[164:165], v[66:67], v[164:165] op_sel_hi:[1,0]
	v_pk_mul_f32 v[184:185], v[134:135], v[184:185]
	v_pk_mul_f32 v[164:165], v[132:133], v[164:165]
	v_pk_mul_f32 v[186:187], v[130:131], v[186:187]
	v_pk_mul_f32 v[176:177], v[136:137], v[176:177]
	v_pk_mul_f32 v[188:189], v[168:169], v[186:187]
	v_pk_mul_f32 v[190:191], v[172:173], v[164:165]
	v_pk_mul_f32 v[168:169], v[168:169], v[184:185]
	v_pk_fma_f32 v[190:191], v[174:175], v[176:177], v[190:191] neg_lo:[0,0,1] neg_hi:[0,0,1]
	v_pk_fma_f32 v[188:189], v[170:171], v[184:185], v[188:189] neg_lo:[0,0,1] neg_hi:[0,0,1]
	v_pk_mul_f32 v[172:173], v[172:173], v[176:177]
	v_pk_fma_f32 v[168:169], v[170:171], v[186:187], v[168:169]
	v_cvt_pk_bf16_f32 v170, v188, v189
	v_cvt_pk_bf16_f32 v171, v190, v191
	v_pk_fma_f32 v[164:165], v[174:175], v[164:165], v[172:173]
	v_cvt_pk_bf16_f32 v168, v168, v169
	s_nop 0
	v_cvt_pk_bf16_f32 v169, v164, v165
	s_nop 1
	v_mov_b32_e32 v200, v170
	v_mov_b32_e32 v201, v171
	v_mov_b32_e32 v202, v168
	v_mov_b32_e32 v203, v169
	v_lshl_add_u64 v[204:205], v[166:167], 0, v[196:197]
	s_nop 0
	v_permlane16_swap_b32_e32 v200, v202
	v_permlane16_swap_b32_e32 v201, v203
	global_store_dwordx4 v[204:205], v[200:203], off offset:256
	v_add_u32_e32 v188, 0x80, v182
	v_add_u32_e32 v163, s19, v188
	v_ashrrev_i32_e32 v163, 6, v163
	v_cndmask_b32_e32 v162, v162, v163, vcc
	v_cvt_f32_i32_e32 v171, v162
	v_lshl_add_u32 v189, v188, 5, s4
	v_mul_f32_e32 v162, v152, v171
	v_mul_f32_e32 v163, v153, v171
	v_fract_f32_e32 v162, v162
	v_fract_f32_e32 v163, v163
	v_sin_f32_e32 v166, v162
	v_cos_f32_e32 v168, v162
	v_sin_f32_e32 v167, v163
	v_cos_f32_e32 v169, v163
	ds_read_b128 v[162:165], v189
	v_mul_f32_e32 v170, v150, v171
	v_mul_f32_e32 v171, v151, v171
	v_fract_f32_e32 v172, v170
	v_sin_f32_e32 v170, v172
	s_waitcnt lgkmcnt(0)
	v_mov_b32_e32 v174, v163
	v_mov_b32_e32 v175, v164
	v_mov_b32_e32 v163, v165
	v_pk_add_f32 v[162:163], v[174:175], v[162:163]
	v_cos_f32_e32 v172, v172
	v_add_f32_e32 v162, v162, v163
	v_fmamk_f32 v162, v162, 0x3c000000, v251
	v_rsq_f32_e32 v162, v162
	v_fract_f32_e32 v163, v171
	v_sin_f32_e32 v171, v163
	v_cos_f32_e32 v173, v163
	v_pk_mul_f32 v[164:165], v[62:63], v[162:163] op_sel_hi:[1,0]
	v_pk_mul_f32 v[174:175], v[60:61], v[162:163] op_sel_hi:[1,0]
	v_pk_mul_f32 v[176:177], v[56:57], v[162:163] op_sel_hi:[1,0]
	v_pk_mul_f32 v[162:163], v[58:59], v[162:163] op_sel_hi:[1,0]
	v_pk_mul_f32 v[176:177], v[130:131], v[176:177]
	v_pk_mul_f32 v[162:163], v[132:133], v[162:163]
	v_pk_mul_f32 v[174:175], v[134:135], v[174:175]
	v_pk_mul_f32 v[164:165], v[136:137], v[164:165]
	v_pk_mul_f32 v[184:185], v[166:167], v[176:177]
	v_pk_mul_f32 v[186:187], v[170:171], v[162:163]
	v_pk_fma_f32 v[184:185], v[168:169], v[174:175], v[184:185] neg_lo:[0,0,1] neg_hi:[0,0,1]
	v_pk_fma_f32 v[186:187], v[172:173], v[164:165], v[186:187] neg_lo:[0,0,1] neg_hi:[0,0,1]
	v_pk_mul_f32 v[174:175], v[166:167], v[174:175]
	v_pk_mul_f32 v[164:165], v[170:171], v[164:165]
	s_nop 0
	v_pk_fma_f32 v[162:163], v[172:173], v[162:163], v[164:165]
	v_pk_fma_f32 v[164:165], v[168:169], v[176:177], v[174:175]
	v_cvt_pk_bf16_f32 v174, v184, v185
	v_cvt_pk_bf16_f32 v175, v186, v187
	v_lshlrev_b32_e32 v184, 8, v188
	v_cvt_pk_bf16_f32 v176, v164, v165
	v_cvt_pk_bf16_f32 v177, v162, v163
	ds_read_b128 v[162:165], v189 offset:16
	v_ashrrev_i32_e32 v185, 31, v184
	s_waitcnt lgkmcnt(0)
	v_mov_b32_e32 v186, v163
	v_mov_b32_e32 v187, v164
	v_mov_b32_e32 v163, v165
	v_pk_add_f32 v[162:163], v[186:187], v[162:163]
	v_lshl_add_u64 v[164:165], v[184:185], 1, v[156:157]
	v_add_f32_e32 v162, v162, v163
	v_fmamk_f32 v162, v162, 0x3c000000, v251
	v_rsq_f32_e32 v162, v162
	s_nop 1
	v_mov_b32_e32 v192, v174
	v_mov_b32_e32 v193, v175
	v_mov_b32_e32 v194, v176
	v_mov_b32_e32 v195, v177
	v_lshl_add_u64 v[198:199], v[164:165], 0, v[196:197]
	s_nop 0
	v_permlane16_swap_b32_e32 v192, v194
	v_permlane16_swap_b32_e32 v193, v195
	global_store_dwordx4 v[198:199], v[192:195], off
	v_pk_mul_f32 v[174:175], v[54:55], v[162:163] op_sel_hi:[1,0]
	v_pk_mul_f32 v[176:177], v[52:53], v[162:163] op_sel_hi:[1,0]
	v_pk_mul_f32 v[184:185], v[48:49], v[162:163] op_sel_hi:[1,0]
	v_pk_mul_f32 v[162:163], v[50:51], v[162:163] op_sel_hi:[1,0]
	v_pk_mul_f32 v[176:177], v[134:135], v[176:177]
	v_pk_mul_f32 v[162:163], v[132:133], v[162:163]
	v_pk_mul_f32 v[184:185], v[130:131], v[184:185]
	v_pk_mul_f32 v[174:175], v[136:137], v[174:175]
	v_pk_mul_f32 v[186:187], v[166:167], v[184:185]
	v_pk_mul_f32 v[188:189], v[170:171], v[162:163]
	v_pk_mul_f32 v[166:167], v[166:167], v[176:177]
	v_pk_fma_f32 v[188:189], v[172:173], v[174:175], v[188:189] neg_lo:[0,0,1] neg_hi:[0,0,1]
	v_pk_fma_f32 v[186:187], v[168:169], v[176:177], v[186:187] neg_lo:[0,0,1] neg_hi:[0,0,1]
	v_pk_mul_f32 v[170:171], v[170:171], v[174:175]
	v_pk_fma_f32 v[166:167], v[168:169], v[184:185], v[166:167]
	v_cvt_pk_bf16_f32 v168, v186, v187
	v_cvt_pk_bf16_f32 v169, v188, v189
	v_pk_fma_f32 v[162:163], v[172:173], v[162:163], v[170:171]
	v_cvt_pk_bf16_f32 v166, v166, v167
	s_nop 0
	v_cvt_pk_bf16_f32 v167, v162, v163
	s_nop 1
	v_mov_b32_e32 v200, v168
	v_mov_b32_e32 v201, v169
	v_mov_b32_e32 v202, v166
	v_mov_b32_e32 v203, v167
	v_lshl_add_u64 v[204:205], v[164:165], 0, v[196:197]
	s_nop 0
	v_permlane16_swap_b32_e32 v200, v202
	v_permlane16_swap_b32_e32 v201, v203
	global_store_dwordx4 v[204:205], v[200:203], off offset:256
	v_add_u32_e32 v188, 0x90, v182
	v_add_u32_e32 v162, s19, v188
	v_ashrrev_i32_e32 v162, 6, v162
	v_cndmask_b32_e32 v161, v161, v162, vcc
	v_cvt_f32_i32_e32 v161, v161
	v_lshl_add_u32 v189, v188, 5, s4
	v_mul_f32_e32 v162, v152, v161
	v_mul_f32_e32 v163, v153, v161
	v_fract_f32_e32 v162, v162
	v_fract_f32_e32 v163, v163
	v_sin_f32_e32 v166, v162
	v_cos_f32_e32 v168, v162
	v_sin_f32_e32 v167, v163
	v_cos_f32_e32 v169, v163
	ds_read_b128 v[162:165], v189
	v_mul_f32_e32 v170, v150, v161
	v_mul_f32_e32 v161, v151, v161
	v_fract_f32_e32 v171, v170
	v_fract_f32_e32 v161, v161
	s_waitcnt lgkmcnt(0)
	v_mov_b32_e32 v174, v163
	v_mov_b32_e32 v175, v164
	v_mov_b32_e32 v163, v165
	v_pk_add_f32 v[162:163], v[174:175], v[162:163]
	v_sin_f32_e32 v170, v171
	v_add_f32_e32 v162, v162, v163
	v_fmamk_f32 v162, v162, 0x3c000000, v251
	v_rsq_f32_e32 v162, v162
	v_cos_f32_e32 v172, v171
	v_sin_f32_e32 v171, v161
	v_cos_f32_e32 v173, v161
	v_pk_mul_f32 v[164:165], v[46:47], v[162:163] op_sel_hi:[1,0]
	v_pk_mul_f32 v[174:175], v[44:45], v[162:163] op_sel_hi:[1,0]
	v_pk_mul_f32 v[176:177], v[40:41], v[162:163] op_sel_hi:[1,0]
	v_pk_mul_f32 v[162:163], v[42:43], v[162:163] op_sel_hi:[1,0]
	v_pk_mul_f32 v[176:177], v[130:131], v[176:177]
	v_pk_mul_f32 v[162:163], v[132:133], v[162:163]
	v_pk_mul_f32 v[174:175], v[134:135], v[174:175]
	v_pk_mul_f32 v[164:165], v[136:137], v[164:165]
	v_pk_mul_f32 v[184:185], v[166:167], v[176:177]
	v_pk_mul_f32 v[186:187], v[170:171], v[162:163]
	v_pk_fma_f32 v[184:185], v[168:169], v[174:175], v[184:185] neg_lo:[0,0,1] neg_hi:[0,0,1]
	v_pk_fma_f32 v[186:187], v[172:173], v[164:165], v[186:187] neg_lo:[0,0,1] neg_hi:[0,0,1]
	v_pk_mul_f32 v[174:175], v[166:167], v[174:175]
	v_pk_mul_f32 v[164:165], v[170:171], v[164:165]
	s_nop 0
	v_pk_fma_f32 v[162:163], v[172:173], v[162:163], v[164:165]
	v_pk_fma_f32 v[164:165], v[168:169], v[176:177], v[174:175]
	v_cvt_pk_bf16_f32 v174, v184, v185
	v_cvt_pk_bf16_f32 v175, v186, v187
	v_lshlrev_b32_e32 v184, 8, v188
	v_cvt_pk_bf16_f32 v176, v164, v165
	v_cvt_pk_bf16_f32 v177, v162, v163
	ds_read_b128 v[162:165], v189 offset:16
	v_ashrrev_i32_e32 v185, 31, v184
	s_waitcnt lgkmcnt(0)
	v_mov_b32_e32 v186, v163
	v_mov_b32_e32 v187, v164
	v_mov_b32_e32 v163, v165
	v_pk_add_f32 v[162:163], v[186:187], v[162:163]
	v_lshl_add_u64 v[164:165], v[184:185], 1, v[156:157]
	v_add_f32_e32 v161, v162, v163
	v_fmamk_f32 v161, v161, 0x3c000000, v251
	v_rsq_f32_e32 v162, v161
	s_nop 1
	v_mov_b32_e32 v192, v174
	v_mov_b32_e32 v193, v175
	v_mov_b32_e32 v194, v176
	v_mov_b32_e32 v195, v177
	v_lshl_add_u64 v[198:199], v[164:165], 0, v[196:197]
	s_nop 0
	v_permlane16_swap_b32_e32 v192, v194
	v_permlane16_swap_b32_e32 v193, v195
	global_store_dwordx4 v[198:199], v[192:195], off
	v_pk_mul_f32 v[174:175], v[38:39], v[162:163] op_sel_hi:[1,0]
	v_pk_mul_f32 v[176:177], v[36:37], v[162:163] op_sel_hi:[1,0]
	v_pk_mul_f32 v[184:185], v[32:33], v[162:163] op_sel_hi:[1,0]
	v_pk_mul_f32 v[162:163], v[34:35], v[162:163] op_sel_hi:[1,0]
	v_pk_mul_f32 v[176:177], v[134:135], v[176:177]
	v_pk_mul_f32 v[162:163], v[132:133], v[162:163]
	v_pk_mul_f32 v[184:185], v[130:131], v[184:185]
	v_pk_mul_f32 v[174:175], v[136:137], v[174:175]
	v_pk_mul_f32 v[186:187], v[166:167], v[184:185]
	v_pk_mul_f32 v[188:189], v[170:171], v[162:163]
	v_pk_mul_f32 v[166:167], v[166:167], v[176:177]
	v_pk_fma_f32 v[188:189], v[172:173], v[174:175], v[188:189] neg_lo:[0,0,1] neg_hi:[0,0,1]
	v_pk_fma_f32 v[186:187], v[168:169], v[176:177], v[186:187] neg_lo:[0,0,1] neg_hi:[0,0,1]
	v_pk_mul_f32 v[170:171], v[170:171], v[174:175]
	v_pk_fma_f32 v[166:167], v[168:169], v[184:185], v[166:167]
	v_cvt_pk_bf16_f32 v168, v186, v187
	v_cvt_pk_bf16_f32 v169, v188, v189
	v_pk_fma_f32 v[162:163], v[172:173], v[162:163], v[170:171]
	v_cvt_pk_bf16_f32 v166, v166, v167
	s_nop 0
	v_cvt_pk_bf16_f32 v167, v162, v163
	s_nop 1
	v_mov_b32_e32 v200, v168
	v_mov_b32_e32 v201, v169
	v_mov_b32_e32 v202, v166
	v_mov_b32_e32 v203, v167
	v_lshl_add_u64 v[204:205], v[164:165], 0, v[196:197]
	s_nop 0
	v_permlane16_swap_b32_e32 v200, v202
	v_permlane16_swap_b32_e32 v201, v203
	global_store_dwordx4 v[204:205], v[200:203], off offset:256
	v_add_u32_e32 v186, 0xa0, v182
	v_add_u32_e32 v161, s19, v186
	v_ashrrev_i32_e32 v161, 6, v161
	v_cndmask_b32_e32 v160, v160, v161, vcc
	v_cvt_f32_i32_e32 v169, v160
	v_lshl_add_u32 v187, v186, 5, s4
	v_mul_f32_e32 v160, v152, v169
	v_mul_f32_e32 v161, v153, v169
	v_fract_f32_e32 v160, v160
	v_fract_f32_e32 v161, v161
	v_sin_f32_e32 v164, v160
	v_cos_f32_e32 v166, v160
	v_sin_f32_e32 v165, v161
	v_cos_f32_e32 v167, v161
	ds_read_b128 v[160:163], v187
	v_mul_f32_e32 v168, v150, v169
	v_mul_f32_e32 v169, v151, v169
	v_fract_f32_e32 v170, v168
	v_sin_f32_e32 v168, v170
	s_waitcnt lgkmcnt(0)
	v_mov_b32_e32 v172, v161
	v_mov_b32_e32 v173, v162
	v_mov_b32_e32 v161, v163
	v_pk_add_f32 v[160:161], v[172:173], v[160:161]
	v_cos_f32_e32 v170, v170
	v_add_f32_e32 v160, v160, v161
	v_fmamk_f32 v160, v160, 0x3c000000, v251
	v_rsq_f32_e32 v160, v160
	v_fract_f32_e32 v161, v169
	v_sin_f32_e32 v169, v161
	v_cos_f32_e32 v171, v161
	v_pk_mul_f32 v[162:163], v[30:31], v[160:161] op_sel_hi:[1,0]
	v_pk_mul_f32 v[172:173], v[28:29], v[160:161] op_sel_hi:[1,0]
	v_pk_mul_f32 v[174:175], v[24:25], v[160:161] op_sel_hi:[1,0]
	v_pk_mul_f32 v[160:161], v[26:27], v[160:161] op_sel_hi:[1,0]
	v_pk_mul_f32 v[174:175], v[130:131], v[174:175]
	v_pk_mul_f32 v[160:161], v[132:133], v[160:161]
	v_pk_mul_f32 v[172:173], v[134:135], v[172:173]
	v_pk_mul_f32 v[162:163], v[136:137], v[162:163]
	v_pk_mul_f32 v[176:177], v[164:165], v[174:175]
	v_pk_mul_f32 v[184:185], v[168:169], v[160:161]
	v_pk_fma_f32 v[176:177], v[166:167], v[172:173], v[176:177] neg_lo:[0,0,1] neg_hi:[0,0,1]
	v_pk_fma_f32 v[184:185], v[170:171], v[162:163], v[184:185] neg_lo:[0,0,1] neg_hi:[0,0,1]
	v_pk_mul_f32 v[172:173], v[164:165], v[172:173]
	v_pk_mul_f32 v[162:163], v[168:169], v[162:163]
	s_nop 0
	v_pk_fma_f32 v[160:161], v[170:171], v[160:161], v[162:163]
	v_pk_fma_f32 v[162:163], v[166:167], v[174:175], v[172:173]
	v_cvt_pk_bf16_f32 v172, v176, v177
	v_cvt_pk_bf16_f32 v173, v184, v185
	v_lshlrev_b32_e32 v176, 8, v186
	v_cvt_pk_bf16_f32 v174, v162, v163
	v_cvt_pk_bf16_f32 v175, v160, v161
	ds_read_b128 v[160:163], v187 offset:16
	v_ashrrev_i32_e32 v177, 31, v176
	s_waitcnt lgkmcnt(0)
	v_mov_b32_e32 v184, v161
	v_mov_b32_e32 v185, v162
	v_mov_b32_e32 v161, v163
	v_pk_add_f32 v[160:161], v[184:185], v[160:161]
	v_lshl_add_u64 v[162:163], v[176:177], 1, v[156:157]
	v_add_f32_e32 v160, v160, v161
	v_fmamk_f32 v160, v160, 0x3c000000, v251
	v_rsq_f32_e32 v160, v160
	s_nop 1
	v_mov_b32_e32 v192, v172
	v_mov_b32_e32 v193, v173
	v_mov_b32_e32 v194, v174
	v_mov_b32_e32 v195, v175
	v_lshl_add_u64 v[198:199], v[162:163], 0, v[196:197]
	s_nop 0
	v_permlane16_swap_b32_e32 v192, v194
	v_permlane16_swap_b32_e32 v193, v195
	global_store_dwordx4 v[198:199], v[192:195], off
	v_pk_mul_f32 v[172:173], v[22:23], v[160:161] op_sel_hi:[1,0]
	v_pk_mul_f32 v[174:175], v[20:21], v[160:161] op_sel_hi:[1,0]
	v_pk_mul_f32 v[176:177], v[16:17], v[160:161] op_sel_hi:[1,0]
	v_pk_mul_f32 v[160:161], v[18:19], v[160:161] op_sel_hi:[1,0]
	v_pk_mul_f32 v[174:175], v[134:135], v[174:175]
	v_pk_mul_f32 v[160:161], v[132:133], v[160:161]
	v_pk_mul_f32 v[176:177], v[130:131], v[176:177]
	v_pk_mul_f32 v[172:173], v[136:137], v[172:173]
	v_pk_mul_f32 v[184:185], v[164:165], v[176:177]
	v_pk_mul_f32 v[186:187], v[168:169], v[160:161]
	v_pk_mul_f32 v[164:165], v[164:165], v[174:175]
	v_pk_fma_f32 v[186:187], v[170:171], v[172:173], v[186:187] neg_lo:[0,0,1] neg_hi:[0,0,1]
	v_pk_fma_f32 v[184:185], v[166:167], v[174:175], v[184:185] neg_lo:[0,0,1] neg_hi:[0,0,1]
	v_pk_mul_f32 v[168:169], v[168:169], v[172:173]
	v_pk_fma_f32 v[164:165], v[166:167], v[176:177], v[164:165]
	v_cvt_pk_bf16_f32 v166, v184, v185
	v_cvt_pk_bf16_f32 v167, v186, v187
	v_pk_fma_f32 v[160:161], v[170:171], v[160:161], v[168:169]
	v_cvt_pk_bf16_f32 v164, v164, v165
	s_nop 0
	v_cvt_pk_bf16_f32 v165, v160, v161
	s_nop 1
	v_mov_b32_e32 v200, v166
	v_mov_b32_e32 v201, v167
	v_mov_b32_e32 v202, v164
	v_mov_b32_e32 v203, v165
	v_lshl_add_u64 v[204:205], v[162:163], 0, v[196:197]
	s_nop 0
	v_permlane16_swap_b32_e32 v200, v202
	v_permlane16_swap_b32_e32 v201, v203
	global_store_dwordx4 v[204:205], v[200:203], off offset:256
	v_add_u32_e32 v186, 0xb0, v182
	v_add_u32_e32 v160, s19, v186
	v_ashrrev_i32_e32 v160, 6, v160
	v_cndmask_b32_e32 v96, v96, v160, vcc
	v_cvt_f32_i32_e32 v96, v96
	v_lshl_add_u32 v187, v186, 5, s4
	v_mul_f32_e32 v160, v152, v96
	v_mul_f32_e32 v161, v153, v96
	v_fract_f32_e32 v160, v160
	v_fract_f32_e32 v161, v161
	v_sin_f32_e32 v164, v160
	v_cos_f32_e32 v166, v160
	v_sin_f32_e32 v165, v161
	v_cos_f32_e32 v167, v161
	ds_read_b128 v[160:163], v187
	v_mul_f32_e32 v168, v150, v96
	v_fract_f32_e32 v169, v168
	v_sin_f32_e32 v168, v169
	v_cos_f32_e32 v170, v169
	s_waitcnt lgkmcnt(0)
	v_mov_b32_e32 v172, v161
	v_mov_b32_e32 v173, v162
	v_mov_b32_e32 v161, v163
	v_pk_add_f32 v[160:161], v[172:173], v[160:161]
	v_mul_f32_e32 v169, v151, v96
	v_add_f32_e32 v96, v160, v161
	v_fmamk_f32 v96, v96, 0x3c000000, v251
	v_rsq_f32_e32 v96, v96
	v_fract_f32_e32 v160, v169
	v_sin_f32_e32 v169, v160
	v_cos_f32_e32 v171, v160
	v_pk_mul_f32 v[172:173], v[8:9], v[96:97] op_sel_hi:[1,0]
	v_pk_mul_f32 v[174:175], v[10:11], v[96:97] op_sel_hi:[1,0]
	v_pk_mul_f32 v[160:161], v[14:15], v[96:97] op_sel_hi:[1,0]
	v_pk_mul_f32 v[162:163], v[12:13], v[96:97] op_sel_hi:[1,0]
	v_pk_mul_f32 v[174:175], v[132:133], v[174:175]
	v_pk_mul_f32 v[172:173], v[130:131], v[172:173]
	v_pk_mul_f32 v[162:163], v[134:135], v[162:163]
	v_pk_mul_f32 v[160:161], v[136:137], v[160:161]
	v_pk_mul_f32 v[176:177], v[164:165], v[172:173]
	v_pk_mul_f32 v[184:185], v[168:169], v[174:175]
	v_pk_fma_f32 v[176:177], v[166:167], v[162:163], v[176:177] neg_lo:[0,0,1] neg_hi:[0,0,1]
	v_pk_fma_f32 v[184:185], v[170:171], v[160:161], v[184:185] neg_lo:[0,0,1] neg_hi:[0,0,1]
	v_pk_mul_f32 v[162:163], v[164:165], v[162:163]
	v_pk_mul_f32 v[160:161], v[168:169], v[160:161]
	v_pk_fma_f32 v[162:163], v[166:167], v[172:173], v[162:163]
	v_pk_fma_f32 v[160:161], v[170:171], v[174:175], v[160:161]
	v_cvt_pk_bf16_f32 v172, v176, v177
	v_cvt_pk_bf16_f32 v173, v184, v185
	v_cvt_pk_bf16_f32 v174, v162, v163
	v_lshlrev_b32_e32 v176, 8, v186
	v_cvt_pk_bf16_f32 v175, v160, v161
	ds_read_b128 v[160:163], v187 offset:16
	v_ashrrev_i32_e32 v177, 31, v176
	s_waitcnt lgkmcnt(0)
	v_mov_b32_e32 v184, v161
	v_mov_b32_e32 v185, v162
	v_mov_b32_e32 v161, v163
	v_pk_add_f32 v[160:161], v[184:185], v[160:161]
	s_nop 0
	v_add_f32_e32 v96, v160, v161
	v_fmamk_f32 v96, v96, 0x3c000000, v251
	v_rsq_f32_e32 v96, v96
	v_lshl_add_u64 v[160:161], v[176:177], 1, v[156:157]
	s_nop 1
	v_mov_b32_e32 v192, v172
	v_mov_b32_e32 v193, v173
	v_mov_b32_e32 v194, v174
	v_mov_b32_e32 v195, v175
	v_lshl_add_u64 v[198:199], v[160:161], 0, v[196:197]
	s_nop 0
	v_permlane16_swap_b32_e32 v192, v194
	v_permlane16_swap_b32_e32 v193, v195
	global_store_dwordx4 v[198:199], v[192:195], off
	v_pk_mul_f32 v[172:173], v[4:5], v[96:97] op_sel_hi:[1,0]
	v_pk_mul_f32 v[174:175], v[0:1], v[96:97] op_sel_hi:[1,0]
	v_pk_mul_f32 v[176:177], v[2:3], v[96:97] op_sel_hi:[1,0]
	v_pk_mul_f32 v[162:163], v[6:7], v[96:97] op_sel_hi:[1,0]
	v_pk_mul_f32 v[172:173], v[134:135], v[172:173]
	v_pk_mul_f32 v[176:177], v[132:133], v[176:177]
	v_pk_mul_f32 v[174:175], v[130:131], v[174:175]
	v_pk_mul_f32 v[162:163], v[136:137], v[162:163]
	v_pk_mul_f32 v[184:185], v[164:165], v[174:175]
	v_pk_mul_f32 v[186:187], v[168:169], v[176:177]
	v_pk_mul_f32 v[164:165], v[164:165], v[172:173]
	v_pk_fma_f32 v[186:187], v[170:171], v[162:163], v[186:187] neg_lo:[0,0,1] neg_hi:[0,0,1]
	v_pk_fma_f32 v[184:185], v[166:167], v[172:173], v[184:185] neg_lo:[0,0,1] neg_hi:[0,0,1]
	v_pk_mul_f32 v[162:163], v[168:169], v[162:163]
	v_pk_fma_f32 v[164:165], v[166:167], v[174:175], v[164:165]
	v_cvt_pk_bf16_f32 v166, v184, v185
	v_cvt_pk_bf16_f32 v167, v186, v187
	v_pk_fma_f32 v[162:163], v[170:171], v[176:177], v[162:163]
	v_cvt_pk_bf16_f32 v164, v164, v165
	s_nop 0
	v_cvt_pk_bf16_f32 v165, v162, v163
	s_nop 1
	v_mov_b32_e32 v200, v166
	v_mov_b32_e32 v201, v167
	v_mov_b32_e32 v202, v164
	v_mov_b32_e32 v203, v165
	v_lshl_add_u64 v[204:205], v[160:161], 0, v[196:197]
	s_nop 0
	v_permlane16_swap_b32_e32 v200, v202
	v_permlane16_swap_b32_e32 v201, v203
	global_store_dwordx4 v[204:205], v[200:203], off offset:256

.LBB0_362:
	s_andn2_b64 vcc, exec, s[4:5]
	s_cbranch_vccnz .LBB0_367
	v_lshlrev_b32_e32 v176, 8, v182
	v_ashrrev_i32_e32 v177, 31, v176
	v_lshl_add_u64 v[174:175], v[176:177], 1, v[156:157]
	s_mov_b64 s[4:5], -1
	s_and_b64 vcc, exec, s[66:67]
	v_add_u32_e32 v172, 0x1000, v176
	v_add_u32_e32 v170, 0x2000, v176
	v_add_u32_e32 v168, 0x3000, v176
	v_add_u32_e32 v166, 0x8000, v176
	v_add_u32_e32 v164, 0x9000, v176
	v_add_u32_e32 v162, 0xa000, v176
	v_add_u32_e32 v160, 0xb000, v176
	s_cbranch_vccz .LBB0_365
	v_cvt_pk_bf16_f32 v184, v126, v127
	v_cvt_pk_bf16_f32 v185, v128, v129
	v_lshl_add_u64 v[176:177], v[176:177], 2, v[158:159]
	v_cvt_pk_bf16_f32 v186, v122, v123
	v_cvt_pk_bf16_f32 v187, v124, v125
	v_mbcnt_lo_u32_b32 v196, -1, 0
	v_mbcnt_hi_u32_b32 v196, -1, v196
	v_bfe_u32 v196, v196, 4, 1
	v_mul_u32_u24_e32 v196, 56, v196
	v_mov_b32_e32 v197, 0
	s_nop 1
	v_mov_b32_e32 v192, v184
	v_mov_b32_e32 v193, v185
	v_mov_b32_e32 v194, v186
	v_mov_b32_e32 v195, v187
	v_lshl_add_u64 v[198:199], v[174:175], 0, v[196:197]
	s_nop 0
	v_permlane16_swap_b32_e32 v192, v194
	v_permlane16_swap_b32_e32 v193, v195
	global_store_dwordx4 v[198:199], v[192:195], off
	global_store_dwordx4 v[176:177], v[126:129], off nt
	global_store_dwordx4 v[176:177], v[122:125], off offset:128 nt
	v_cvt_pk_bf16_f32 v184, v118, v119
	v_cvt_pk_bf16_f32 v185, v120, v121
	v_cvt_pk_bf16_f32 v186, v114, v115
	v_cvt_pk_bf16_f32 v187, v116, v117
	s_nop 1
	v_mov_b32_e32 v200, v184
	v_mov_b32_e32 v201, v185
	v_mov_b32_e32 v202, v186
	v_mov_b32_e32 v203, v187
	v_lshl_add_u64 v[204:205], v[174:175], 0, v[196:197]
	s_nop 0
	v_permlane16_swap_b32_e32 v200, v202
	v_permlane16_swap_b32_e32 v201, v203
	global_store_dwordx4 v[204:205], v[200:203], off offset:256
	global_store_dwordx4 v[176:177], v[118:121], off offset:512 nt
	global_store_dwordx4 v[176:177], v[114:117], off offset:640 nt
	v_ashrrev_i32_e32 v173, 31, v172
	v_lshl_add_u64 v[176:177], v[172:173], 1, v[156:157]
	v_cvt_pk_bf16_f32 v186, v110, v111
	v_cvt_pk_bf16_f32 v187, v112, v113
	v_lshl_add_u64 v[184:185], v[172:173], 2, v[158:159]
	v_cvt_pk_bf16_f32 v188, v106, v107
	v_cvt_pk_bf16_f32 v189, v108, v109
	s_nop 1
	v_mov_b32_e32 v192, v186
	v_mov_b32_e32 v193, v187
	v_mov_b32_e32 v194, v188
	v_mov_b32_e32 v195, v189
	v_lshl_add_u64 v[198:199], v[176:177], 0, v[196:197]
	s_nop 0
	v_permlane16_swap_b32_e32 v192, v194
	v_permlane16_swap_b32_e32 v193, v195
	global_store_dwordx4 v[198:199], v[192:195], off
	global_store_dwordx4 v[184:185], v[110:113], off nt
	global_store_dwordx4 v[184:185], v[106:109], off offset:128 nt
	v_cvt_pk_bf16_f32 v186, v102, v103
	v_cvt_pk_bf16_f32 v187, v104, v105
	v_cvt_pk_bf16_f32 v188, v98, v99
	v_cvt_pk_bf16_f32 v189, v100, v101
	s_nop 1
	v_mov_b32_e32 v200, v186
	v_mov_b32_e32 v201, v187
	v_mov_b32_e32 v202, v188
	v_mov_b32_e32 v203, v189
	v_lshl_add_u64 v[204:205], v[176:177], 0, v[196:197]
	s_nop 0
	v_permlane16_swap_b32_e32 v200, v202
	v_permlane16_swap_b32_e32 v201, v203
	global_store_dwordx4 v[204:205], v[200:203], off offset:256
	global_store_dwordx4 v[184:185], v[102:105], off offset:512 nt
	global_store_dwordx4 v[184:185], v[98:101], off offset:640 nt
	v_ashrrev_i32_e32 v171, 31, v170
	v_lshl_add_u64 v[176:177], v[170:171], 1, v[156:157]
	v_cvt_pk_bf16_f32 v186, v92, v93
	v_cvt_pk_bf16_f32 v187, v94, v95
	v_lshl_add_u64 v[184:185], v[170:171], 2, v[158:159]
	v_cvt_pk_bf16_f32 v188, v88, v89
	v_cvt_pk_bf16_f32 v189, v90, v91
	s_nop 1
	v_mov_b32_e32 v192, v186
	v_mov_b32_e32 v193, v187
	v_mov_b32_e32 v194, v188
	v_mov_b32_e32 v195, v189
	v_lshl_add_u64 v[198:199], v[176:177], 0, v[196:197]
	s_nop 0
	v_permlane16_swap_b32_e32 v192, v194
	v_permlane16_swap_b32_e32 v193, v195
	global_store_dwordx4 v[198:199], v[192:195], off
	global_store_dwordx4 v[184:185], v[92:95], off nt
	global_store_dwordx4 v[184:185], v[88:91], off offset:128 nt
	v_cvt_pk_bf16_f32 v186, v84, v85
	v_cvt_pk_bf16_f32 v187, v86, v87
	v_cvt_pk_bf16_f32 v188, v80, v81
	v_cvt_pk_bf16_f32 v189, v82, v83
	s_nop 1
	v_mov_b32_e32 v200, v186
	v_mov_b32_e32 v201, v187
	v_mov_b32_e32 v202, v188
	v_mov_b32_e32 v203, v189
	v_lshl_add_u64 v[204:205], v[176:177], 0, v[196:197]
	s_nop 0
	v_permlane16_swap_b32_e32 v200, v202
	v_permlane16_swap_b32_e32 v201, v203
	global_store_dwordx4 v[204:205], v[200:203], off offset:256
	global_store_dwordx4 v[184:185], v[84:87], off offset:512 nt
	global_store_dwordx4 v[184:185], v[80:83], off offset:640 nt
	v_ashrrev_i32_e32 v169, 31, v168
	v_lshl_add_u64 v[176:177], v[168:169], 1, v[156:157]
	v_cvt_pk_bf16_f32 v186, v76, v77
	v_cvt_pk_bf16_f32 v187, v78, v79
	v_lshl_add_u64 v[184:185], v[168:169], 2, v[158:159]
	v_cvt_pk_bf16_f32 v188, v72, v73
	v_cvt_pk_bf16_f32 v189, v74, v75
	s_nop 1
	v_mov_b32_e32 v192, v186
	v_mov_b32_e32 v193, v187
	v_mov_b32_e32 v194, v188
	v_mov_b32_e32 v195, v189
	v_lshl_add_u64 v[198:199], v[176:177], 0, v[196:197]
	s_nop 0
	v_permlane16_swap_b32_e32 v192, v194
	v_permlane16_swap_b32_e32 v193, v195
	global_store_dwordx4 v[198:199], v[192:195], off
	global_store_dwordx4 v[184:185], v[76:79], off nt
	global_store_dwordx4 v[184:185], v[72:75], off offset:128 nt
	v_cvt_pk_bf16_f32 v186, v68, v69
	v_cvt_pk_bf16_f32 v187, v70, v71
	v_cvt_pk_bf16_f32 v188, v64, v65
	v_cvt_pk_bf16_f32 v189, v66, v67
	s_nop 1
	v_mov_b32_e32 v200, v186
	v_mov_b32_e32 v201, v187
	v_mov_b32_e32 v202, v188
	v_mov_b32_e32 v203, v189
	v_lshl_add_u64 v[204:205], v[176:177], 0, v[196:197]
	s_nop 0
	v_permlane16_swap_b32_e32 v200, v202
	v_permlane16_swap_b32_e32 v201, v203
	global_store_dwordx4 v[204:205], v[200:203], off offset:256
	global_store_dwordx4 v[184:185], v[68:71], off offset:512 nt
	global_store_dwordx4 v[184:185], v[64:67], off offset:640 nt
	v_ashrrev_i32_e32 v167, 31, v166
	v_lshl_add_u64 v[176:177], v[166:167], 1, v[156:157]
	v_cvt_pk_bf16_f32 v186, v60, v61
	v_cvt_pk_bf16_f32 v187, v62, v63
	v_lshl_add_u64 v[184:185], v[166:167], 2, v[158:159]
	v_cvt_pk_bf16_f32 v188, v56, v57
	v_cvt_pk_bf16_f32 v189, v58, v59
	s_nop 1
	v_mov_b32_e32 v192, v186
	v_mov_b32_e32 v193, v187
	v_mov_b32_e32 v194, v188
	v_mov_b32_e32 v195, v189
	v_lshl_add_u64 v[198:199], v[176:177], 0, v[196:197]
	s_nop 0
	v_permlane16_swap_b32_e32 v192, v194
	v_permlane16_swap_b32_e32 v193, v195
	global_store_dwordx4 v[198:199], v[192:195], off
	global_store_dwordx4 v[184:185], v[60:63], off nt
	global_store_dwordx4 v[184:185], v[56:59], off offset:128 nt
	v_cvt_pk_bf16_f32 v186, v52, v53
	v_cvt_pk_bf16_f32 v187, v54, v55
	v_cvt_pk_bf16_f32 v188, v48, v49
	v_cvt_pk_bf16_f32 v189, v50, v51
	s_nop 1
	v_mov_b32_e32 v200, v186
	v_mov_b32_e32 v201, v187
	v_mov_b32_e32 v202, v188
	v_mov_b32_e32 v203, v189
	v_lshl_add_u64 v[204:205], v[176:177], 0, v[196:197]
	s_nop 0
	v_permlane16_swap_b32_e32 v200, v202
	v_permlane16_swap_b32_e32 v201, v203
	global_store_dwordx4 v[204:205], v[200:203], off offset:256
	global_store_dwordx4 v[184:185], v[52:55], off offset:512 nt
	global_store_dwordx4 v[184:185], v[48:51], off offset:640 nt
	v_ashrrev_i32_e32 v165, 31, v164
	v_lshl_add_u64 v[176:177], v[164:165], 1, v[156:157]
	v_cvt_pk_bf16_f32 v186, v44, v45
	v_cvt_pk_bf16_f32 v187, v46, v47
	v_lshl_add_u64 v[184:185], v[164:165], 2, v[158:159]
	v_cvt_pk_bf16_f32 v188, v40, v41
	v_cvt_pk_bf16_f32 v189, v42, v43
	s_nop 1
	v_mov_b32_e32 v192, v186
	v_mov_b32_e32 v193, v187
	v_mov_b32_e32 v194, v188
	v_mov_b32_e32 v195, v189
	v_lshl_add_u64 v[198:199], v[176:177], 0, v[196:197]
	s_nop 0
	v_permlane16_swap_b32_e32 v192, v194
	v_permlane16_swap_b32_e32 v193, v195
	global_store_dwordx4 v[198:199], v[192:195], off
	global_store_dwordx4 v[184:185], v[44:47], off nt
	global_store_dwordx4 v[184:185], v[40:43], off offset:128 nt
	v_cvt_pk_bf16_f32 v186, v36, v37
	v_cvt_pk_bf16_f32 v187, v38, v39
	v_cvt_pk_bf16_f32 v188, v32, v33
	v_cvt_pk_bf16_f32 v189, v34, v35
	s_nop 1
	v_mov_b32_e32 v200, v186
	v_mov_b32_e32 v201, v187
	v_mov_b32_e32 v202, v188
	v_mov_b32_e32 v203, v189
	v_lshl_add_u64 v[204:205], v[176:177], 0, v[196:197]
	s_nop 0
	v_permlane16_swap_b32_e32 v200, v202
	v_permlane16_swap_b32_e32 v201, v203
	global_store_dwordx4 v[204:205], v[200:203], off offset:256
	global_store_dwordx4 v[184:185], v[36:39], off offset:512 nt
	global_store_dwordx4 v[184:185], v[32:35], off offset:640 nt
	v_ashrrev_i32_e32 v163, 31, v162
	v_lshl_add_u64 v[176:177], v[162:163], 1, v[156:157]
	v_cvt_pk_bf16_f32 v186, v28, v29
	v_cvt_pk_bf16_f32 v187, v30, v31
	v_lshl_add_u64 v[184:185], v[162:163], 2, v[158:159]
	v_cvt_pk_bf16_f32 v188, v24, v25
	v_cvt_pk_bf16_f32 v189, v26, v27
	s_nop 1
	v_mov_b32_e32 v192, v186
	v_mov_b32_e32 v193, v187
	v_mov_b32_e32 v194, v188
	v_mov_b32_e32 v195, v189
	v_lshl_add_u64 v[198:199], v[176:177], 0, v[196:197]
	s_nop 0
	v_permlane16_swap_b32_e32 v192, v194
	v_permlane16_swap_b32_e32 v193, v195
	global_store_dwordx4 v[198:199], v[192:195], off
	global_store_dwordx4 v[184:185], v[28:31], off nt
	global_store_dwordx4 v[184:185], v[24:27], off offset:128 nt
	v_cvt_pk_bf16_f32 v186, v20, v21
	v_cvt_pk_bf16_f32 v187, v22, v23
	v_cvt_pk_bf16_f32 v188, v16, v17
	v_cvt_pk_bf16_f32 v189, v18, v19
	s_nop 1
	v_mov_b32_e32 v200, v186
	v_mov_b32_e32 v201, v187
	v_mov_b32_e32 v202, v188
	v_mov_b32_e32 v203, v189
	v_lshl_add_u64 v[204:205], v[176:177], 0, v[196:197]
	s_nop 0
	v_permlane16_swap_b32_e32 v200, v202
	v_permlane16_swap_b32_e32 v201, v203
	global_store_dwordx4 v[204:205], v[200:203], off offset:256
	global_store_dwordx4 v[184:185], v[20:23], off offset:512 nt
	global_store_dwordx4 v[184:185], v[16:19], off offset:640 nt
	v_ashrrev_i32_e32 v161, 31, v160
	v_lshl_add_u64 v[176:177], v[160:161], 1, v[156:157]
	v_cvt_pk_bf16_f32 v184, v12, v13
	v_cvt_pk_bf16_f32 v185, v14, v15
	v_lshl_add_u64 v[158:159], v[160:161], 2, v[158:159]
	v_cvt_pk_bf16_f32 v186, v8, v9
	v_cvt_pk_bf16_f32 v187, v10, v11
	s_nop 1
	v_mov_b32_e32 v192, v184
	v_mov_b32_e32 v193, v185
	v_mov_b32_e32 v194, v186
	v_mov_b32_e32 v195, v187
	v_lshl_add_u64 v[198:199], v[176:177], 0, v[196:197]
	s_nop 0
	v_permlane16_swap_b32_e32 v192, v194
	v_permlane16_swap_b32_e32 v193, v195
	global_store_dwordx4 v[198:199], v[192:195], off
	global_store_dwordx4 v[158:159], v[12:15], off nt
	global_store_dwordx4 v[158:159], v[8:11], off offset:128 nt
	v_cvt_pk_bf16_f32 v184, v4, v5
	v_cvt_pk_bf16_f32 v185, v6, v7
	v_cvt_pk_bf16_f32 v186, v0, v1
	v_cvt_pk_bf16_f32 v187, v2, v3
	s_nop 1
	v_mov_b32_e32 v200, v184
	v_mov_b32_e32 v201, v185
	v_mov_b32_e32 v202, v186
	v_mov_b32_e32 v203, v187
	v_lshl_add_u64 v[204:205], v[176:177], 0, v[196:197]
	s_nop 0
	v_permlane16_swap_b32_e32 v200, v202
	v_permlane16_swap_b32_e32 v201, v203
	global_store_dwordx4 v[204:205], v[200:203], off offset:256
	global_store_dwordx4 v[158:159], v[4:7], off offset:512 nt
	global_store_dwordx4 v[158:159], v[0:3], off offset:640 nt
	s_mov_b64 s[4:5], 0
.LBB0_365:
	s_andn2_b64 vcc, exec, s[4:5]
	s_cbranch_vccnz .LBB0_367
	v_cvt_pk_bf16_f32 v158, v126, v127
	v_cvt_pk_bf16_f32 v159, v128, v129
	v_cvt_pk_bf16_f32 v176, v122, v123
	v_cvt_pk_bf16_f32 v177, v124, v125
	v_mbcnt_lo_u32_b32 v196, -1, 0
	v_mbcnt_hi_u32_b32 v196, -1, v196
	v_bfe_u32 v196, v196, 4, 1
	v_mul_u32_u24_e32 v196, 56, v196
	v_mov_b32_e32 v197, 0
	s_nop 1
	v_mov_b32_e32 v192, v158
	v_mov_b32_e32 v193, v159
	v_mov_b32_e32 v194, v176
	v_mov_b32_e32 v195, v177
	v_lshl_add_u64 v[198:199], v[174:175], 0, v[196:197]
	s_nop 0
	v_permlane16_swap_b32_e32 v192, v194
	v_permlane16_swap_b32_e32 v193, v195
	global_store_dwordx4 v[198:199], v[192:195], off
	v_cvt_pk_bf16_f32 v158, v118, v119
	v_cvt_pk_bf16_f32 v159, v120, v121
	v_cvt_pk_bf16_f32 v176, v114, v115
	v_cvt_pk_bf16_f32 v177, v116, v117
	s_nop 1
	v_mov_b32_e32 v200, v158
	v_mov_b32_e32 v201, v159
	v_mov_b32_e32 v202, v176
	v_mov_b32_e32 v203, v177
	v_lshl_add_u64 v[204:205], v[174:175], 0, v[196:197]
	s_nop 0
	v_permlane16_swap_b32_e32 v200, v202
	v_permlane16_swap_b32_e32 v201, v203
	global_store_dwordx4 v[204:205], v[200:203], off offset:256
	v_ashrrev_i32_e32 v173, 31, v172
	v_lshl_add_u64 v[158:159], v[172:173], 1, v[156:157]
	v_cvt_pk_bf16_f32 v172, v110, v111
	v_cvt_pk_bf16_f32 v173, v112, v113
	v_cvt_pk_bf16_f32 v174, v106, v107
	v_cvt_pk_bf16_f32 v175, v108, v109
	s_nop 1
	v_mov_b32_e32 v192, v172
	v_mov_b32_e32 v193, v173
	v_mov_b32_e32 v194, v174
	v_mov_b32_e32 v195, v175
	v_lshl_add_u64 v[198:199], v[158:159], 0, v[196:197]
	s_nop 0
	v_permlane16_swap_b32_e32 v192, v194
	v_permlane16_swap_b32_e32 v193, v195
	global_store_dwordx4 v[198:199], v[192:195], off
	v_cvt_pk_bf16_f32 v172, v102, v103
	v_cvt_pk_bf16_f32 v173, v104, v105
	v_cvt_pk_bf16_f32 v174, v98, v99
	v_cvt_pk_bf16_f32 v175, v100, v101
	s_nop 1
	v_mov_b32_e32 v200, v172
	v_mov_b32_e32 v201, v173
	v_mov_b32_e32 v202, v174
	v_mov_b32_e32 v203, v175
	v_lshl_add_u64 v[204:205], v[158:159], 0, v[196:197]
	s_nop 0
	v_permlane16_swap_b32_e32 v200, v202
	v_permlane16_swap_b32_e32 v201, v203
	global_store_dwordx4 v[204:205], v[200:203], off offset:256
	v_ashrrev_i32_e32 v171, 31, v170
	v_lshl_add_u64 v[158:159], v[170:171], 1, v[156:157]
	v_cvt_pk_bf16_f32 v170, v92, v93
	v_cvt_pk_bf16_f32 v171, v94, v95
	v_cvt_pk_bf16_f32 v172, v88, v89
	v_cvt_pk_bf16_f32 v173, v90, v91
	s_nop 1
	v_mov_b32_e32 v192, v170
	v_mov_b32_e32 v193, v171
	v_mov_b32_e32 v194, v172
	v_mov_b32_e32 v195, v173
	v_lshl_add_u64 v[198:199], v[158:159], 0, v[196:197]
	s_nop 0
	v_permlane16_swap_b32_e32 v192, v194
	v_permlane16_swap_b32_e32 v193, v195
	global_store_dwordx4 v[198:199], v[192:195], off
	v_cvt_pk_bf16_f32 v170, v84, v85
	v_cvt_pk_bf16_f32 v171, v86, v87
	v_cvt_pk_bf16_f32 v172, v80, v81
	v_cvt_pk_bf16_f32 v173, v82, v83
	s_nop 1
	v_mov_b32_e32 v200, v170
	v_mov_b32_e32 v201, v171
	v_mov_b32_e32 v202, v172
	v_mov_b32_e32 v203, v173
	v_lshl_add_u64 v[204:205], v[158:159], 0, v[196:197]
	s_nop 0
	v_permlane16_swap_b32_e32 v200, v202
	v_permlane16_swap_b32_e32 v201, v203
	global_store_dwordx4 v[204:205], v[200:203], off offset:256
	v_ashrrev_i32_e32 v169, 31, v168
	v_lshl_add_u64 v[158:159], v[168:169], 1, v[156:157]
	v_cvt_pk_bf16_f32 v168, v76, v77
	v_cvt_pk_bf16_f32 v169, v78, v79
	v_cvt_pk_bf16_f32 v170, v72, v73
	v_cvt_pk_bf16_f32 v171, v74, v75
	s_nop 1
	v_mov_b32_e32 v192, v168
	v_mov_b32_e32 v193, v169
	v_mov_b32_e32 v194, v170
	v_mov_b32_e32 v195, v171
	v_lshl_add_u64 v[198:199], v[158:159], 0, v[196:197]
	s_nop 0
	v_permlane16_swap_b32_e32 v192, v194
	v_permlane16_swap_b32_e32 v193, v195
	global_store_dwordx4 v[198:199], v[192:195], off
	v_cvt_pk_bf16_f32 v168, v68, v69
	v_cvt_pk_bf16_f32 v169, v70, v71
	v_cvt_pk_bf16_f32 v170, v64, v65
	v_cvt_pk_bf16_f32 v171, v66, v67
	s_nop 1
	v_mov_b32_e32 v200, v168
	v_mov_b32_e32 v201, v169
	v_mov_b32_e32 v202, v170
	v_mov_b32_e32 v203, v171
	v_lshl_add_u64 v[204:205], v[158:159], 0, v[196:197]
	s_nop 0
	v_permlane16_swap_b32_e32 v200, v202
	v_permlane16_swap_b32_e32 v201, v203
	global_store_dwordx4 v[204:205], v[200:203], off offset:256
	v_ashrrev_i32_e32 v167, 31, v166
	v_lshl_add_u64 v[158:159], v[166:167], 1, v[156:157]
	v_cvt_pk_bf16_f32 v166, v60, v61
	v_cvt_pk_bf16_f32 v167, v62, v63
	v_cvt_pk_bf16_f32 v168, v56, v57
	v_cvt_pk_bf16_f32 v169, v58, v59
	s_nop 1
	v_mov_b32_e32 v192, v166
	v_mov_b32_e32 v193, v167
	v_mov_b32_e32 v194, v168
	v_mov_b32_e32 v195, v169
	v_lshl_add_u64 v[198:199], v[158:159], 0, v[196:197]
	s_nop 0
	v_permlane16_swap_b32_e32 v192, v194
	v_permlane16_swap_b32_e32 v193, v195
	global_store_dwordx4 v[198:199], v[192:195], off
	v_cvt_pk_bf16_f32 v166, v52, v53
	v_cvt_pk_bf16_f32 v167, v54, v55
	v_cvt_pk_bf16_f32 v168, v48, v49
	v_cvt_pk_bf16_f32 v169, v50, v51
	s_nop 1
	v_mov_b32_e32 v200, v166
	v_mov_b32_e32 v201, v167
	v_mov_b32_e32 v202, v168
	v_mov_b32_e32 v203, v169
	v_lshl_add_u64 v[204:205], v[158:159], 0, v[196:197]
	s_nop 0
	v_permlane16_swap_b32_e32 v200, v202
	v_permlane16_swap_b32_e32 v201, v203
	global_store_dwordx4 v[204:205], v[200:203], off offset:256
	v_ashrrev_i32_e32 v165, 31, v164
	v_lshl_add_u64 v[158:159], v[164:165], 1, v[156:157]
	v_cvt_pk_bf16_f32 v164, v44, v45
	v_cvt_pk_bf16_f32 v165, v46, v47
	v_cvt_pk_bf16_f32 v166, v40, v41
	v_cvt_pk_bf16_f32 v167, v42, v43
	s_nop 1
	v_mov_b32_e32 v192, v164
	v_mov_b32_e32 v193, v165
	v_mov_b32_e32 v194, v166
	v_mov_b32_e32 v195, v167
	v_lshl_add_u64 v[198:199], v[158:159], 0, v[196:197]
	s_nop 0
	v_permlane16_swap_b32_e32 v192, v194
	v_permlane16_swap_b32_e32 v193, v195
	global_store_dwordx4 v[198:199], v[192:195], off
	v_cvt_pk_bf16_f32 v164, v36, v37
	v_cvt_pk_bf16_f32 v165, v38, v39
	v_cvt_pk_bf16_f32 v166, v32, v33
	v_cvt_pk_bf16_f32 v167, v34, v35
	s_nop 1
	v_mov_b32_e32 v200, v164
	v_mov_b32_e32 v201, v165
	v_mov_b32_e32 v202, v166
	v_mov_b32_e32 v203, v167
	v_lshl_add_u64 v[204:205], v[158:159], 0, v[196:197]
	s_nop 0
	v_permlane16_swap_b32_e32 v200, v202
	v_permlane16_swap_b32_e32 v201, v203
	global_store_dwordx4 v[204:205], v[200:203], off offset:256
	v_ashrrev_i32_e32 v163, 31, v162
	v_lshl_add_u64 v[158:159], v[162:163], 1, v[156:157]
	v_cvt_pk_bf16_f32 v162, v28, v29
	v_cvt_pk_bf16_f32 v163, v30, v31
	v_cvt_pk_bf16_f32 v164, v24, v25
	v_cvt_pk_bf16_f32 v165, v26, v27
	s_nop 1
	v_mov_b32_e32 v192, v162
	v_mov_b32_e32 v193, v163
	v_mov_b32_e32 v194, v164
	v_mov_b32_e32 v195, v165
	v_lshl_add_u64 v[198:199], v[158:159], 0, v[196:197]
	s_nop 0
	v_permlane16_swap_b32_e32 v192, v194
	v_permlane16_swap_b32_e32 v193, v195
	global_store_dwordx4 v[198:199], v[192:195], off
	v_cvt_pk_bf16_f32 v162, v20, v21
	v_cvt_pk_bf16_f32 v163, v22, v23
	v_cvt_pk_bf16_f32 v164, v16, v17
	v_cvt_pk_bf16_f32 v165, v18, v19
	s_nop 1
	v_mov_b32_e32 v200, v162
	v_mov_b32_e32 v201, v163
	v_mov_b32_e32 v202, v164
	v_mov_b32_e32 v203, v165
	v_lshl_add_u64 v[204:205], v[158:159], 0, v[196:197]
	s_nop 0
	v_permlane16_swap_b32_e32 v200, v202
	v_permlane16_swap_b32_e32 v201, v203
	global_store_dwordx4 v[204:205], v[200:203], off offset:256
	v_ashrrev_i32_e32 v161, 31, v160
	v_lshl_add_u64 v[156:157], v[160:161], 1, v[156:157]
	v_cvt_pk_bf16_f32 v158, v12, v13
	v_cvt_pk_bf16_f32 v159, v14, v15
	v_cvt_pk_bf16_f32 v160, v8, v9
	v_cvt_pk_bf16_f32 v161, v10, v11
	s_nop 1
	v_mov_b32_e32 v192, v158
	v_mov_b32_e32 v193, v159
	v_mov_b32_e32 v194, v160
	v_mov_b32_e32 v195, v161
	v_lshl_add_u64 v[198:199], v[156:157], 0, v[196:197]
	s_nop 0
	v_permlane16_swap_b32_e32 v192, v194
	v_permlane16_swap_b32_e32 v193, v195
	global_store_dwordx4 v[198:199], v[192:195], off
	v_cvt_pk_bf16_f32 v158, v4, v5
	v_cvt_pk_bf16_f32 v159, v6, v7
	v_cvt_pk_bf16_f32 v160, v0, v1
	v_cvt_pk_bf16_f32 v161, v2, v3
	s_nop 1
	v_mov_b32_e32 v200, v158
	v_mov_b32_e32 v201, v159
	v_mov_b32_e32 v202, v160
	v_mov_b32_e32 v203, v161
	v_lshl_add_u64 v[204:205], v[156:157], 0, v[196:197]
	s_nop 0
	v_permlane16_swap_b32_e32 v200, v202
	v_permlane16_swap_b32_e32 v201, v203
	global_store_dwordx4 v[204:205], v[200:203], off offset:256

.LBB0_368:
	s_and_b64 vcc, exec, s[72:73]
	s_cbranch_vccz .LBB0_373
	s_ashr_i32 s69, s68, 31
	s_lshl_b64 s[4:5], s[68:69], 11
	s_add_u32 s6, s6, s4
	s_addc_u32 s7, s7, s5
	s_lshl_b32 s4, s26, 8
	s_ashr_i32 s5, s4, 31
	s_lshl_b64 s[4:5], s[4:5], 1
	s_add_u32 s4, s6, s4
	s_addc_u32 s5, s7, s5
	v_lshl_add_u64 v[154:155], v[154:155], 1, s[4:5]
	s_mov_b64 s[4:5], 0xb000000
	v_lshlrev_b32_e32 v164, 10, v182
	v_add_u32_e32 v170, 16, v182
	v_add_u32_e32 v169, 32, v182
	v_add_u32_e32 v168, 48, v182
	v_add_u32_e32 v167, 0x80, v182
	v_lshl_add_u64 v[154:155], v[154:155], 0, s[4:5]
	s_mov_b64 s[4:5], -1
	s_and_b64 vcc, exec, s[66:67]
	v_ashrrev_i32_e32 v165, 31, v164
	v_lshlrev_b32_e32 v162, 10, v170
	v_lshlrev_b32_e32 v160, 10, v169
	v_lshlrev_b32_e32 v158, 10, v168
	v_lshlrev_b32_e32 v156, 10, v167
	v_add_u32_e32 v166, 0x90, v182
	v_add_u32_e32 v96, 0xa0, v182
	s_cbranch_vccz .LBB0_371
	s_add_i32 s4, 0, 0x20000
	v_lshl_add_u32 v157, v182, 5, s4
	ds_read_b128 v[172:175], v157
	s_waitcnt lgkmcnt(0)
	v_mov_b32_e32 v176, v173
	v_mov_b32_e32 v177, v174
	v_mov_b32_e32 v173, v175
	v_pk_add_f32 v[172:173], v[176:177], v[172:173]
	s_nop 0
	v_add_f32_e32 v159, v172, v173
	v_fmamk_f32 v159, v159, 0x3c000000, v251
	v_rsq_f32_e32 v172, v159
	s_nop 0
	v_pk_mul_f32 v[174:175], v[126:127], v[172:173] op_sel_hi:[1,0]
	v_pk_mul_f32 v[176:177], v[128:129], v[172:173] op_sel_hi:[1,0]
	v_pk_mul_f32 v[184:185], v[122:123], v[172:173] op_sel_hi:[1,0]
	v_pk_mul_f32 v[172:173], v[124:125], v[172:173] op_sel_hi:[1,0]
	s_waitcnt vmcnt(0)
	v_pk_mul_f32 v[176:177], v[136:137], v[176:177]
	v_pk_mul_f32 v[174:175], v[134:135], v[174:175]
	v_pk_mul_f32 v[172:173], v[132:133], v[172:173]
	v_pk_mul_f32 v[184:185], v[130:131], v[184:185]
	v_cvt_pk_bf16_f32 v186, v174, v175
	v_cvt_pk_bf16_f32 v187, v176, v177
	s_nop 0
	v_cvt_pk_bf16_f32 v176, v184, v185
	v_cvt_pk_bf16_f32 v177, v172, v173
	ds_read_b128 v[172:175], v157 offset:16
	s_waitcnt lgkmcnt(0)
	v_mov_b32_e32 v184, v173
	v_mov_b32_e32 v185, v174
	v_mov_b32_e32 v173, v175
	v_pk_add_f32 v[172:173], v[184:185], v[172:173]
	v_lshl_add_u64 v[174:175], v[164:165], 1, v[154:155]
	v_add_f32_e32 v157, v172, v173
	v_fmamk_f32 v157, v157, 0x3c000000, v251
	v_rsq_f32_e32 v172, v157
	v_mbcnt_lo_u32_b32 v196, -1, 0
	v_mbcnt_hi_u32_b32 v196, -1, v196
	v_bfe_u32 v196, v196, 4, 1
	v_mul_u32_u24_e32 v196, 56, v196
	v_mov_b32_e32 v197, 0
	s_nop 1
	v_mov_b32_e32 v192, v186
	v_mov_b32_e32 v193, v187
	v_mov_b32_e32 v194, v176
	v_mov_b32_e32 v195, v177
	v_lshl_add_u64 v[198:199], v[174:175], 0, v[196:197]
	s_nop 0
	v_permlane16_swap_b32_e32 v192, v194
	v_permlane16_swap_b32_e32 v193, v195
	global_store_dwordx4 v[198:199], v[192:195], off
	v_pk_mul_f32 v[176:177], v[118:119], v[172:173] op_sel_hi:[1,0]
	v_pk_mul_f32 v[184:185], v[120:121], v[172:173] op_sel_hi:[1,0]
	v_pk_mul_f32 v[176:177], v[134:135], v[176:177]
	v_pk_mul_f32 v[184:185], v[136:137], v[184:185]
	v_pk_mul_f32 v[186:187], v[114:115], v[172:173] op_sel_hi:[1,0]
	v_pk_mul_f32 v[172:173], v[116:117], v[172:173] op_sel_hi:[1,0]
	v_cvt_pk_bf16_f32 v176, v176, v177
	v_cvt_pk_bf16_f32 v177, v184, v185
	v_pk_mul_f32 v[186:187], v[130:131], v[186:187]
	v_pk_mul_f32 v[172:173], v[132:133], v[172:173]
	v_cvt_pk_bf16_f32 v184, v186, v187
	s_nop 0
	v_cvt_pk_bf16_f32 v185, v172, v173
	s_nop 1
	v_mov_b32_e32 v200, v176
	v_mov_b32_e32 v201, v177
	v_mov_b32_e32 v202, v184
	v_mov_b32_e32 v203, v185
	v_lshl_add_u64 v[204:205], v[174:175], 0, v[196:197]
	s_nop 0
	v_permlane16_swap_b32_e32 v200, v202
	v_permlane16_swap_b32_e32 v201, v203
	global_store_dwordx4 v[204:205], v[200:203], off offset:256
	v_lshl_add_u32 v157, v170, 5, s4
	ds_read_b128 v[172:175], v157
	v_ashrrev_i32_e32 v163, 31, v162
	s_waitcnt lgkmcnt(0)
	v_mov_b32_e32 v176, v173
	v_mov_b32_e32 v177, v174
	v_mov_b32_e32 v173, v175
	v_pk_add_f32 v[172:173], v[176:177], v[172:173]
	s_nop 0
	v_add_f32_e32 v159, v172, v173
	v_fmamk_f32 v159, v159, 0x3c000000, v251
	v_rsq_f32_e32 v172, v159
	s_nop 0
	v_pk_mul_f32 v[174:175], v[110:111], v[172:173] op_sel_hi:[1,0]
	v_pk_mul_f32 v[176:177], v[112:113], v[172:173] op_sel_hi:[1,0]
	v_pk_mul_f32 v[184:185], v[106:107], v[172:173] op_sel_hi:[1,0]
	v_pk_mul_f32 v[172:173], v[108:109], v[172:173] op_sel_hi:[1,0]
	v_pk_mul_f32 v[176:177], v[136:137], v[176:177]
	v_pk_mul_f32 v[174:175], v[134:135], v[174:175]
	v_pk_mul_f32 v[172:173], v[132:133], v[172:173]
	v_pk_mul_f32 v[184:185], v[130:131], v[184:185]
	v_cvt_pk_bf16_f32 v186, v174, v175
	v_cvt_pk_bf16_f32 v187, v176, v177
	s_nop 0
	v_cvt_pk_bf16_f32 v176, v184, v185
	v_cvt_pk_bf16_f32 v177, v172, v173
	ds_read_b128 v[172:175], v157 offset:16
	s_waitcnt lgkmcnt(0)
	v_mov_b32_e32 v184, v173
	v_mov_b32_e32 v185, v174
	v_mov_b32_e32 v173, v175
	v_pk_add_f32 v[172:173], v[184:185], v[172:173]
	v_lshl_add_u64 v[174:175], v[162:163], 1, v[154:155]
	v_add_f32_e32 v157, v172, v173
	v_fmamk_f32 v157, v157, 0x3c000000, v251
	v_rsq_f32_e32 v172, v157
	s_nop 1
	v_mov_b32_e32 v192, v186
	v_mov_b32_e32 v193, v187
	v_mov_b32_e32 v194, v176
	v_mov_b32_e32 v195, v177
	v_lshl_add_u64 v[198:199], v[174:175], 0, v[196:197]
	s_nop 0
	v_permlane16_swap_b32_e32 v192, v194
	v_permlane16_swap_b32_e32 v193, v195
	global_store_dwordx4 v[198:199], v[192:195], off
	v_pk_mul_f32 v[176:177], v[102:103], v[172:173] op_sel_hi:[1,0]
	v_pk_mul_f32 v[184:185], v[104:105], v[172:173] op_sel_hi:[1,0]
	v_pk_mul_f32 v[176:177], v[134:135], v[176:177]
	v_pk_mul_f32 v[184:185], v[136:137], v[184:185]
	v_pk_mul_f32 v[186:187], v[98:99], v[172:173] op_sel_hi:[1,0]
	v_pk_mul_f32 v[172:173], v[100:101], v[172:173] op_sel_hi:[1,0]
	v_cvt_pk_bf16_f32 v176, v176, v177
	v_cvt_pk_bf16_f32 v177, v184, v185
	v_pk_mul_f32 v[186:187], v[130:131], v[186:187]
	v_pk_mul_f32 v[172:173], v[132:133], v[172:173]
	v_cvt_pk_bf16_f32 v184, v186, v187
	s_nop 0
	v_cvt_pk_bf16_f32 v185, v172, v173
	s_nop 1
	v_mov_b32_e32 v200, v176
	v_mov_b32_e32 v201, v177
	v_mov_b32_e32 v202, v184
	v_mov_b32_e32 v203, v185
	v_lshl_add_u64 v[204:205], v[174:175], 0, v[196:197]
	s_nop 0
	v_permlane16_swap_b32_e32 v200, v202
	v_permlane16_swap_b32_e32 v201, v203
	global_store_dwordx4 v[204:205], v[200:203], off offset:256
	v_lshl_add_u32 v157, v169, 5, s4
	ds_read_b128 v[172:175], v157
	v_ashrrev_i32_e32 v161, 31, v160
	s_waitcnt lgkmcnt(0)
	v_mov_b32_e32 v176, v173
	v_mov_b32_e32 v177, v174
	v_mov_b32_e32 v173, v175
	v_pk_add_f32 v[172:173], v[176:177], v[172:173]
	s_nop 0
	v_add_f32_e32 v159, v172, v173
	v_fmamk_f32 v159, v159, 0x3c000000, v251
	v_rsq_f32_e32 v172, v159
	s_nop 0
	v_pk_mul_f32 v[174:175], v[92:93], v[172:173] op_sel_hi:[1,0]
	v_pk_mul_f32 v[176:177], v[94:95], v[172:173] op_sel_hi:[1,0]
	v_pk_mul_f32 v[184:185], v[88:89], v[172:173] op_sel_hi:[1,0]
	v_pk_mul_f32 v[172:173], v[90:91], v[172:173] op_sel_hi:[1,0]
	v_pk_mul_f32 v[176:177], v[136:137], v[176:177]
	v_pk_mul_f32 v[174:175], v[134:135], v[174:175]
	v_pk_mul_f32 v[172:173], v[132:133], v[172:173]
	v_pk_mul_f32 v[184:185], v[130:131], v[184:185]
	v_cvt_pk_bf16_f32 v186, v174, v175
	v_cvt_pk_bf16_f32 v187, v176, v177
	s_nop 0
	v_cvt_pk_bf16_f32 v176, v184, v185
	v_cvt_pk_bf16_f32 v177, v172, v173
	ds_read_b128 v[172:175], v157 offset:16
	s_waitcnt lgkmcnt(0)
	v_mov_b32_e32 v184, v173
	v_mov_b32_e32 v185, v174
	v_mov_b32_e32 v173, v175
	v_pk_add_f32 v[172:173], v[184:185], v[172:173]
	v_lshl_add_u64 v[174:175], v[160:161], 1, v[154:155]
	v_add_f32_e32 v157, v172, v173
	v_fmamk_f32 v157, v157, 0x3c000000, v251
	v_rsq_f32_e32 v172, v157
	s_nop 1
	v_mov_b32_e32 v192, v186
	v_mov_b32_e32 v193, v187
	v_mov_b32_e32 v194, v176
	v_mov_b32_e32 v195, v177
	v_lshl_add_u64 v[198:199], v[174:175], 0, v[196:197]
	s_nop 0
	v_permlane16_swap_b32_e32 v192, v194
	v_permlane16_swap_b32_e32 v193, v195
	global_store_dwordx4 v[198:199], v[192:195], off
	v_pk_mul_f32 v[176:177], v[84:85], v[172:173] op_sel_hi:[1,0]
	v_pk_mul_f32 v[184:185], v[86:87], v[172:173] op_sel_hi:[1,0]
	v_pk_mul_f32 v[176:177], v[134:135], v[176:177]
	v_pk_mul_f32 v[184:185], v[136:137], v[184:185]
	v_pk_mul_f32 v[186:187], v[80:81], v[172:173] op_sel_hi:[1,0]
	v_pk_mul_f32 v[172:173], v[82:83], v[172:173] op_sel_hi:[1,0]
	v_cvt_pk_bf16_f32 v176, v176, v177
	v_cvt_pk_bf16_f32 v177, v184, v185
	v_pk_mul_f32 v[186:187], v[130:131], v[186:187]
	v_pk_mul_f32 v[172:173], v[132:133], v[172:173]
	v_cvt_pk_bf16_f32 v184, v186, v187
	s_nop 0
	v_cvt_pk_bf16_f32 v185, v172, v173
	s_nop 1
	v_mov_b32_e32 v200, v176
	v_mov_b32_e32 v201, v177
	v_mov_b32_e32 v202, v184
	v_mov_b32_e32 v203, v185
	v_lshl_add_u64 v[204:205], v[174:175], 0, v[196:197]
	s_nop 0
	v_permlane16_swap_b32_e32 v200, v202
	v_permlane16_swap_b32_e32 v201, v203
	global_store_dwordx4 v[204:205], v[200:203], off offset:256
	v_lshl_add_u32 v157, v168, 5, s4
	ds_read_b128 v[172:175], v157
	s_waitcnt lgkmcnt(0)
	v_mov_b32_e32 v176, v173
	v_mov_b32_e32 v177, v174
	v_mov_b32_e32 v173, v175
	v_pk_add_f32 v[172:173], v[176:177], v[172:173]
	s_nop 0
	v_add_f32_e32 v159, v172, v173
	v_fmamk_f32 v159, v159, 0x3c000000, v251
	v_rsq_f32_e32 v172, v159
	v_ashrrev_i32_e32 v159, 31, v158
	v_pk_mul_f32 v[174:175], v[76:77], v[172:173] op_sel_hi:[1,0]
	v_pk_mul_f32 v[176:177], v[78:79], v[172:173] op_sel_hi:[1,0]
	v_pk_mul_f32 v[184:185], v[72:73], v[172:173] op_sel_hi:[1,0]
	v_pk_mul_f32 v[172:173], v[74:75], v[172:173] op_sel_hi:[1,0]
	v_pk_mul_f32 v[176:177], v[136:137], v[176:177]
	v_pk_mul_f32 v[174:175], v[134:135], v[174:175]
	v_pk_mul_f32 v[172:173], v[132:133], v[172:173]
	v_pk_mul_f32 v[184:185], v[130:131], v[184:185]
	v_cvt_pk_bf16_f32 v186, v174, v175
	v_cvt_pk_bf16_f32 v187, v176, v177
	s_nop 0
	v_cvt_pk_bf16_f32 v176, v184, v185
	v_cvt_pk_bf16_f32 v177, v172, v173
	ds_read_b128 v[172:175], v157 offset:16
	s_waitcnt lgkmcnt(0)
	v_mov_b32_e32 v184, v173
	v_mov_b32_e32 v185, v174
	v_mov_b32_e32 v173, v175
	v_pk_add_f32 v[172:173], v[184:185], v[172:173]
	v_lshl_add_u64 v[174:175], v[158:159], 1, v[154:155]
	v_add_f32_e32 v157, v172, v173
	v_fmamk_f32 v157, v157, 0x3c000000, v251
	v_rsq_f32_e32 v172, v157
	s_nop 1
	v_mov_b32_e32 v192, v186
	v_mov_b32_e32 v193, v187
	v_mov_b32_e32 v194, v176
	v_mov_b32_e32 v195, v177
	v_lshl_add_u64 v[198:199], v[174:175], 0, v[196:197]
	s_nop 0
	v_permlane16_swap_b32_e32 v192, v194
	v_permlane16_swap_b32_e32 v193, v195
	global_store_dwordx4 v[198:199], v[192:195], off
	v_pk_mul_f32 v[176:177], v[68:69], v[172:173] op_sel_hi:[1,0]
	v_pk_mul_f32 v[184:185], v[70:71], v[172:173] op_sel_hi:[1,0]
	v_pk_mul_f32 v[176:177], v[134:135], v[176:177]
	v_pk_mul_f32 v[184:185], v[136:137], v[184:185]
	v_pk_mul_f32 v[186:187], v[64:65], v[172:173] op_sel_hi:[1,0]
	v_pk_mul_f32 v[172:173], v[66:67], v[172:173] op_sel_hi:[1,0]
	v_cvt_pk_bf16_f32 v176, v176, v177
	v_cvt_pk_bf16_f32 v177, v184, v185
	v_pk_mul_f32 v[186:187], v[130:131], v[186:187]
	v_pk_mul_f32 v[172:173], v[132:133], v[172:173]
	v_cvt_pk_bf16_f32 v184, v186, v187
	s_nop 0
	v_cvt_pk_bf16_f32 v185, v172, v173
	s_nop 1
	v_mov_b32_e32 v200, v176
	v_mov_b32_e32 v201, v177
	v_mov_b32_e32 v202, v184
	v_mov_b32_e32 v203, v185
	v_lshl_add_u64 v[204:205], v[174:175], 0, v[196:197]
	s_nop 0
	v_permlane16_swap_b32_e32 v200, v202
	v_permlane16_swap_b32_e32 v201, v203
	global_store_dwordx4 v[204:205], v[200:203], off offset:256
	v_lshl_add_u32 v157, v167, 5, s4
	ds_read_b128 v[172:175], v157
	s_waitcnt lgkmcnt(0)
	v_mov_b32_e32 v176, v173
	v_mov_b32_e32 v177, v174
	v_mov_b32_e32 v173, v175
	v_pk_add_f32 v[172:173], v[176:177], v[172:173]
	s_nop 0
	v_add_f32_e32 v159, v172, v173
	v_fmamk_f32 v159, v159, 0x3c000000, v251
	v_rsq_f32_e32 v172, v159
	s_nop 0
	v_pk_mul_f32 v[174:175], v[60:61], v[172:173] op_sel_hi:[1,0]
	v_pk_mul_f32 v[176:177], v[62:63], v[172:173] op_sel_hi:[1,0]
	v_pk_mul_f32 v[184:185], v[56:57], v[172:173] op_sel_hi:[1,0]
	v_pk_mul_f32 v[172:173], v[58:59], v[172:173] op_sel_hi:[1,0]
	v_pk_mul_f32 v[176:177], v[136:137], v[176:177]
	v_pk_mul_f32 v[174:175], v[134:135], v[174:175]
	v_pk_mul_f32 v[172:173], v[132:133], v[172:173]
	v_pk_mul_f32 v[184:185], v[130:131], v[184:185]
	v_cvt_pk_bf16_f32 v186, v174, v175
	v_cvt_pk_bf16_f32 v187, v176, v177
	s_nop 0
	v_cvt_pk_bf16_f32 v176, v184, v185
	v_cvt_pk_bf16_f32 v177, v172, v173
	ds_read_b128 v[172:175], v157 offset:16
	v_ashrrev_i32_e32 v157, 31, v156
	s_waitcnt lgkmcnt(0)
	v_mov_b32_e32 v184, v173
	v_mov_b32_e32 v185, v174
	v_mov_b32_e32 v173, v175
	v_pk_add_f32 v[172:173], v[184:185], v[172:173]
	v_lshl_add_u64 v[174:175], v[156:157], 1, v[154:155]
	v_add_f32_e32 v159, v172, v173
	v_fmamk_f32 v159, v159, 0x3c000000, v251
	v_rsq_f32_e32 v172, v159
	s_nop 1
	v_mov_b32_e32 v192, v186
	v_mov_b32_e32 v193, v187
	v_mov_b32_e32 v194, v176
	v_mov_b32_e32 v195, v177
	v_lshl_add_u64 v[198:199], v[174:175], 0, v[196:197]
	s_nop 0
	v_permlane16_swap_b32_e32 v192, v194
	v_permlane16_swap_b32_e32 v193, v195
	global_store_dwordx4 v[198:199], v[192:195], off
	v_pk_mul_f32 v[176:177], v[52:53], v[172:173] op_sel_hi:[1,0]
	v_pk_mul_f32 v[184:185], v[54:55], v[172:173] op_sel_hi:[1,0]
	v_pk_mul_f32 v[176:177], v[134:135], v[176:177]
	v_pk_mul_f32 v[184:185], v[136:137], v[184:185]
	v_pk_mul_f32 v[186:187], v[48:49], v[172:173] op_sel_hi:[1,0]
	v_pk_mul_f32 v[172:173], v[50:51], v[172:173] op_sel_hi:[1,0]
	v_cvt_pk_bf16_f32 v176, v176, v177
	v_cvt_pk_bf16_f32 v177, v184, v185
	v_pk_mul_f32 v[186:187], v[130:131], v[186:187]
	v_pk_mul_f32 v[172:173], v[132:133], v[172:173]
	v_cvt_pk_bf16_f32 v184, v186, v187
	s_nop 0
	v_cvt_pk_bf16_f32 v185, v172, v173
	s_nop 1
	v_mov_b32_e32 v200, v176
	v_mov_b32_e32 v201, v177
	v_mov_b32_e32 v202, v184
	v_mov_b32_e32 v203, v185
	v_lshl_add_u64 v[204:205], v[174:175], 0, v[196:197]
	s_nop 0
	v_permlane16_swap_b32_e32 v200, v202
	v_permlane16_swap_b32_e32 v201, v203
	global_store_dwordx4 v[204:205], v[200:203], off offset:256
	v_lshlrev_b32_e32 v172, 10, v166
	v_lshl_add_u32 v157, v166, 5, s4
	v_ashrrev_i32_e32 v173, 31, v172
	v_lshl_add_u64 v[176:177], v[172:173], 1, v[154:155]
	ds_read_b128 v[172:175], v157
	s_waitcnt lgkmcnt(0)
	v_mov_b32_e32 v184, v173
	v_mov_b32_e32 v185, v174
	v_mov_b32_e32 v173, v175
	v_pk_add_f32 v[172:173], v[184:185], v[172:173]
	s_nop 0
	v_add_f32_e32 v159, v172, v173
	v_fmamk_f32 v159, v159, 0x3c000000, v251
	v_rsq_f32_e32 v172, v159
	s_nop 0
	v_pk_mul_f32 v[174:175], v[44:45], v[172:173] op_sel_hi:[1,0]
	v_pk_mul_f32 v[184:185], v[46:47], v[172:173] op_sel_hi:[1,0]
	v_pk_mul_f32 v[174:175], v[134:135], v[174:175]
	v_pk_mul_f32 v[184:185], v[136:137], v[184:185]
	v_pk_mul_f32 v[186:187], v[40:41], v[172:173] op_sel_hi:[1,0]
	v_pk_mul_f32 v[172:173], v[42:43], v[172:173] op_sel_hi:[1,0]
	v_cvt_pk_bf16_f32 v174, v174, v175
	v_cvt_pk_bf16_f32 v175, v184, v185
	v_pk_mul_f32 v[186:187], v[130:131], v[186:187]
	v_pk_mul_f32 v[172:173], v[132:133], v[172:173]
	v_cvt_pk_bf16_f32 v184, v186, v187
	s_nop 0
	v_cvt_pk_bf16_f32 v185, v172, v173
	s_nop 1
	v_mov_b32_e32 v192, v174
	v_mov_b32_e32 v193, v175
	v_mov_b32_e32 v194, v184
	v_mov_b32_e32 v195, v185
	v_lshl_add_u64 v[198:199], v[176:177], 0, v[196:197]
	s_nop 0
	v_permlane16_swap_b32_e32 v192, v194
	v_permlane16_swap_b32_e32 v193, v195
	global_store_dwordx4 v[198:199], v[192:195], off
	ds_read_b128 v[172:175], v157 offset:16
	s_waitcnt lgkmcnt(0)
	v_mov_b32_e32 v184, v173
	v_mov_b32_e32 v185, v174
	v_mov_b32_e32 v173, v175
	v_pk_add_f32 v[172:173], v[184:185], v[172:173]
	s_nop 0
	v_add_f32_e32 v157, v172, v173
	v_fmamk_f32 v157, v157, 0x3c000000, v251
	v_rsq_f32_e32 v172, v157
	s_nop 0
	v_pk_mul_f32 v[174:175], v[36:37], v[172:173] op_sel_hi:[1,0]
	v_pk_mul_f32 v[184:185], v[38:39], v[172:173] op_sel_hi:[1,0]
	v_pk_mul_f32 v[174:175], v[134:135], v[174:175]
	v_pk_mul_f32 v[184:185], v[136:137], v[184:185]
	v_pk_mul_f32 v[186:187], v[32:33], v[172:173] op_sel_hi:[1,0]
	v_pk_mul_f32 v[172:173], v[34:35], v[172:173] op_sel_hi:[1,0]
	v_cvt_pk_bf16_f32 v174, v174, v175
	v_cvt_pk_bf16_f32 v175, v184, v185
	v_pk_mul_f32 v[186:187], v[130:131], v[186:187]
	v_pk_mul_f32 v[172:173], v[132:133], v[172:173]
	v_cvt_pk_bf16_f32 v184, v186, v187
	s_nop 0
	v_cvt_pk_bf16_f32 v185, v172, v173
	s_nop 1
	v_mov_b32_e32 v200, v174
	v_mov_b32_e32 v201, v175
	v_mov_b32_e32 v202, v184
	v_mov_b32_e32 v203, v185
	v_lshl_add_u64 v[204:205], v[176:177], 0, v[196:197]
	s_nop 0
	v_permlane16_swap_b32_e32 v200, v202
	v_permlane16_swap_b32_e32 v201, v203
	global_store_dwordx4 v[204:205], v[200:203], off offset:256
	v_lshlrev_b32_e32 v172, 10, v96
	v_lshl_add_u32 v157, v96, 5, s4
	v_ashrrev_i32_e32 v173, 31, v172
	v_lshl_add_u64 v[176:177], v[172:173], 1, v[154:155]
	ds_read_b128 v[172:175], v157
	s_waitcnt lgkmcnt(0)
	v_mov_b32_e32 v184, v173
	v_mov_b32_e32 v185, v174
	v_mov_b32_e32 v173, v175
	v_pk_add_f32 v[172:173], v[184:185], v[172:173]
	s_nop 0
	v_add_f32_e32 v159, v172, v173
	v_fmamk_f32 v159, v159, 0x3c000000, v251
	v_rsq_f32_e32 v172, v159
	s_nop 0
	v_pk_mul_f32 v[174:175], v[28:29], v[172:173] op_sel_hi:[1,0]
	v_pk_mul_f32 v[184:185], v[30:31], v[172:173] op_sel_hi:[1,0]
	v_pk_mul_f32 v[174:175], v[134:135], v[174:175]
	v_pk_mul_f32 v[184:185], v[136:137], v[184:185]
	v_pk_mul_f32 v[186:187], v[24:25], v[172:173] op_sel_hi:[1,0]
	v_pk_mul_f32 v[172:173], v[26:27], v[172:173] op_sel_hi:[1,0]
	v_cvt_pk_bf16_f32 v174, v174, v175
	v_cvt_pk_bf16_f32 v175, v184, v185
	v_pk_mul_f32 v[186:187], v[130:131], v[186:187]
	v_pk_mul_f32 v[172:173], v[132:133], v[172:173]
	v_cvt_pk_bf16_f32 v184, v186, v187
	s_nop 0
	v_cvt_pk_bf16_f32 v185, v172, v173
	s_nop 1
	v_mov_b32_e32 v192, v174
	v_mov_b32_e32 v193, v175
	v_mov_b32_e32 v194, v184
	v_mov_b32_e32 v195, v185
	v_lshl_add_u64 v[198:199], v[176:177], 0, v[196:197]
	s_nop 0
	v_permlane16_swap_b32_e32 v192, v194
	v_permlane16_swap_b32_e32 v193, v195
	global_store_dwordx4 v[198:199], v[192:195], off
	ds_read_b128 v[172:175], v157 offset:16
	s_waitcnt lgkmcnt(0)
	v_mov_b32_e32 v184, v173
	v_mov_b32_e32 v185, v174
	v_mov_b32_e32 v173, v175
	v_pk_add_f32 v[172:173], v[184:185], v[172:173]
	s_nop 0
	v_add_f32_e32 v157, v172, v173
	v_fmamk_f32 v157, v157, 0x3c000000, v251
	v_rsq_f32_e32 v172, v157
	s_nop 0
	v_pk_mul_f32 v[174:175], v[20:21], v[172:173] op_sel_hi:[1,0]
	v_pk_mul_f32 v[184:185], v[22:23], v[172:173] op_sel_hi:[1,0]
	v_pk_mul_f32 v[174:175], v[134:135], v[174:175]
	v_pk_mul_f32 v[184:185], v[136:137], v[184:185]
	v_pk_mul_f32 v[186:187], v[16:17], v[172:173] op_sel_hi:[1,0]
	v_pk_mul_f32 v[172:173], v[18:19], v[172:173] op_sel_hi:[1,0]
	v_cvt_pk_bf16_f32 v174, v174, v175
	v_cvt_pk_bf16_f32 v175, v184, v185
	v_pk_mul_f32 v[186:187], v[130:131], v[186:187]
	v_pk_mul_f32 v[172:173], v[132:133], v[172:173]
	v_cvt_pk_bf16_f32 v184, v186, v187
	s_nop 0
	v_cvt_pk_bf16_f32 v185, v172, v173
	s_nop 1
	v_mov_b32_e32 v200, v174
	v_mov_b32_e32 v201, v175
	v_mov_b32_e32 v202, v184
	v_mov_b32_e32 v203, v185
	v_lshl_add_u64 v[204:205], v[176:177], 0, v[196:197]
	s_nop 0
	v_permlane16_swap_b32_e32 v200, v202
	v_permlane16_swap_b32_e32 v201, v203
	global_store_dwordx4 v[204:205], v[200:203], off offset:256
	v_add_u32_e32 v157, 0xb0, v182
	v_lshlrev_b32_e32 v172, 10, v157
	v_lshl_add_u32 v159, v157, 5, s4
	v_ashrrev_i32_e32 v173, 31, v172
	v_lshl_add_u64 v[176:177], v[172:173], 1, v[154:155]
	ds_read_b128 v[172:175], v159
	s_waitcnt lgkmcnt(0)
	v_mov_b32_e32 v184, v173
	v_mov_b32_e32 v185, v174
	v_mov_b32_e32 v173, v175
	v_pk_add_f32 v[172:173], v[184:185], v[172:173]
	s_nop 0
	v_add_f32_e32 v157, v172, v173
	v_fmamk_f32 v157, v157, 0x3c000000, v251
	v_rsq_f32_e32 v172, v157
	s_nop 0
	v_pk_mul_f32 v[174:175], v[12:13], v[172:173] op_sel_hi:[1,0]
	v_pk_mul_f32 v[184:185], v[14:15], v[172:173] op_sel_hi:[1,0]
	v_pk_mul_f32 v[174:175], v[134:135], v[174:175]
	v_pk_mul_f32 v[184:185], v[136:137], v[184:185]
	v_pk_mul_f32 v[186:187], v[8:9], v[172:173] op_sel_hi:[1,0]
	v_pk_mul_f32 v[172:173], v[10:11], v[172:173] op_sel_hi:[1,0]
	v_cvt_pk_bf16_f32 v174, v174, v175
	v_cvt_pk_bf16_f32 v175, v184, v185
	v_pk_mul_f32 v[186:187], v[130:131], v[186:187]
	v_pk_mul_f32 v[172:173], v[132:133], v[172:173]
	v_cvt_pk_bf16_f32 v184, v186, v187
	s_nop 0
	v_cvt_pk_bf16_f32 v185, v172, v173
	s_nop 1
	v_mov_b32_e32 v192, v174
	v_mov_b32_e32 v193, v175
	v_mov_b32_e32 v194, v184
	v_mov_b32_e32 v195, v185
	v_lshl_add_u64 v[198:199], v[176:177], 0, v[196:197]
	s_nop 0
	v_permlane16_swap_b32_e32 v192, v194
	v_permlane16_swap_b32_e32 v193, v195
	global_store_dwordx4 v[198:199], v[192:195], off
	ds_read_b128 v[172:175], v159 offset:16
	s_waitcnt lgkmcnt(0)
	v_mov_b32_e32 v184, v173
	v_mov_b32_e32 v185, v174
	v_mov_b32_e32 v173, v175
	v_pk_add_f32 v[172:173], v[184:185], v[172:173]
	s_nop 0
	v_add_f32_e32 v157, v172, v173
	v_fmamk_f32 v157, v157, 0x3c000000, v251
	v_rsq_f32_e32 v172, v157
	s_nop 0
	v_pk_mul_f32 v[174:175], v[4:5], v[172:173] op_sel_hi:[1,0]
	v_pk_mul_f32 v[184:185], v[6:7], v[172:173] op_sel_hi:[1,0]
	v_pk_mul_f32 v[174:175], v[134:135], v[174:175]
	v_pk_mul_f32 v[184:185], v[136:137], v[184:185]
	v_pk_mul_f32 v[186:187], v[0:1], v[172:173] op_sel_hi:[1,0]
	v_pk_mul_f32 v[172:173], v[2:3], v[172:173] op_sel_hi:[1,0]
	v_cvt_pk_bf16_f32 v174, v174, v175
	v_cvt_pk_bf16_f32 v175, v184, v185
	v_pk_mul_f32 v[186:187], v[130:131], v[186:187]
	v_pk_mul_f32 v[172:173], v[132:133], v[172:173]
	v_cvt_pk_bf16_f32 v184, v186, v187
	s_nop 0
	v_cvt_pk_bf16_f32 v185, v172, v173
	s_nop 1
	v_mov_b32_e32 v200, v174
	v_mov_b32_e32 v201, v175
	v_mov_b32_e32 v202, v184
	v_mov_b32_e32 v203, v185
	v_lshl_add_u64 v[204:205], v[176:177], 0, v[196:197]
	s_nop 0
	v_permlane16_swap_b32_e32 v200, v202
	v_permlane16_swap_b32_e32 v201, v203
	global_store_dwordx4 v[204:205], v[200:203], off offset:256
	s_mov_b64 s[4:5], 0
.LBB0_371:
	s_andn2_b64 vcc, exec, s[4:5]
	s_cbranch_vccnz .LBB0_373
	s_cmp_lt_u32 s21, 2
	v_add_u32_e32 v159, s19, v182
	v_and_b32_e32 v157, 63, v183
	v_ashrrev_i32_e32 v159, 6, v159
	s_cselect_b64 vcc, -1, 0
	v_cndmask_b32_e32 v159, v157, v159, vcc
	v_cvt_f32_i32_e32 v159, v159
	s_add_i32 s4, 0, 0x20000
	v_lshl_add_u32 v171, v182, 5, s4
	ds_read_b128 v[172:175], v171
	v_mul_f32_e32 v163, v152, v159
	v_fract_f32_e32 v163, v163
	v_sin_f32_e32 v176, v163
	v_cos_f32_e32 v184, v163
	v_mul_f32_e32 v163, v153, v159
	v_fract_f32_e32 v163, v163
	v_sin_f32_e32 v177, v163
	v_cos_f32_e32 v185, v163
	v_mul_f32_e32 v163, v150, v159
	s_waitcnt lgkmcnt(0)
	v_mov_b32_e32 v190, v173
	v_mov_b32_e32 v191, v174
	v_mov_b32_e32 v173, v175
	v_fract_f32_e32 v163, v163
	v_pk_add_f32 v[172:173], v[190:191], v[172:173]
	v_sin_f32_e32 v186, v163
	v_cos_f32_e32 v188, v163
	v_add_f32_e32 v163, v172, v173
	v_fmamk_f32 v163, v163, 0x3c000000, v251
	v_mul_f32_e32 v159, v151, v159
	v_rsq_f32_e32 v172, v163
	v_fract_f32_e32 v159, v159
	v_sin_f32_e32 v187, v159
	v_cos_f32_e32 v189, v159
	v_pk_mul_f32 v[122:123], v[122:123], v[172:173] op_sel_hi:[1,0]
	v_pk_mul_f32 v[124:125], v[124:125], v[172:173] op_sel_hi:[1,0]
	v_pk_mul_f32 v[128:129], v[128:129], v[172:173] op_sel_hi:[1,0]
	v_pk_mul_f32 v[126:127], v[126:127], v[172:173] op_sel_hi:[1,0]
	s_waitcnt vmcnt(0)
	v_pk_mul_f32 v[124:125], v[132:133], v[124:125]
	v_pk_mul_f32 v[122:123], v[130:131], v[122:123]
	v_pk_mul_f32 v[126:127], v[134:135], v[126:127]
	v_pk_mul_f32 v[128:129], v[136:137], v[128:129]
	v_pk_mul_f32 v[172:173], v[176:177], v[122:123]
	v_pk_mul_f32 v[174:175], v[186:187], v[124:125]
	v_pk_fma_f32 v[172:173], v[184:185], v[126:127], v[172:173] neg_lo:[0,0,1] neg_hi:[0,0,1]
	v_pk_fma_f32 v[174:175], v[188:189], v[128:129], v[174:175] neg_lo:[0,0,1] neg_hi:[0,0,1]
	v_pk_mul_f32 v[126:127], v[176:177], v[126:127]
	v_pk_mul_f32 v[128:129], v[186:187], v[128:129]
	v_pk_fma_f32 v[122:123], v[184:185], v[122:123], v[126:127]
	v_pk_fma_f32 v[124:125], v[188:189], v[124:125], v[128:129]
	v_cvt_pk_bf16_f32 v172, v172, v173
	v_cvt_pk_bf16_f32 v173, v174, v175
	v_cvt_pk_bf16_f32 v174, v122, v123
	v_add_u32_e32 v161, 16, v183
	v_cvt_pk_bf16_f32 v175, v124, v125
	ds_read_b128 v[126:129], v171 offset:16
	v_add_u32_e32 v122, 48, v183
	v_and_b32_e32 v124, 63, v161
	v_bitop3_b32 v123, v183, 32, 63 bitop3:0x6c
	v_and_b32_e32 v122, 63, v122
	s_waitcnt lgkmcnt(0)
	v_mov_b32_e32 v190, v127
	v_mov_b32_e32 v191, v128
	v_mov_b32_e32 v127, v129
	v_pk_add_f32 v[126:127], v[190:191], v[126:127]
	v_lshl_add_u64 v[128:129], v[164:165], 1, v[154:155]
	v_add_f32_e32 v125, v126, v127
	v_fmamk_f32 v125, v125, 0x3c000000, v251
	v_rsq_f32_e32 v126, v125
	v_mbcnt_lo_u32_b32 v196, -1, 0
	v_mbcnt_hi_u32_b32 v196, -1, v196
	v_bfe_u32 v196, v196, 4, 1
	v_mul_u32_u24_e32 v196, 56, v196
	v_mov_b32_e32 v197, 0
	s_nop 1
	v_mov_b32_e32 v192, v172
	v_mov_b32_e32 v193, v173
	v_mov_b32_e32 v194, v174
	v_mov_b32_e32 v195, v175
	v_lshl_add_u64 v[198:199], v[128:129], 0, v[196:197]
	s_nop 0
	v_permlane16_swap_b32_e32 v192, v194
	v_permlane16_swap_b32_e32 v193, v195
	global_store_dwordx4 v[198:199], v[192:195], off
	v_pk_mul_f32 v[114:115], v[114:115], v[126:127] op_sel_hi:[1,0]
	v_pk_mul_f32 v[118:119], v[118:119], v[126:127] op_sel_hi:[1,0]
	v_pk_mul_f32 v[116:117], v[116:117], v[126:127] op_sel_hi:[1,0]
	v_pk_mul_f32 v[114:115], v[130:131], v[114:115]
	v_pk_mul_f32 v[120:121], v[120:121], v[126:127] op_sel_hi:[1,0]
	v_pk_mul_f32 v[118:119], v[134:135], v[118:119]
	v_pk_mul_f32 v[116:117], v[132:133], v[116:117]
	v_pk_mul_f32 v[126:127], v[176:177], v[114:115]
	v_pk_mul_f32 v[120:121], v[136:137], v[120:121]
	v_pk_mul_f32 v[164:165], v[186:187], v[116:117]
	v_pk_fma_f32 v[126:127], v[184:185], v[118:119], v[126:127] neg_lo:[0,0,1] neg_hi:[0,0,1]
	v_pk_mul_f32 v[118:119], v[176:177], v[118:119]
	v_pk_fma_f32 v[164:165], v[188:189], v[120:121], v[164:165] neg_lo:[0,0,1] neg_hi:[0,0,1]
	v_pk_mul_f32 v[120:121], v[186:187], v[120:121]
	v_pk_fma_f32 v[114:115], v[184:185], v[114:115], v[118:119]
	v_cvt_pk_bf16_f32 v118, v126, v127
	v_cvt_pk_bf16_f32 v119, v164, v165
	v_pk_fma_f32 v[116:117], v[188:189], v[116:117], v[120:121]
	v_cvt_pk_bf16_f32 v114, v114, v115
	s_nop 0
	v_cvt_pk_bf16_f32 v115, v116, v117
	s_nop 1
	v_mov_b32_e32 v200, v118
	v_mov_b32_e32 v201, v119
	v_mov_b32_e32 v202, v114
	v_mov_b32_e32 v203, v115
	v_lshl_add_u64 v[204:205], v[128:129], 0, v[196:197]
	s_nop 0
	v_permlane16_swap_b32_e32 v200, v202
	v_permlane16_swap_b32_e32 v201, v203
	global_store_dwordx4 v[204:205], v[200:203], off offset:256
	v_add_u32_e32 v114, s19, v170
	v_ashrrev_i32_e32 v114, 6, v114
	v_cndmask_b32_e32 v114, v124, v114, vcc
	v_cvt_f32_i32_e32 v125, v114
	v_lshl_add_u32 v159, v170, 5, s4
	v_ashrrev_i32_e32 v163, 31, v162
	v_mul_f32_e32 v114, v152, v125
	v_mul_f32_e32 v115, v153, v125
	v_fract_f32_e32 v114, v114
	v_fract_f32_e32 v115, v115
	v_sin_f32_e32 v118, v114
	v_cos_f32_e32 v120, v114
	v_sin_f32_e32 v119, v115
	v_cos_f32_e32 v121, v115
	ds_read_b128 v[114:117], v159
	v_mul_f32_e32 v126, v150, v125
	v_mul_f32_e32 v125, v151, v125
	v_fract_f32_e32 v127, v126
	v_sin_f32_e32 v126, v127
	s_waitcnt lgkmcnt(0)
	v_mov_b32_e32 v164, v115
	v_mov_b32_e32 v165, v116
	v_mov_b32_e32 v115, v117
	v_pk_add_f32 v[114:115], v[164:165], v[114:115]
	v_cos_f32_e32 v128, v127
	v_add_f32_e32 v114, v114, v115
	v_fmamk_f32 v114, v114, 0x3c000000, v251
	v_rsq_f32_e32 v114, v114
	v_fract_f32_e32 v115, v125
	v_sin_f32_e32 v127, v115
	v_cos_f32_e32 v129, v115
	v_pk_mul_f32 v[106:107], v[106:107], v[114:115] op_sel_hi:[1,0]
	v_pk_mul_f32 v[108:109], v[108:109], v[114:115] op_sel_hi:[1,0]
	v_pk_mul_f32 v[112:113], v[112:113], v[114:115] op_sel_hi:[1,0]
	v_pk_mul_f32 v[110:111], v[110:111], v[114:115] op_sel_hi:[1,0]
	v_pk_mul_f32 v[108:109], v[132:133], v[108:109]
	v_pk_mul_f32 v[106:107], v[130:131], v[106:107]
	v_pk_mul_f32 v[110:111], v[134:135], v[110:111]
	v_pk_mul_f32 v[112:113], v[136:137], v[112:113]
	v_pk_mul_f32 v[114:115], v[118:119], v[106:107]
	v_pk_mul_f32 v[116:117], v[126:127], v[108:109]
	v_pk_fma_f32 v[114:115], v[120:121], v[110:111], v[114:115] neg_lo:[0,0,1] neg_hi:[0,0,1]
	v_pk_fma_f32 v[116:117], v[128:129], v[112:113], v[116:117] neg_lo:[0,0,1] neg_hi:[0,0,1]
	v_pk_mul_f32 v[110:111], v[118:119], v[110:111]
	v_pk_mul_f32 v[112:113], v[126:127], v[112:113]
	v_pk_fma_f32 v[106:107], v[120:121], v[106:107], v[110:111]
	v_pk_fma_f32 v[108:109], v[128:129], v[108:109], v[112:113]
	v_cvt_pk_bf16_f32 v110, v114, v115
	v_cvt_pk_bf16_f32 v111, v116, v117
	v_cvt_pk_bf16_f32 v112, v106, v107
	s_nop 0
	v_cvt_pk_bf16_f32 v113, v108, v109
	ds_read_b128 v[106:109], v159 offset:16
	s_waitcnt lgkmcnt(0)
	v_mov_b32_e32 v114, v107
	v_mov_b32_e32 v115, v108
	v_mov_b32_e32 v107, v109
	v_pk_add_f32 v[106:107], v[114:115], v[106:107]
	v_lshl_add_u64 v[108:109], v[162:163], 1, v[154:155]
	v_add_f32_e32 v106, v106, v107
	v_fmamk_f32 v106, v106, 0x3c000000, v251
	v_rsq_f32_e32 v106, v106
	s_nop 1
	v_mov_b32_e32 v192, v110
	v_mov_b32_e32 v193, v111
	v_mov_b32_e32 v194, v112
	v_mov_b32_e32 v195, v113
	v_lshl_add_u64 v[198:199], v[108:109], 0, v[196:197]
	s_nop 0
	v_permlane16_swap_b32_e32 v192, v194
	v_permlane16_swap_b32_e32 v193, v195
	global_store_dwordx4 v[198:199], v[192:195], off
	v_pk_mul_f32 v[98:99], v[98:99], v[106:107] op_sel_hi:[1,0]
	v_pk_mul_f32 v[102:103], v[102:103], v[106:107] op_sel_hi:[1,0]
	v_pk_mul_f32 v[100:101], v[100:101], v[106:107] op_sel_hi:[1,0]
	v_pk_mul_f32 v[98:99], v[130:131], v[98:99]
	v_pk_mul_f32 v[104:105], v[104:105], v[106:107] op_sel_hi:[1,0]
	v_pk_mul_f32 v[102:103], v[134:135], v[102:103]
	v_pk_mul_f32 v[100:101], v[132:133], v[100:101]
	v_pk_mul_f32 v[106:107], v[118:119], v[98:99]
	v_pk_mul_f32 v[104:105], v[136:137], v[104:105]
	v_pk_mul_f32 v[110:111], v[126:127], v[100:101]
	v_pk_fma_f32 v[106:107], v[120:121], v[102:103], v[106:107] neg_lo:[0,0,1] neg_hi:[0,0,1]
	v_pk_mul_f32 v[102:103], v[118:119], v[102:103]
	v_pk_fma_f32 v[110:111], v[128:129], v[104:105], v[110:111] neg_lo:[0,0,1] neg_hi:[0,0,1]
	v_pk_mul_f32 v[104:105], v[126:127], v[104:105]
	v_pk_fma_f32 v[98:99], v[120:121], v[98:99], v[102:103]
	v_cvt_pk_bf16_f32 v102, v106, v107
	v_cvt_pk_bf16_f32 v103, v110, v111
	v_pk_fma_f32 v[100:101], v[128:129], v[100:101], v[104:105]
	v_cvt_pk_bf16_f32 v98, v98, v99
	s_nop 0
	v_cvt_pk_bf16_f32 v99, v100, v101
	s_nop 1
	v_mov_b32_e32 v200, v102
	v_mov_b32_e32 v201, v103
	v_mov_b32_e32 v202, v98
	v_mov_b32_e32 v203, v99
	v_lshl_add_u64 v[204:205], v[108:109], 0, v[196:197]
	s_nop 0
	v_permlane16_swap_b32_e32 v200, v202
	v_permlane16_swap_b32_e32 v201, v203
	global_store_dwordx4 v[204:205], v[200:203], off offset:256
	v_add_u32_e32 v98, s19, v169
	v_ashrrev_i32_e32 v98, 6, v98
	v_cndmask_b32_e32 v98, v123, v98, vcc
	v_cvt_f32_i32_e32 v107, v98
	v_lshl_add_u32 v112, v169, 5, s4
	v_ashrrev_i32_e32 v161, 31, v160
	v_mul_f32_e32 v98, v152, v107
	v_mul_f32_e32 v99, v153, v107
	v_fract_f32_e32 v98, v98
	v_fract_f32_e32 v99, v99
	v_sin_f32_e32 v102, v98
	v_cos_f32_e32 v104, v98
	v_sin_f32_e32 v103, v99
	v_cos_f32_e32 v105, v99
	ds_read_b128 v[98:101], v112
	v_mul_f32_e32 v106, v150, v107
	v_mul_f32_e32 v107, v151, v107
	v_fract_f32_e32 v108, v106
	v_sin_f32_e32 v106, v108
	s_waitcnt lgkmcnt(0)
	v_mov_b32_e32 v110, v99
	v_mov_b32_e32 v111, v100
	v_mov_b32_e32 v99, v101
	v_pk_add_f32 v[98:99], v[110:111], v[98:99]
	v_cos_f32_e32 v108, v108
	v_add_f32_e32 v98, v98, v99
	v_fmamk_f32 v98, v98, 0x3c000000, v251
	v_rsq_f32_e32 v98, v98
	v_fract_f32_e32 v99, v107
	v_sin_f32_e32 v107, v99
	v_cos_f32_e32 v109, v99
	v_pk_mul_f32 v[88:89], v[88:89], v[98:99] op_sel_hi:[1,0]
	v_pk_mul_f32 v[90:91], v[90:91], v[98:99] op_sel_hi:[1,0]
	v_pk_mul_f32 v[94:95], v[94:95], v[98:99] op_sel_hi:[1,0]
	v_pk_mul_f32 v[92:93], v[92:93], v[98:99] op_sel_hi:[1,0]
	v_pk_mul_f32 v[90:91], v[132:133], v[90:91]
	v_pk_mul_f32 v[88:89], v[130:131], v[88:89]
	v_pk_mul_f32 v[92:93], v[134:135], v[92:93]
	v_pk_mul_f32 v[94:95], v[136:137], v[94:95]
	v_pk_mul_f32 v[98:99], v[102:103], v[88:89]
	v_pk_mul_f32 v[100:101], v[106:107], v[90:91]
	v_pk_fma_f32 v[98:99], v[104:105], v[92:93], v[98:99] neg_lo:[0,0,1] neg_hi:[0,0,1]
	v_pk_fma_f32 v[100:101], v[108:109], v[94:95], v[100:101] neg_lo:[0,0,1] neg_hi:[0,0,1]
	v_pk_mul_f32 v[92:93], v[102:103], v[92:93]
	v_pk_mul_f32 v[94:95], v[106:107], v[94:95]
	v_pk_fma_f32 v[88:89], v[104:105], v[88:89], v[92:93]
	v_pk_fma_f32 v[90:91], v[108:109], v[90:91], v[94:95]
	v_cvt_pk_bf16_f32 v92, v98, v99
	v_cvt_pk_bf16_f32 v93, v100, v101
	v_cvt_pk_bf16_f32 v94, v88, v89
	s_nop 0
	v_cvt_pk_bf16_f32 v95, v90, v91
	ds_read_b128 v[88:91], v112 offset:16
	s_waitcnt lgkmcnt(0)
	v_mov_b32_e32 v98, v89
	v_mov_b32_e32 v99, v90
	v_mov_b32_e32 v89, v91
	v_pk_add_f32 v[88:89], v[98:99], v[88:89]
	v_lshl_add_u64 v[90:91], v[160:161], 1, v[154:155]
	v_add_f32_e32 v88, v88, v89
	v_fmamk_f32 v88, v88, 0x3c000000, v251
	v_rsq_f32_e32 v88, v88
	s_nop 1
	v_mov_b32_e32 v192, v92
	v_mov_b32_e32 v193, v93
	v_mov_b32_e32 v194, v94
	v_mov_b32_e32 v195, v95
	v_lshl_add_u64 v[198:199], v[90:91], 0, v[196:197]
	s_nop 0
	v_permlane16_swap_b32_e32 v192, v194
	v_permlane16_swap_b32_e32 v193, v195
	global_store_dwordx4 v[198:199], v[192:195], off
	v_pk_mul_f32 v[80:81], v[80:81], v[88:89] op_sel_hi:[1,0]
	v_pk_mul_f32 v[84:85], v[84:85], v[88:89] op_sel_hi:[1,0]
	v_pk_mul_f32 v[82:83], v[82:83], v[88:89] op_sel_hi:[1,0]
	v_pk_mul_f32 v[80:81], v[130:131], v[80:81]
	v_pk_mul_f32 v[86:87], v[86:87], v[88:89] op_sel_hi:[1,0]
	v_pk_mul_f32 v[84:85], v[134:135], v[84:85]
	v_pk_mul_f32 v[82:83], v[132:133], v[82:83]
	v_pk_mul_f32 v[88:89], v[102:103], v[80:81]
	v_pk_mul_f32 v[86:87], v[136:137], v[86:87]
	v_pk_mul_f32 v[92:93], v[106:107], v[82:83]
	v_pk_fma_f32 v[88:89], v[104:105], v[84:85], v[88:89] neg_lo:[0,0,1] neg_hi:[0,0,1]
	v_pk_mul_f32 v[84:85], v[102:103], v[84:85]
	v_pk_fma_f32 v[92:93], v[108:109], v[86:87], v[92:93] neg_lo:[0,0,1] neg_hi:[0,0,1]
	v_pk_mul_f32 v[86:87], v[106:107], v[86:87]
	v_pk_fma_f32 v[80:81], v[104:105], v[80:81], v[84:85]
	v_cvt_pk_bf16_f32 v84, v88, v89
	v_cvt_pk_bf16_f32 v85, v92, v93
	v_pk_fma_f32 v[82:83], v[108:109], v[82:83], v[86:87]
	v_cvt_pk_bf16_f32 v80, v80, v81
	s_nop 0
	v_cvt_pk_bf16_f32 v81, v82, v83
	s_nop 1
	v_mov_b32_e32 v200, v84
	v_mov_b32_e32 v201, v85
	v_mov_b32_e32 v202, v80
	v_mov_b32_e32 v203, v81
	v_lshl_add_u64 v[204:205], v[90:91], 0, v[196:197]
	s_nop 0
	v_permlane16_swap_b32_e32 v200, v202
	v_permlane16_swap_b32_e32 v201, v203
	global_store_dwordx4 v[204:205], v[200:203], off offset:256
	v_add_u32_e32 v80, s19, v168
	v_ashrrev_i32_e32 v80, 6, v80
	v_cndmask_b32_e32 v80, v122, v80, vcc
	v_cvt_f32_i32_e32 v89, v80
	v_lshl_add_u32 v94, v168, 5, s4
	v_ashrrev_i32_e32 v159, 31, v158
	v_mul_f32_e32 v80, v152, v89
	v_mul_f32_e32 v81, v153, v89
	v_fract_f32_e32 v80, v80
	v_fract_f32_e32 v81, v81
	v_sin_f32_e32 v84, v80
	v_cos_f32_e32 v86, v80
	v_sin_f32_e32 v85, v81
	v_cos_f32_e32 v87, v81
	ds_read_b128 v[80:83], v94
	v_mul_f32_e32 v88, v150, v89
	v_mul_f32_e32 v89, v151, v89
	v_fract_f32_e32 v90, v88
	v_sin_f32_e32 v88, v90
	s_waitcnt lgkmcnt(0)
	v_mov_b32_e32 v92, v81
	v_mov_b32_e32 v93, v82
	v_mov_b32_e32 v81, v83
	v_pk_add_f32 v[80:81], v[92:93], v[80:81]
	v_cos_f32_e32 v90, v90
	v_add_f32_e32 v80, v80, v81
	v_fmamk_f32 v80, v80, 0x3c000000, v251
	v_rsq_f32_e32 v80, v80
	v_fract_f32_e32 v81, v89
	v_sin_f32_e32 v89, v81
	v_cos_f32_e32 v91, v81
	v_pk_mul_f32 v[72:73], v[72:73], v[80:81] op_sel_hi:[1,0]
	v_pk_mul_f32 v[74:75], v[74:75], v[80:81] op_sel_hi:[1,0]
	v_pk_mul_f32 v[78:79], v[78:79], v[80:81] op_sel_hi:[1,0]
	v_pk_mul_f32 v[76:77], v[76:77], v[80:81] op_sel_hi:[1,0]
	v_pk_mul_f32 v[74:75], v[132:133], v[74:75]
	v_pk_mul_f32 v[72:73], v[130:131], v[72:73]
	v_pk_mul_f32 v[76:77], v[134:135], v[76:77]
	v_pk_mul_f32 v[78:79], v[136:137], v[78:79]
	v_pk_mul_f32 v[80:81], v[84:85], v[72:73]
	v_pk_mul_f32 v[82:83], v[88:89], v[74:75]
	v_pk_fma_f32 v[80:81], v[86:87], v[76:77], v[80:81] neg_lo:[0,0,1] neg_hi:[0,0,1]
	v_pk_fma_f32 v[82:83], v[90:91], v[78:79], v[82:83] neg_lo:[0,0,1] neg_hi:[0,0,1]
	v_pk_mul_f32 v[76:77], v[84:85], v[76:77]
	v_pk_mul_f32 v[78:79], v[88:89], v[78:79]
	v_pk_fma_f32 v[72:73], v[86:87], v[72:73], v[76:77]
	v_pk_fma_f32 v[74:75], v[90:91], v[74:75], v[78:79]
	v_cvt_pk_bf16_f32 v76, v80, v81
	v_cvt_pk_bf16_f32 v77, v82, v83
	v_cvt_pk_bf16_f32 v78, v72, v73
	s_nop 0
	v_cvt_pk_bf16_f32 v79, v74, v75
	ds_read_b128 v[72:75], v94 offset:16
	s_waitcnt lgkmcnt(0)
	v_mov_b32_e32 v80, v73
	v_mov_b32_e32 v81, v74
	v_mov_b32_e32 v73, v75
	v_pk_add_f32 v[72:73], v[80:81], v[72:73]
	v_lshl_add_u64 v[74:75], v[158:159], 1, v[154:155]
	v_add_f32_e32 v72, v72, v73
	v_fmamk_f32 v72, v72, 0x3c000000, v251
	v_rsq_f32_e32 v72, v72
	s_nop 1
	v_mov_b32_e32 v192, v76
	v_mov_b32_e32 v193, v77
	v_mov_b32_e32 v194, v78
	v_mov_b32_e32 v195, v79
	v_lshl_add_u64 v[198:199], v[74:75], 0, v[196:197]
	s_nop 0
	v_permlane16_swap_b32_e32 v192, v194
	v_permlane16_swap_b32_e32 v193, v195
	global_store_dwordx4 v[198:199], v[192:195], off
	v_pk_mul_f32 v[64:65], v[64:65], v[72:73] op_sel_hi:[1,0]
	v_pk_mul_f32 v[68:69], v[68:69], v[72:73] op_sel_hi:[1,0]
	v_pk_mul_f32 v[66:67], v[66:67], v[72:73] op_sel_hi:[1,0]
	v_pk_mul_f32 v[64:65], v[130:131], v[64:65]
	v_pk_mul_f32 v[70:71], v[70:71], v[72:73] op_sel_hi:[1,0]
	v_pk_mul_f32 v[68:69], v[134:135], v[68:69]
	v_pk_mul_f32 v[66:67], v[132:133], v[66:67]
	v_pk_mul_f32 v[72:73], v[84:85], v[64:65]
	v_pk_mul_f32 v[70:71], v[136:137], v[70:71]
	v_pk_mul_f32 v[76:77], v[88:89], v[66:67]
	v_pk_fma_f32 v[72:73], v[86:87], v[68:69], v[72:73] neg_lo:[0,0,1] neg_hi:[0,0,1]
	v_pk_mul_f32 v[68:69], v[84:85], v[68:69]
	v_pk_fma_f32 v[76:77], v[90:91], v[70:71], v[76:77] neg_lo:[0,0,1] neg_hi:[0,0,1]
	v_pk_mul_f32 v[70:71], v[88:89], v[70:71]
	v_pk_fma_f32 v[64:65], v[86:87], v[64:65], v[68:69]
	v_cvt_pk_bf16_f32 v68, v72, v73
	v_cvt_pk_bf16_f32 v69, v76, v77
	v_pk_fma_f32 v[66:67], v[90:91], v[66:67], v[70:71]
	v_cvt_pk_bf16_f32 v64, v64, v65
	s_nop 0
	v_cvt_pk_bf16_f32 v65, v66, v67
	s_nop 1
	v_mov_b32_e32 v200, v68
	v_mov_b32_e32 v201, v69
	v_mov_b32_e32 v202, v64
	v_mov_b32_e32 v203, v65
	v_lshl_add_u64 v[204:205], v[74:75], 0, v[196:197]
	s_nop 0
	v_permlane16_swap_b32_e32 v200, v202
	v_permlane16_swap_b32_e32 v201, v203
	global_store_dwordx4 v[204:205], v[200:203], off offset:256
	v_add_u32_e32 v64, s19, v167
	v_ashrrev_i32_e32 v64, 6, v64
	v_cndmask_b32_e32 v64, v157, v64, vcc
	v_cvt_f32_i32_e32 v73, v64
	v_lshl_add_u32 v78, v167, 5, s4
	v_ashrrev_i32_e32 v157, 31, v156
	v_mul_f32_e32 v64, v152, v73
	v_mul_f32_e32 v65, v153, v73
	v_fract_f32_e32 v64, v64
	v_fract_f32_e32 v65, v65
	v_sin_f32_e32 v68, v64
	v_cos_f32_e32 v70, v64
	v_sin_f32_e32 v69, v65
	v_cos_f32_e32 v71, v65
	ds_read_b128 v[64:67], v78
	v_mul_f32_e32 v72, v150, v73
	v_mul_f32_e32 v73, v151, v73
	v_fract_f32_e32 v74, v72
	v_sin_f32_e32 v72, v74
	s_waitcnt lgkmcnt(0)
	v_mov_b32_e32 v76, v65
	v_mov_b32_e32 v77, v66
	v_mov_b32_e32 v65, v67
	v_pk_add_f32 v[64:65], v[76:77], v[64:65]
	v_cos_f32_e32 v74, v74
	v_add_f32_e32 v64, v64, v65
	v_fmamk_f32 v64, v64, 0x3c000000, v251
	v_rsq_f32_e32 v64, v64
	v_fract_f32_e32 v65, v73
	v_sin_f32_e32 v73, v65
	v_cos_f32_e32 v75, v65
	v_pk_mul_f32 v[56:57], v[56:57], v[64:65] op_sel_hi:[1,0]
	v_pk_mul_f32 v[58:59], v[58:59], v[64:65] op_sel_hi:[1,0]
	v_pk_mul_f32 v[62:63], v[62:63], v[64:65] op_sel_hi:[1,0]
	v_pk_mul_f32 v[60:61], v[60:61], v[64:65] op_sel_hi:[1,0]
	v_pk_mul_f32 v[58:59], v[132:133], v[58:59]
	v_pk_mul_f32 v[56:57], v[130:131], v[56:57]
	v_pk_mul_f32 v[60:61], v[134:135], v[60:61]
	v_pk_mul_f32 v[62:63], v[136:137], v[62:63]
	v_pk_mul_f32 v[64:65], v[68:69], v[56:57]
	v_pk_mul_f32 v[66:67], v[72:73], v[58:59]
	v_pk_fma_f32 v[64:65], v[70:71], v[60:61], v[64:65] neg_lo:[0,0,1] neg_hi:[0,0,1]
	v_pk_fma_f32 v[66:67], v[74:75], v[62:63], v[66:67] neg_lo:[0,0,1] neg_hi:[0,0,1]
	v_pk_mul_f32 v[60:61], v[68:69], v[60:61]
	v_pk_mul_f32 v[62:63], v[72:73], v[62:63]
	v_pk_fma_f32 v[56:57], v[70:71], v[56:57], v[60:61]
	v_pk_fma_f32 v[58:59], v[74:75], v[58:59], v[62:63]
	v_cvt_pk_bf16_f32 v60, v64, v65
	v_cvt_pk_bf16_f32 v61, v66, v67
	v_cvt_pk_bf16_f32 v62, v56, v57
	s_nop 0
	v_cvt_pk_bf16_f32 v63, v58, v59
	ds_read_b128 v[56:59], v78 offset:16
	s_waitcnt lgkmcnt(0)
	v_mov_b32_e32 v64, v57
	v_mov_b32_e32 v65, v58
	v_mov_b32_e32 v57, v59
	v_pk_add_f32 v[56:57], v[64:65], v[56:57]
	v_lshl_add_u64 v[58:59], v[156:157], 1, v[154:155]
	v_add_f32_e32 v56, v56, v57
	v_fmamk_f32 v56, v56, 0x3c000000, v251
	v_rsq_f32_e32 v56, v56
	s_nop 1
	v_mov_b32_e32 v192, v60
	v_mov_b32_e32 v193, v61
	v_mov_b32_e32 v194, v62
	v_mov_b32_e32 v195, v63
	v_lshl_add_u64 v[198:199], v[58:59], 0, v[196:197]
	s_nop 0
	v_permlane16_swap_b32_e32 v192, v194
	v_permlane16_swap_b32_e32 v193, v195
	global_store_dwordx4 v[198:199], v[192:195], off
	v_pk_mul_f32 v[48:49], v[48:49], v[56:57] op_sel_hi:[1,0]
	v_pk_mul_f32 v[52:53], v[52:53], v[56:57] op_sel_hi:[1,0]
	v_pk_mul_f32 v[50:51], v[50:51], v[56:57] op_sel_hi:[1,0]
	v_pk_mul_f32 v[48:49], v[130:131], v[48:49]
	v_pk_mul_f32 v[54:55], v[54:55], v[56:57] op_sel_hi:[1,0]
	v_pk_mul_f32 v[52:53], v[134:135], v[52:53]
	v_pk_mul_f32 v[50:51], v[132:133], v[50:51]
	v_pk_mul_f32 v[56:57], v[68:69], v[48:49]
	v_pk_mul_f32 v[54:55], v[136:137], v[54:55]
	v_pk_mul_f32 v[60:61], v[72:73], v[50:51]
	v_pk_fma_f32 v[56:57], v[70:71], v[52:53], v[56:57] neg_lo:[0,0,1] neg_hi:[0,0,1]
	v_pk_mul_f32 v[52:53], v[68:69], v[52:53]
	v_pk_fma_f32 v[60:61], v[74:75], v[54:55], v[60:61] neg_lo:[0,0,1] neg_hi:[0,0,1]
	v_pk_mul_f32 v[54:55], v[72:73], v[54:55]
	v_pk_fma_f32 v[48:49], v[70:71], v[48:49], v[52:53]
	v_cvt_pk_bf16_f32 v52, v56, v57
	v_cvt_pk_bf16_f32 v53, v60, v61
	v_pk_fma_f32 v[50:51], v[74:75], v[50:51], v[54:55]
	v_cvt_pk_bf16_f32 v48, v48, v49
	s_nop 0
	v_cvt_pk_bf16_f32 v49, v50, v51
	s_nop 1
	v_mov_b32_e32 v200, v52
	v_mov_b32_e32 v201, v53
	v_mov_b32_e32 v202, v48
	v_mov_b32_e32 v203, v49
	v_lshl_add_u64 v[204:205], v[58:59], 0, v[196:197]
	s_nop 0
	v_permlane16_swap_b32_e32 v200, v202
	v_permlane16_swap_b32_e32 v201, v203
	global_store_dwordx4 v[204:205], v[200:203], off offset:256
	v_add_u32_e32 v48, s19, v166
	v_ashrrev_i32_e32 v48, 6, v48
	v_cndmask_b32_e32 v48, v124, v48, vcc
	v_cvt_f32_i32_e32 v57, v48
	v_lshl_add_u32 v62, v166, 5, s4
	v_mul_f32_e32 v48, v152, v57
	v_mul_f32_e32 v49, v153, v57
	v_fract_f32_e32 v48, v48
	v_fract_f32_e32 v49, v49
	v_sin_f32_e32 v52, v48
	v_cos_f32_e32 v54, v48
	v_sin_f32_e32 v53, v49
	v_cos_f32_e32 v55, v49
	ds_read_b128 v[48:51], v62
	v_mul_f32_e32 v56, v150, v57
	v_mul_f32_e32 v57, v151, v57
	v_fract_f32_e32 v58, v56
	v_sin_f32_e32 v56, v58
	s_waitcnt lgkmcnt(0)
	v_mov_b32_e32 v60, v49
	v_mov_b32_e32 v61, v50
	v_mov_b32_e32 v49, v51
	v_pk_add_f32 v[48:49], v[60:61], v[48:49]
	v_cos_f32_e32 v58, v58
	v_add_f32_e32 v48, v48, v49
	v_fmamk_f32 v48, v48, 0x3c000000, v251
	v_rsq_f32_e32 v48, v48
	v_fract_f32_e32 v49, v57
	v_sin_f32_e32 v57, v49
	v_cos_f32_e32 v59, v49
	v_pk_mul_f32 v[40:41], v[40:41], v[48:49] op_sel_hi:[1,0]
	v_pk_mul_f32 v[42:43], v[42:43], v[48:49] op_sel_hi:[1,0]
	v_pk_mul_f32 v[46:47], v[46:47], v[48:49] op_sel_hi:[1,0]
	v_pk_mul_f32 v[44:45], v[44:45], v[48:49] op_sel_hi:[1,0]
	v_pk_mul_f32 v[42:43], v[132:133], v[42:43]
	v_pk_mul_f32 v[40:41], v[130:131], v[40:41]
	v_pk_mul_f32 v[44:45], v[134:135], v[44:45]
	v_pk_mul_f32 v[46:47], v[136:137], v[46:47]
	v_pk_mul_f32 v[48:49], v[52:53], v[40:41]
	v_pk_mul_f32 v[50:51], v[56:57], v[42:43]
	v_pk_fma_f32 v[48:49], v[54:55], v[44:45], v[48:49] neg_lo:[0,0,1] neg_hi:[0,0,1]
	v_pk_fma_f32 v[50:51], v[58:59], v[46:47], v[50:51] neg_lo:[0,0,1] neg_hi:[0,0,1]
	v_pk_mul_f32 v[44:45], v[52:53], v[44:45]
	v_pk_mul_f32 v[46:47], v[56:57], v[46:47]
	v_pk_fma_f32 v[40:41], v[54:55], v[40:41], v[44:45]
	v_pk_fma_f32 v[42:43], v[58:59], v[42:43], v[46:47]
	v_cvt_pk_bf16_f32 v44, v48, v49
	v_cvt_pk_bf16_f32 v45, v50, v51
	v_cvt_pk_bf16_f32 v46, v40, v41
	v_lshlrev_b32_e32 v48, 10, v166
	v_cvt_pk_bf16_f32 v47, v42, v43
	ds_read_b128 v[40:43], v62 offset:16
	v_ashrrev_i32_e32 v49, 31, v48
	s_waitcnt lgkmcnt(0)
	v_mov_b32_e32 v50, v41
	v_mov_b32_e32 v51, v42
	v_mov_b32_e32 v41, v43
	v_pk_add_f32 v[40:41], v[50:51], v[40:41]
	v_lshl_add_u64 v[42:43], v[48:49], 1, v[154:155]
	v_add_f32_e32 v40, v40, v41
	v_fmamk_f32 v40, v40, 0x3c000000, v251
	v_rsq_f32_e32 v40, v40
	s_nop 1
	v_mov_b32_e32 v192, v44
	v_mov_b32_e32 v193, v45
	v_mov_b32_e32 v194, v46
	v_mov_b32_e32 v195, v47
	v_lshl_add_u64 v[198:199], v[42:43], 0, v[196:197]
	s_nop 0
	v_permlane16_swap_b32_e32 v192, v194
	v_permlane16_swap_b32_e32 v193, v195
	global_store_dwordx4 v[198:199], v[192:195], off
	v_pk_mul_f32 v[32:33], v[32:33], v[40:41] op_sel_hi:[1,0]
	v_pk_mul_f32 v[36:37], v[36:37], v[40:41] op_sel_hi:[1,0]
	v_pk_mul_f32 v[34:35], v[34:35], v[40:41] op_sel_hi:[1,0]
	v_pk_mul_f32 v[32:33], v[130:131], v[32:33]
	v_pk_mul_f32 v[38:39], v[38:39], v[40:41] op_sel_hi:[1,0]
	v_pk_mul_f32 v[36:37], v[134:135], v[36:37]
	v_pk_mul_f32 v[34:35], v[132:133], v[34:35]
	v_pk_mul_f32 v[40:41], v[52:53], v[32:33]
	v_pk_mul_f32 v[38:39], v[136:137], v[38:39]
	v_pk_mul_f32 v[44:45], v[56:57], v[34:35]
	v_pk_fma_f32 v[40:41], v[54:55], v[36:37], v[40:41] neg_lo:[0,0,1] neg_hi:[0,0,1]
	v_pk_mul_f32 v[36:37], v[52:53], v[36:37]
	v_pk_fma_f32 v[44:45], v[58:59], v[38:39], v[44:45] neg_lo:[0,0,1] neg_hi:[0,0,1]
	v_pk_mul_f32 v[38:39], v[56:57], v[38:39]
	v_pk_fma_f32 v[32:33], v[54:55], v[32:33], v[36:37]
	v_cvt_pk_bf16_f32 v36, v40, v41
	v_cvt_pk_bf16_f32 v37, v44, v45
	v_pk_fma_f32 v[34:35], v[58:59], v[34:35], v[38:39]
	v_cvt_pk_bf16_f32 v32, v32, v33
	s_nop 0
	v_cvt_pk_bf16_f32 v33, v34, v35
	s_nop 1
	v_mov_b32_e32 v200, v36
	v_mov_b32_e32 v201, v37
	v_mov_b32_e32 v202, v32
	v_mov_b32_e32 v203, v33
	v_lshl_add_u64 v[204:205], v[42:43], 0, v[196:197]
	s_nop 0
	v_permlane16_swap_b32_e32 v200, v202
	v_permlane16_swap_b32_e32 v201, v203
	global_store_dwordx4 v[204:205], v[200:203], off offset:256
	v_add_u32_e32 v32, s19, v96
	v_ashrrev_i32_e32 v32, 6, v32
	v_cndmask_b32_e32 v32, v123, v32, vcc
	v_cvt_f32_i32_e32 v41, v32
	v_lshl_add_u32 v46, v96, 5, s4
	v_mul_f32_e32 v32, v152, v41
	v_mul_f32_e32 v33, v153, v41
	v_fract_f32_e32 v32, v32
	v_fract_f32_e32 v33, v33
	v_sin_f32_e32 v36, v32
	v_cos_f32_e32 v38, v32
	v_sin_f32_e32 v37, v33
	v_cos_f32_e32 v39, v33
	ds_read_b128 v[32:35], v46
	v_mul_f32_e32 v40, v150, v41
	v_mul_f32_e32 v41, v151, v41
	v_fract_f32_e32 v42, v40
	v_sin_f32_e32 v40, v42
	s_waitcnt lgkmcnt(0)
	v_mov_b32_e32 v44, v33
	v_mov_b32_e32 v45, v34
	v_mov_b32_e32 v33, v35
	v_pk_add_f32 v[32:33], v[44:45], v[32:33]
	v_cos_f32_e32 v42, v42
	v_add_f32_e32 v32, v32, v33
	v_fmamk_f32 v32, v32, 0x3c000000, v251
	v_rsq_f32_e32 v32, v32
	v_fract_f32_e32 v33, v41
	v_sin_f32_e32 v41, v33
	v_cos_f32_e32 v43, v33
	v_pk_mul_f32 v[24:25], v[24:25], v[32:33] op_sel_hi:[1,0]
	v_pk_mul_f32 v[26:27], v[26:27], v[32:33] op_sel_hi:[1,0]
	v_pk_mul_f32 v[30:31], v[30:31], v[32:33] op_sel_hi:[1,0]
	v_pk_mul_f32 v[28:29], v[28:29], v[32:33] op_sel_hi:[1,0]
	v_pk_mul_f32 v[26:27], v[132:133], v[26:27]
	v_pk_mul_f32 v[24:25], v[130:131], v[24:25]
	v_pk_mul_f32 v[28:29], v[134:135], v[28:29]
	v_pk_mul_f32 v[30:31], v[136:137], v[30:31]
	v_pk_mul_f32 v[32:33], v[36:37], v[24:25]
	v_pk_mul_f32 v[34:35], v[40:41], v[26:27]
	v_pk_fma_f32 v[32:33], v[38:39], v[28:29], v[32:33] neg_lo:[0,0,1] neg_hi:[0,0,1]
	v_pk_fma_f32 v[34:35], v[42:43], v[30:31], v[34:35] neg_lo:[0,0,1] neg_hi:[0,0,1]
	v_pk_mul_f32 v[28:29], v[36:37], v[28:29]
	v_pk_mul_f32 v[30:31], v[40:41], v[30:31]
	v_pk_fma_f32 v[24:25], v[38:39], v[24:25], v[28:29]
	v_pk_fma_f32 v[26:27], v[42:43], v[26:27], v[30:31]
	v_cvt_pk_bf16_f32 v28, v32, v33
	v_cvt_pk_bf16_f32 v29, v34, v35
	v_cvt_pk_bf16_f32 v30, v24, v25
	v_lshlrev_b32_e32 v32, 10, v96
	v_cvt_pk_bf16_f32 v31, v26, v27
	ds_read_b128 v[24:27], v46 offset:16
	v_ashrrev_i32_e32 v33, 31, v32
	s_waitcnt lgkmcnt(0)
	v_mov_b32_e32 v34, v25
	v_mov_b32_e32 v35, v26
	v_mov_b32_e32 v25, v27
	v_pk_add_f32 v[24:25], v[34:35], v[24:25]
	v_lshl_add_u64 v[26:27], v[32:33], 1, v[154:155]
	v_add_f32_e32 v24, v24, v25
	v_fmamk_f32 v24, v24, 0x3c000000, v251
	v_rsq_f32_e32 v24, v24
	s_nop 1
	v_mov_b32_e32 v192, v28
	v_mov_b32_e32 v193, v29
	v_mov_b32_e32 v194, v30
	v_mov_b32_e32 v195, v31
	v_lshl_add_u64 v[198:199], v[26:27], 0, v[196:197]
	s_nop 0
	v_permlane16_swap_b32_e32 v192, v194
	v_permlane16_swap_b32_e32 v193, v195
	global_store_dwordx4 v[198:199], v[192:195], off
	v_pk_mul_f32 v[16:17], v[16:17], v[24:25] op_sel_hi:[1,0]
	v_pk_mul_f32 v[20:21], v[20:21], v[24:25] op_sel_hi:[1,0]
	v_pk_mul_f32 v[18:19], v[18:19], v[24:25] op_sel_hi:[1,0]
	v_pk_mul_f32 v[16:17], v[130:131], v[16:17]
	v_pk_mul_f32 v[22:23], v[22:23], v[24:25] op_sel_hi:[1,0]
	v_pk_mul_f32 v[20:21], v[134:135], v[20:21]
	v_pk_mul_f32 v[18:19], v[132:133], v[18:19]
	v_pk_mul_f32 v[24:25], v[36:37], v[16:17]
	v_pk_mul_f32 v[22:23], v[136:137], v[22:23]
	v_pk_mul_f32 v[28:29], v[40:41], v[18:19]
	v_pk_fma_f32 v[24:25], v[38:39], v[20:21], v[24:25] neg_lo:[0,0,1] neg_hi:[0,0,1]
	v_pk_mul_f32 v[20:21], v[36:37], v[20:21]
	v_pk_fma_f32 v[28:29], v[42:43], v[22:23], v[28:29] neg_lo:[0,0,1] neg_hi:[0,0,1]
	v_pk_mul_f32 v[22:23], v[40:41], v[22:23]
	v_pk_fma_f32 v[16:17], v[38:39], v[16:17], v[20:21]
	v_cvt_pk_bf16_f32 v20, v24, v25
	v_cvt_pk_bf16_f32 v21, v28, v29
	v_pk_fma_f32 v[18:19], v[42:43], v[18:19], v[22:23]
	v_cvt_pk_bf16_f32 v16, v16, v17
	s_nop 0
	v_cvt_pk_bf16_f32 v17, v18, v19
	s_nop 1
	v_mov_b32_e32 v200, v20
	v_mov_b32_e32 v201, v21
	v_mov_b32_e32 v202, v16
	v_mov_b32_e32 v203, v17
	v_lshl_add_u64 v[204:205], v[26:27], 0, v[196:197]
	s_nop 0
	v_permlane16_swap_b32_e32 v200, v202
	v_permlane16_swap_b32_e32 v201, v203
	global_store_dwordx4 v[204:205], v[200:203], off offset:256
	v_add_u32_e32 v16, 0xb0, v182
	v_add_u32_e32 v17, s19, v16
	v_ashrrev_i32_e32 v17, 6, v17
	v_cndmask_b32_e32 v17, v122, v17, vcc
	v_cvt_f32_i32_e32 v17, v17
	v_lshl_add_u32 v32, v16, 5, s4
	v_lshlrev_b32_e32 v16, 10, v16
	v_mul_f32_e32 v18, v152, v17
	v_fract_f32_e32 v18, v18
	v_sin_f32_e32 v20, v18
	v_cos_f32_e32 v22, v18
	v_mul_f32_e32 v18, v153, v17
	v_fract_f32_e32 v18, v18
	v_sin_f32_e32 v21, v18
	v_cos_f32_e32 v23, v18
	v_mul_f32_e32 v18, v150, v17
	v_mul_f32_e32 v17, v151, v17
	v_fract_f32_e32 v17, v17
	v_fract_f32_e32 v18, v18
	v_sin_f32_e32 v25, v17
	v_cos_f32_e32 v27, v17
	v_ashrrev_i32_e32 v17, 31, v16
	v_sin_f32_e32 v24, v18
	v_cos_f32_e32 v26, v18
	v_lshl_add_u64 v[28:29], v[16:17], 1, v[154:155]
	ds_read_b128 v[16:19], v32
	s_waitcnt lgkmcnt(0)
	v_mov_b32_e32 v30, v17
	v_mov_b32_e32 v31, v18
	v_mov_b32_e32 v17, v19
	v_pk_add_f32 v[16:17], v[30:31], v[16:17]
	s_nop 0
	v_add_f32_e32 v16, v16, v17
	v_fmamk_f32 v16, v16, 0x3c000000, v251
	v_rsq_f32_e32 v16, v16
	s_nop 0
	v_pk_mul_f32 v[8:9], v[8:9], v[16:17] op_sel_hi:[1,0]
	v_pk_mul_f32 v[12:13], v[12:13], v[16:17] op_sel_hi:[1,0]
	v_pk_mul_f32 v[10:11], v[10:11], v[16:17] op_sel_hi:[1,0]
	v_pk_mul_f32 v[8:9], v[130:131], v[8:9]
	v_pk_mul_f32 v[14:15], v[14:15], v[16:17] op_sel_hi:[1,0]
	v_pk_mul_f32 v[12:13], v[134:135], v[12:13]
	v_pk_mul_f32 v[10:11], v[132:133], v[10:11]
	v_pk_mul_f32 v[16:17], v[20:21], v[8:9]
	v_pk_mul_f32 v[14:15], v[136:137], v[14:15]
	v_pk_mul_f32 v[18:19], v[24:25], v[10:11]
	v_pk_fma_f32 v[16:17], v[22:23], v[12:13], v[16:17] neg_lo:[0,0,1] neg_hi:[0,0,1]
	v_pk_mul_f32 v[12:13], v[20:21], v[12:13]
	v_pk_fma_f32 v[18:19], v[26:27], v[14:15], v[18:19] neg_lo:[0,0,1] neg_hi:[0,0,1]
	v_pk_mul_f32 v[14:15], v[24:25], v[14:15]
	v_pk_fma_f32 v[8:9], v[22:23], v[8:9], v[12:13]
	v_cvt_pk_bf16_f32 v12, v16, v17
	v_cvt_pk_bf16_f32 v13, v18, v19
	v_pk_fma_f32 v[10:11], v[26:27], v[10:11], v[14:15]
	v_cvt_pk_bf16_f32 v8, v8, v9
	s_nop 0
	v_cvt_pk_bf16_f32 v9, v10, v11
	s_nop 1
	v_mov_b32_e32 v192, v12
	v_mov_b32_e32 v193, v13
	v_mov_b32_e32 v194, v8
	v_mov_b32_e32 v195, v9
	v_lshl_add_u64 v[198:199], v[28:29], 0, v[196:197]
	s_nop 0
	v_permlane16_swap_b32_e32 v192, v194
	v_permlane16_swap_b32_e32 v193, v195
	global_store_dwordx4 v[198:199], v[192:195], off
	ds_read_b128 v[8:11], v32 offset:16
	s_waitcnt lgkmcnt(0)
	v_mov_b32_e32 v12, v9
	v_mov_b32_e32 v13, v10
	v_mov_b32_e32 v9, v11
	v_pk_add_f32 v[8:9], v[12:13], v[8:9]
	s_nop 0
	v_add_f32_e32 v8, v8, v9
	v_fmamk_f32 v8, v8, 0x3c000000, v251
	v_rsq_f32_e32 v8, v8
	s_nop 0
	v_pk_mul_f32 v[0:1], v[0:1], v[8:9] op_sel_hi:[1,0]
	v_pk_mul_f32 v[4:5], v[4:5], v[8:9] op_sel_hi:[1,0]
	v_pk_mul_f32 v[2:3], v[2:3], v[8:9] op_sel_hi:[1,0]
	v_pk_mul_f32 v[0:1], v[130:131], v[0:1]
	v_pk_mul_f32 v[6:7], v[6:7], v[8:9] op_sel_hi:[1,0]
	v_pk_mul_f32 v[4:5], v[134:135], v[4:5]
	v_pk_mul_f32 v[2:3], v[132:133], v[2:3]
	v_pk_mul_f32 v[8:9], v[20:21], v[0:1]
	v_pk_mul_f32 v[6:7], v[136:137], v[6:7]
	v_pk_mul_f32 v[10:11], v[24:25], v[2:3]
	v_pk_fma_f32 v[8:9], v[22:23], v[4:5], v[8:9] neg_lo:[0,0,1] neg_hi:[0,0,1]
	v_pk_mul_f32 v[4:5], v[20:21], v[4:5]
	v_pk_fma_f32 v[10:11], v[26:27], v[6:7], v[10:11] neg_lo:[0,0,1] neg_hi:[0,0,1]
	v_pk_mul_f32 v[6:7], v[24:25], v[6:7]
	v_pk_fma_f32 v[0:1], v[22:23], v[0:1], v[4:5]
	v_cvt_pk_bf16_f32 v4, v8, v9
	v_cvt_pk_bf16_f32 v5, v10, v11
	v_pk_fma_f32 v[2:3], v[26:27], v[2:3], v[6:7]
	v_cvt_pk_bf16_f32 v0, v0, v1
	s_nop 0
	v_cvt_pk_bf16_f32 v1, v2, v3
	s_nop 1
	v_mov_b32_e32 v200, v4
	v_mov_b32_e32 v201, v5
	v_mov_b32_e32 v202, v0
	v_mov_b32_e32 v203, v1
	v_lshl_add_u64 v[204:205], v[28:29], 0, v[196:197]
	s_nop 0
	v_permlane16_swap_b32_e32 v200, v202
	v_permlane16_swap_b32_e32 v201, v203
	global_store_dwordx4 v[204:205], v[200:203], off offset:256
